# attention steady loops: next iteration's first V-fragment LDS address formed in front of the closing barrier instead of as the first instruction behind it; on top of v95
# speedup vs baseline: 1.0026x; 1.0026x over previous
; __device__ __forceinline__ int fresh_tid() { int t = threadIdx.x; asm volatile("" : "+v"(t)); return t; }
; #define WAIT_BAR(N) asm volatile("s_waitcnt vmcnt(" #N ") lgkmcnt(0)\n\ts_barrier":::"memory")
;   #define DMA_K(t,slot) glds16(ksrc+(long)(t)*KVBLK*PK,(unsigned)__builtin_amdgcn_readfirstlane(kdst+(slot)))
;   #define CMASK(P0,P1,t) do{}while(0)
; template<int THRL,bool FIXREF,bool HALFK> __device__ __forceinline__ void attn_unit(float mref,long rowbase,int q0,const bf16*Qh,int PQ,const bf16*__restrict__ Kh_,int PK,const bf16*__restrict__ Vh_,int PV,bf16*Oh,int PO,const bf16*Gh,int PG,u32x4(&okeep)[4],int omode,float lam,float oml,const float ...
;   const int tid=fresh_tid(),lane=tid&63,r32=lane&31,hi=lane>>5; const int wid=__builtin_amdgcn_readfirstlane(tid>>6);
;   const bf16*Qw=Qh+(rowbase+q0+wid*QBLK)*PQ;
;   const bf16*Kh=Kh_+rowbase*PK,*Vh=Vh_+rowbase*PV;
;   const unsigned lds0=(unsigned)(uintptr_t)shm;
;   float*wsf=(float*)(shm+LDS_WS)+wid*64;
;   const bf16*ksrc=Kh+(long)lane*PK+wid*8;
;   const bf16*vsrc=Vh+(long)(16*(wid&3)+(lane>>2))*PV+(wid>>2)*32+(lane&3)*8;
;   const unsigned kdst=lds0+LDS_K+wid*1024, vdst=lds0+LDS_V+wid*1024;
;     ...
;   const int vb0=(int)(lds0+LDS_V)+((lane>>4)&1)*32+(lane&3)*8+(4*hi+((lane&15)>>2))*64;
;   const char*Kbase=shm+LDS_K; bf16x8 kf[8];
;   const lds_cptr shm3=(lds_cptr)shm; const lds_cptr kp0=shm3+LDS_K+hi*1024+r32*16; const lds_cptr vp0=shm3+LDS_V+((lane>>4)&1)*32+(lane&3)*8+(4*hi+((lane&15)>>2))*64;
;   constexpr int NT=SEQ/KVBLK;
;   if(Gh){ const bf16*Gw=Gh+(rowbase+q0+wid*QBLK)*PG;
;     #pragma unroll
;     for(int i=0;i<4;++i) glds16(Gw+(long)(i*8+(lane>>3))*PG+(lane&7)*8,(unsigned)__builtin_amdgcn_readfirstlane(lds0+LDS_GST+wid*4096+i*1024)); }
;   DMA_K(0,0);DMA_V(0,0);DMA_K(1,SLOTB);
;   bf16x8 qr[4];
;   #pragma unroll
;   for(int d0=0;d0<4;++d0)qr[d0]=*reinterpret_cast<const bf16x8*>(&Qw[(long)r32*PQ+d0*16+hi*8]);
;   float mhat=0.f,l_reg=0.f;f32x16 o[2];o[0]=f32x16{};o[1]=f32x16{};f32x16 negm=f32x16{};
;   if constexpr(FIXREF){ mhat=mref; _Pragma("unroll") for(int r=0;r<16;++r)negm[r]=-mref; }
;   asm volatile("":"+v"(negm));
;     ...
;   bool resc=false;
;     ...
;   f32x16 pA0,pA1,pB0,pB1;
;   int sl_prev=0,sl_cur=0,sl_next=SLOTB;
;     ...
;   DMA_K(2,2*SLOTB);
;   WAIT_BAR(3);
;   qkt<HALFK?2:4>(pA0,pA1,Kbase,qr,negm,r32,hi);asm volatile("s_nop 15\n\ts_nop 7":"+v"(pA0),"+v"(pA1));CMASK(pA0,pA1,0);
.LBB0_450:
	s_bfe_u32 s16, s58, 0x20004
	s_lshl_b32 s59, s16, 6
	s_and_b32 s67, s59, 0x80
	s_ashr_i32 s42, s58, 6
	s_lshl_b32 s16, s16, 7
	s_add_u32 s46, s2, s16
	s_addc_u32 s47, s3, 0
	s_lshl_b32 s17, s58, 2
	s_and_b32 s17, s17, 0x80
	s_add_u32 s60, s14, s17
	s_addc_u32 s61, s15, 0
	s_add_u32 s62, s20, s17
	s_addc_u32 s63, s28, 0
	s_add_u32 s65, s34, s16
	v_mov_b32_e32 v104, v218
	s_addc_u32 s66, s35, 0
	s_ashr_i32 s43, s42, 31
	s_lshl_b32 s40, s58, 8
	s_lshl_b64 s[16:17], s[42:43], 12
	v_readfirstlane_b32 s64, v104
	s_and_b32 s40, s40, 0xf00
	s_ashr_i32 s73, s64, 6
	s_or_b32 s16, s16, s40
	s_lshl_b32 s40, s73, 5
	s_ashr_i32 s41, s40, 31
	s_add_u32 s16, s16, s40
	s_addc_u32 s17, s17, s41
	s_lshl_b64 s[40:41], s[16:17], 9
	s_add_u32 s48, s46, s40
	s_addc_u32 s49, s47, s41
	s_lshl_b64 s[40:41], s[42:43], 20
	s_add_u32 s46, s60, s40
	s_addc_u32 s47, s61, s41
	s_mul_i32 s69, s42, 0x1e00000
	s_mul_hi_i32 s68, s42, 0x1e00000
	s_add_u32 s60, s62, s69
	v_and_b32_e32 v205, 63, v104
	s_addc_u32 s61, s63, s68
	s_lshl_b32 s42, s73, 3
	v_lshlrev_b32_e32 v0, 8, v205
	s_ashr_i32 s43, s42, 31
	v_lshl_add_u64 v[18:19], s[46:47], 0, v[0:1]
	s_lshl_b64 s[42:43], s[42:43], 1
	v_lshl_add_u64 v[210:211], v[18:19], 0, s[42:43]
	s_lshl_b32 s46, s73, 4
	v_bfe_u32 v18, v104, 2, 4
	v_and_or_b32 v18, s46, 48, v18
	s_ashr_i32 s46, s64, 3
	s_andn2_b32 s46, s46, 31
	s_ashr_i32 s47, s46, 31
	s_lshl_b64 s[46:47], s[46:47], 1
	s_lshl_b32 s63, s73, 10
	v_mul_u32_u24_e32 v18, 0xf00, v18
	s_cmp_lg_u32 0, -1
	v_lshlrev_b32_e32 v102, 1, v18
	v_mov_b32_e32 v103, v1
	s_cselect_b32 s75, 0, 0
	v_lshl_add_u64 v[18:19], s[60:61], 0, v[102:103]
	v_lshlrev_b32_e32 v22, 3, v104
	s_add_i32 s62, s63, s75
	s_mul_i32 s60, s17, 0x1e00
	s_mul_hi_u32 s70, s16, 0x1e00
	v_and_b32_e32 v229, 24, v22
	s_add_i32 s61, s62, 0x6000
	s_add_i32 s60, s70, s60
	s_mul_i32 s70, s16, 0x1e00
	v_lshl_add_u64 v[18:19], v[18:19], 0, s[46:47]
	v_lshlrev_b32_e32 v20, 1, v229
	v_mov_b32_e32 v21, v1
	s_add_u32 s70, s65, s70
	v_bfe_u32 v203, v104, 3, 3
	v_and_b32_e32 v206, 56, v22
	v_lshl_add_u64 v[208:209], v[18:19], 0, v[20:21]
	s_addc_u32 s71, s66, s60
	v_lshlrev_b32_e32 v18, 1, v206
	v_mov_b32_e32 v19, v1
	s_lshl_b32 s60, s73, 12
	v_mul_u32_u24_e32 v20, 0xf00, v203
	v_lshl_add_u64 v[18:19], s[70:71], 0, v[18:19]
	v_lshlrev_b32_e32 v20, 1, v20
	s_add_i32 s65, s75, s60
	v_lshl_add_u64 v[18:19], v[18:19], 0, v[20:21]
	s_add_i32 s66, s65, 0x14800
	s_mov_b32 s70, m0
	s_mov_b32 m0, s66
	s_nop 0
	global_load_lds_dwordx4 v[18:19], off
	s_mov_b32 m0, s70
	v_lshl_add_u64 v[20:21], v[18:19], 0, s[30:31]
	s_add_i32 s66, s65, 0x14c00
	s_mov_b32 s70, m0
	s_mov_b32 m0, s66
	s_nop 0
	global_load_lds_dwordx4 v[20:21], off
	s_mov_b32 m0, s70
	v_lshl_add_u64 v[20:21], v[18:19], 0, s[56:57]
	s_add_i32 s66, s65, 0x15000
	s_mov_b32 s70, m0
	s_mov_b32 m0, s66
	s_nop 0
	global_load_lds_dwordx4 v[20:21], off
	s_mov_b32 m0, s70
	v_lshl_add_u64 v[18:19], v[18:19], 0, s[8:9]
	s_add_i32 s65, s65, 0x15400
	s_mov_b32 s66, m0
	s_mov_b32 m0, s65
	s_nop 0
	global_load_lds_dwordx4 v[18:19], off
	s_mov_b32 m0, s66
	s_mov_b32 s65, m0
	s_mov_b32 m0, s62
	s_nop 0
	global_load_lds_dwordx4 v[210:211], off
	s_mov_b32 m0, s65
	s_mov_b64 s[70:71], 0x4000
	v_and_b32_e32 v216, 31, v104
	s_mov_b32 s65, m0
	s_mov_b32 m0, s61
	s_nop 0
	global_load_lds_dwordx4 v[208:209], off
	s_mov_b32 m0, s65
	v_lshl_add_u64 v[18:19], v[210:211], 0, s[70:71]
	v_bfe_u32 v217, v104, 5, 1
	s_add_i32 s65, s62, 0x2000
	s_mov_b32 s66, m0
	s_mov_b32 m0, s65
	s_nop 0
	global_load_lds_dwordx4 v[18:19], off
	s_mov_b32 m0, s66
	v_lshlrev_b32_e32 v18, 9, v216
	v_lshl_or_b32 v18, v217, 4, v18
	global_load_dwordx4 v[174:177], v18, s[48:49]
	global_load_dwordx4 v[170:173], v18, s[48:49] offset:32
	global_load_dwordx4 v[162:165], v18, s[48:49] offset:64
	global_load_dwordx4 v[154:157], v18, s[48:49] offset:96
	v_mov_b64_e32 v[64:65], v[16:17]
	v_lshlrev_b32_e32 v18, 10, v217
	v_lshlrev_b32_e32 v19, 4, v216
	v_mov_b64_e32 v[62:63], v[14:15]
	v_mov_b64_e32 v[60:61], v[12:13]
	v_mov_b64_e32 v[58:59], v[10:11]
	v_mov_b64_e32 v[56:57], v[8:9]
	v_mov_b64_e32 v[54:55], v[6:7]
	v_mov_b64_e32 v[52:53], v[4:5]
	v_mov_b64_e32 v[50:51], v[2:3]
	v_add3_u32 v228, 0, v18, v19
	v_lshl_add_u64 v[18:19], v[210:211], 0, s[10:11]
	s_add_i32 s48, s62, 0x4000
	s_mov_b32 s49, m0
	s_mov_b32 m0, s48
	s_nop 0
	global_load_lds_dwordx4 v[18:19], off
	s_mov_b32 m0, s49
	s_waitcnt vmcnt(3) lgkmcnt(0)
	s_barrier
	ds_read_b128 v[18:21], v228
	ds_read_b128 v[66:69], v228 offset:512
	s_or_b32 s69, s69, s67
	s_waitcnt vmcnt(3) lgkmcnt(1)
	v_mfma_f32_32x32x16_bf16 v[34:49], v[18:21], v[174:177], v[50:65]
	v_mov_b32_e32 v232, 0
	s_mov_b32 s48, -1
	s_mov_b32 s66, 0
	s_movk_i32 s65, 0x2000
	s_movk_i32 s49, 0x4000
	s_waitcnt lgkmcnt(0)
	v_mfma_f32_32x32x16_bf16 v[18:33], v[66:69], v[174:177], v[50:65]
	ds_read_b128 v[66:69], v228 offset:2048
	ds_read_b128 v[70:73], v228 offset:2560
	s_waitcnt vmcnt(2) lgkmcnt(1)
	v_mfma_f32_32x32x16_bf16 v[34:49], v[66:69], v[170:173], v[34:49]
	s_waitcnt lgkmcnt(0)
	v_mfma_f32_32x32x16_bf16 v[18:33], v[70:73], v[170:173], v[18:33]
	ds_read_b128 v[66:69], v228 offset:4096
	ds_read_b128 v[70:73], v228 offset:4608
	s_waitcnt vmcnt(1) lgkmcnt(1)
	v_mfma_f32_32x32x16_bf16 v[34:49], v[66:69], v[162:165], v[34:49]
	ds_read_b128 v[66:69], v228 offset:6144
	s_waitcnt lgkmcnt(1)
	v_mfma_f32_32x32x16_bf16 v[18:33], v[70:73], v[162:165], v[18:33]
	ds_read_b128 v[70:73], v228 offset:6656
	s_waitcnt vmcnt(0) lgkmcnt(1)
	v_mfma_f32_32x32x16_bf16 v[34:49], v[66:69], v[154:157], v[34:49]
	v_lshlrev_b32_e32 v66, 1, v104
	v_lshlrev_b32_e32 v67, 4, v104
	v_and_b32_e32 v231, 32, v66
	v_and_b32_e32 v66, 0xc0, v67
	v_lshl_or_b32 v230, v217, 8, v66
	v_add_u32_e32 v66, 0, v231
	v_add3_u32 v227, v66, v229, v230
	s_waitcnt lgkmcnt(0)
	v_mfma_f32_32x32x16_bf16 v[18:33], v[70:73], v[154:157], v[18:33]
	s_nop 15
	s_nop 7
	s_waitcnt vmcnt(0) lgkmcnt(0)
	s_barrier
; #define WAIT_BAR(N) asm volatile("s_waitcnt vmcnt(" #N ") lgkmcnt(0)\n\ts_barrier":::"memory")
; __device__ __forceinline__ void kload2(bf16x8*kf,lds_cptr kp,int j){ kf[2*j]=*(const __attribute__((address_space(3))) bf16x8*)(kp+j*2048); kf[2*j+1]=*(const __attribute__((address_space(3))) bf16x8*)(kp+j*2048+512); }
;   #define DMA_K(t,slot) glds16(ksrc+(long)(t)*KVBLK*PK,(unsigned)__builtin_amdgcn_readfirstlane(kdst+(slot)))
;   #define DMA_V(t,slot) glds16(vsrc+(long)(t)*KVBLK*PV,(unsigned)__builtin_amdgcn_readfirstlane(vdst+(slot)))
;   #define ROT() do{sl_prev=sl_cur;sl_cur=sl_next;sl_next=(sl_next==(NSLOT-1)*SLOTB)?0:sl_next+SLOTB;}while(0)
; template<int THRL,bool FIXREF,bool HALFK> __device__ __forceinline__ void attn_unit(float mref,long rowbase,int q0,const bf16*Qh,int PQ,const bf16*__restrict__ Kh_,int PK,const bf16*__restrict__ Vh_,int PV,bf16*Oh,int PO,const bf16*Gh,int PG,u32x4(&okeep)[4],int omode,float lam,float oml,const float ...
;     ...
;   START(pA0,pA1);
;   _Pragma("unroll") for(int r=0;r<16;++r)pA1[r]=__builtin_amdgcn_exp2f(pA1[r]);
;   WAIT_BAR(0);
;   DMA_K(3,0);DMA_V(1,SLOTB);
;   ROT();
;   if constexpr(HALFK){ kload2(kf,kp0+sl_cur,0); kload2(kf,kp0+sl_cur,1); } else kload8(kf,kp0+sl_cur);
;   WAIT_BAR(2);
	s_nop 2
	v_exp_f32_e32 v82, v34
	v_exp_f32_e32 v83, v35
	s_nop 6
	v_exp_f32_e32 v66, v18
	v_exp_f32_e32 v67, v19
	v_lshl_add_u64 v[18:19], v[210:211], 0, s[12:13]
	s_mov_b32 s70, m0
	s_mov_b32 m0, s62
	s_nop 0
	global_load_lds_dwordx4 v[18:19], off
	s_mov_b32 m0, s70
	v_lshl_add_u64 v[18:19], v[208:209], 0, s[22:23]
	s_add_i32 s70, s62, 0x8000
	s_mov_b32 s71, m0
	s_mov_b32 m0, s70
	s_nop 0
	global_load_lds_dwordx4 v[18:19], off
	s_mov_b32 m0, s71
	ds_read_b128 v[98:101], v228 offset:8192
	ds_read_b128 v[182:185], v228 offset:8704
	ds_read_b128 v[186:189], v228 offset:10240
	ds_read_b128 v[178:181], v228 offset:10752
	ds_read_b128 v[142:145], v228 offset:12288
	ds_read_b128 v[138:141], v228 offset:12800
	ds_read_b128 v[134:137], v228 offset:14336
	ds_read_b128 v[130:133], v228 offset:14848
	s_add_u32 s46, s46, s69
	s_addc_u32 s47, s47, s68
	s_add_u32 s42, s50, s42
	s_addc_u32 s43, s51, s43
	s_add_u32 s42, s42, s67
	v_exp_f32_e32 v84, v36
	v_exp_f32_e32 v85, v37
	v_exp_f32_e32 v86, v38
	v_exp_f32_e32 v87, v39
	v_exp_f32_e32 v88, v40
	v_exp_f32_e32 v89, v41
	v_exp_f32_e32 v90, v42
	v_exp_f32_e32 v91, v43
	v_exp_f32_e32 v92, v44
	v_exp_f32_e32 v93, v45
	v_exp_f32_e32 v94, v46
	v_exp_f32_e32 v95, v47
	v_exp_f32_e32 v96, v48
	v_exp_f32_e32 v97, v49
	v_exp_f32_e32 v68, v20
	v_exp_f32_e32 v69, v21
	v_exp_f32_e32 v70, v22
	v_exp_f32_e32 v71, v23
	v_exp_f32_e32 v72, v24
	v_exp_f32_e32 v73, v25
	v_exp_f32_e32 v74, v26
	v_exp_f32_e32 v75, v27
	v_exp_f32_e32 v76, v28
	v_exp_f32_e32 v77, v29
	v_exp_f32_e32 v78, v30
	v_exp_f32_e32 v79, v31
	v_exp_f32_e32 v80, v32
	v_exp_f32_e32 v81, v33
	v_and_b32_e32 v18, 3, v104
	s_addc_u32 s43, s43, 0
	s_waitcnt vmcnt(2) lgkmcnt(0)
	s_barrier
	v_lshl_or_b32 v18, v18, 4, s46
	v_mov_b32_e32 v19, s47
	s_add_u32 s40, s42, s40
	v_lshl_add_u64 v[18:19], v[18:19], 0, v[102:103]
	s_addc_u32 s41, s43, s41
	v_lshl_add_u64 v[212:213], s[0:1], 0, v[18:19]
	v_lshl_add_u64 v[214:215], s[40:41], 0, v[0:1]
	v_mov_b32_e32 v18, 0
	v_mov_b32_e32 v19, v232
	v_mov_b32_e32 v20, v232
	v_mov_b32_e32 v21, v232
	v_mov_b32_e32 v22, v232
	v_mov_b32_e32 v23, v232
	v_mov_b32_e32 v24, v232
	v_mov_b32_e32 v25, v232
	v_mov_b32_e32 v26, v232
	v_mov_b32_e32 v27, v232
	v_mov_b32_e32 v28, v232
	v_mov_b32_e32 v29, v232
	v_mov_b32_e32 v30, v232
	v_mov_b32_e32 v31, v232
	v_mov_b32_e32 v32, v232
	v_mov_b32_e32 v33, v232
	v_mov_b32_e32 v34, 0
	v_mov_b32_e32 v35, v232
	v_mov_b32_e32 v36, v232
	v_mov_b32_e32 v37, v232
	v_mov_b32_e32 v38, v232
	v_mov_b32_e32 v39, v232
	v_mov_b32_e32 v40, v232
	v_mov_b32_e32 v41, v232
	v_mov_b32_e32 v42, v232
	v_mov_b32_e32 v43, v232
	v_mov_b32_e32 v44, v232
	v_mov_b32_e32 v45, v232
	v_mov_b32_e32 v46, v232
	v_mov_b32_e32 v47, v232
	v_mov_b32_e32 v48, v232
	v_mov_b32_e32 v49, v232
	v_add_u32_e32 v0, s66, v227
.LBB0_451:
	ds_read_b64_tr_b16 v[234:235], v0 offset:24576
	ds_read_b64_tr_b16 v[236:237], v0 offset:25088
	v_add_f32_e32 v102, v82, v83
	v_add_f32_e32 v102, v84, v102
	v_add_f32_e32 v102, v85, v102
	v_add_f32_e32 v102, v86, v102
	v_add_f32_e32 v102, v87, v102
	v_cvt_pk_bf16_f32 v166, v82, v83
	v_cvt_pk_bf16_f32 v167, v84, v85
	s_waitcnt lgkmcnt(9)
	v_mfma_f32_32x32x16_bf16 v[114:129], v[98:101], v[174:177], v[50:65]
	ds_read_b64_tr_b16 v[82:83], v0 offset:28672
	ds_read_b64_tr_b16 v[84:85], v0 offset:29184
	v_add_f32_e32 v98, v88, v102
	v_add_f32_e32 v98, v89, v98
	v_add_f32_e32 v98, v90, v98
	v_add_f32_e32 v146, v91, v98
	s_waitcnt lgkmcnt(10)
	v_mfma_f32_32x32x16_bf16 v[98:113], v[182:185], v[174:177], v[50:65]
	v_cvt_pk_bf16_f32 v168, v86, v87
	v_cvt_pk_bf16_f32 v169, v88, v89
	ds_read_b64_tr_b16 v[86:87], v0 offset:25600
	ds_read_b64_tr_b16 v[88:89], v0 offset:26112
	v_add_f32_e32 v146, v92, v146
	v_add_f32_e32 v146, v93, v146
	v_add_f32_e32 v146, v94, v146
	v_add_f32_e32 v146, v95, v146
	v_cvt_pk_bf16_f32 v158, v90, v91
	v_cvt_pk_bf16_f32 v159, v92, v93
	s_waitcnt lgkmcnt(11)
	v_mfma_f32_32x32x16_bf16 v[114:129], v[186:189], v[170:173], v[114:129]
	ds_read_b64_tr_b16 v[90:91], v0 offset:29696
	ds_read_b64_tr_b16 v[92:93], v0 offset:30208
	s_waitcnt lgkmcnt(12)
	v_mfma_f32_32x32x16_bf16 v[98:113], v[178:181], v[170:173], v[98:113]
	v_add_f32_e32 v146, v96, v146
	v_add_f32_e32 v146, v97, v146
	v_add_f32_e32 v146, v66, v146
	v_add_f32_e32 v146, v67, v146
	v_cvt_pk_bf16_f32 v160, v94, v95
	v_cvt_pk_bf16_f32 v161, v96, v97
	ds_read_b64_tr_b16 v[94:95], v0 offset:26624
	ds_read_b64_tr_b16 v[96:97], v0 offset:27136
	s_waitcnt lgkmcnt(13)
	v_mfma_f32_32x32x16_bf16 v[114:129], v[142:145], v[162:165], v[114:129]
	v_add_f32_e32 v142, v68, v146
	v_add_f32_e32 v142, v69, v142
	v_add_f32_e32 v142, v70, v142
	v_add_f32_e32 v142, v71, v142
	v_cvt_pk_bf16_f32 v150, v66, v67
	v_cvt_pk_bf16_f32 v151, v68, v69
	ds_read_b64_tr_b16 v[66:67], v0 offset:30720
	ds_read_b64_tr_b16 v[68:69], v0 offset:31232
	s_waitcnt lgkmcnt(14)
	v_mfma_f32_32x32x16_bf16 v[98:113], v[138:141], v[162:165], v[98:113]
	v_add_f32_e32 v138, v72, v142
	v_add_f32_e32 v138, v73, v138
	v_add_f32_e32 v138, v74, v138
	v_add_f32_e32 v138, v75, v138
	v_cvt_pk_bf16_f32 v152, v70, v71
	v_cvt_pk_bf16_f32 v153, v72, v73
	ds_read_b64_tr_b16 v[70:71], v0 offset:27648
	ds_read_b64_tr_b16 v[72:73], v0 offset:28160
	s_waitcnt lgkmcnt(14)
; #define WAIT_BAR(N) asm volatile("s_waitcnt vmcnt(" #N ") lgkmcnt(0)\n\ts_barrier":::"memory")
;   #define RESC() do{ if(!FIXREF&&resc){ asm volatile("s_waitcnt lgkmcnt(0)":::"memory"); \
;       _Pragma("unroll") for(int d_=0;d_<2;++d_) _Pragma("unroll") for(int r=0;r<16;++r)o[d_][r]*=wsf[crow(r,hi)]; } }while(0)
;   #define ROT() do{sl_prev=sl_cur;sl_cur=sl_next;sl_next=(sl_next==(NSLOT-1)*SLOTB)?0:sl_next+SLOTB;}while(0)
; template<int THRL,bool FIXREF,bool HALFK> __device__ __forceinline__ void attn_unit(float mref,long rowbase,int q0,const bf16*Qh,int PQ,const bf16*__restrict__ Kh_,int PK,const bf16*__restrict__ Vh_,int PV,bf16*Oh,int PO,const bf16*Gh,int PG,u32x4(&okeep)[4],int omode,float lam,float oml,const float ...
;     ...
;   int t=1;
;     ...
;   for(;t+5<NT;t+=2){
;     STEP(pB0,pB1,pA0,pA1,t,true,true,true);     WAIT_BAR(2); RESC(); ROT();
;     STEP(pA0,pA1,pB0,pB1,t+1,true,true,true);   WAIT_BAR(2); RESC(); ROT();
	v_mfma_f32_32x32x16_bf16 v[114:129], v[134:137], v[154:157], v[114:129]
	v_add_f32_e32 v134, v76, v138
	v_add_f32_e32 v134, v77, v134
	v_add_f32_e32 v134, v78, v134
	v_add_f32_e32 v134, v79, v134
	v_cvt_pk_bf16_f32 v146, v74, v75
	v_cvt_pk_bf16_f32 v147, v76, v77
	ds_read_b64_tr_b16 v[74:75], v0 offset:31744
	ds_read_b64_tr_b16 v[76:77], v0 offset:32256
	v_mfma_f32_32x32x16_bf16 v[98:113], v[130:133], v[154:157], v[98:113]
	v_add_f32_e32 v0, v80, v134
	v_add_f32_e32 v0, v81, v0
	v_cvt_pk_bf16_f32 v148, v78, v79
	v_cvt_pk_bf16_f32 v149, v80, v81
	v_lshl_add_u64 v[78:79], v[214:215], 0, s[12:13]
	s_add_i32 s40, s65, s62
	s_mov_b32 s41, m0
	s_mov_b32 m0, s40
	s_nop 0
	global_load_lds_dwordx4 v[78:79], off
	s_mov_b32 m0, s41
	v_lshl_add_u64 v[78:79], v[212:213], 0, s[22:23]
	s_add_i32 s40, s49, s61
	s_mov_b32 s41, m0
	s_mov_b32 m0, s40
	s_nop 0
	global_load_lds_dwordx4 v[78:79], off
	s_mov_b32 m0, s41
	v_add_f32_e32 v0, v232, v0
	s_waitcnt lgkmcnt(14)
	v_mfma_f32_32x32x16_bf16 v[18:33], v[166:169], v[234:237], v[18:33]
	v_exp_f32_e32 v114, v114
	v_exp_f32_e32 v115, v115
	v_exp_f32_e32 v116, v116
	v_exp_f32_e32 v117, v117
	s_waitcnt lgkmcnt(12)
	v_mfma_f32_32x32x16_bf16 v[34:49], v[166:169], v[82:85], v[34:49]
	v_exp_f32_e32 v118, v118
	v_exp_f32_e32 v119, v119
	v_exp_f32_e32 v120, v120
	v_exp_f32_e32 v121, v121
	v_add_u32_e32 v82, s49, v228
	ds_read_b128 v[78:81], v82
	ds_read_b128 v[134:137], v82 offset:512
	s_waitcnt lgkmcnt(12)
	v_mfma_f32_32x32x16_bf16 v[18:33], v[158:161], v[86:89], v[18:33]
	v_exp_f32_e32 v122, v122
	v_exp_f32_e32 v123, v123
	v_exp_f32_e32 v124, v124
	v_exp_f32_e32 v125, v125
	ds_read_b128 v[138:141], v82 offset:2048
	ds_read_b128 v[142:145], v82 offset:2560
	s_waitcnt lgkmcnt(12)
	v_mfma_f32_32x32x16_bf16 v[34:49], v[158:161], v[90:93], v[34:49]
	v_exp_f32_e32 v126, v126
	v_exp_f32_e32 v127, v127
	v_exp_f32_e32 v128, v128
	v_exp_f32_e32 v129, v129
	ds_read_b128 v[178:181], v82 offset:4096
	ds_read_b128 v[182:185], v82 offset:4608
	s_waitcnt lgkmcnt(12)
	v_mfma_f32_32x32x16_bf16 v[18:33], v[150:153], v[94:97], v[18:33]
	v_exp_f32_e32 v98, v98
	v_exp_f32_e32 v99, v99
	v_exp_f32_e32 v100, v100
	v_exp_f32_e32 v101, v101
	ds_read_b128 v[186:189], v82 offset:6144
	ds_read_b128 v[130:133], v82 offset:6656
	s_waitcnt lgkmcnt(12)
	v_mfma_f32_32x32x16_bf16 v[34:49], v[150:153], v[66:69], v[34:49]
	v_exp_f32_e32 v102, v102
	v_exp_f32_e32 v103, v103
	v_exp_f32_e32 v104, v104
	v_exp_f32_e32 v105, v105
	s_waitcnt lgkmcnt(10)
	v_mfma_f32_32x32x16_bf16 v[18:33], v[146:149], v[70:73], v[18:33]
	v_exp_f32_e32 v106, v106
	v_exp_f32_e32 v107, v107
	v_exp_f32_e32 v108, v108
	v_exp_f32_e32 v109, v109
	s_waitcnt lgkmcnt(8)
	v_mfma_f32_32x32x16_bf16 v[34:49], v[146:149], v[74:77], v[34:49]
	v_exp_f32_e32 v110, v110
	v_exp_f32_e32 v111, v111
	v_exp_f32_e32 v112, v112
	v_exp_f32_e32 v113, v113
	s_add_i32 s40, s49, 0x2000
	s_cmpk_lg_i32 s49, 0x4000
	s_cselect_b32 s40, s40, 0
	v_add_u32_e32 v232, s65, v227
	s_waitcnt vmcnt(2) lgkmcnt(0)
	s_barrier
	ds_read_b64_tr_b16 v[234:235], v232 offset:24576
	ds_read_b64_tr_b16 v[236:237], v232 offset:25088
	s_waitcnt lgkmcnt(9)
	v_mfma_f32_32x32x16_bf16 v[82:97], v[78:81], v[174:177], v[50:65]
	v_add_f32_e32 v66, v114, v115
	v_add_f32_e32 v66, v116, v66
	v_add_f32_e32 v66, v117, v66
	v_add_f32_e32 v66, v118, v66
	v_add_f32_e32 v66, v119, v66
	v_cvt_pk_bf16_f32 v166, v114, v115
	v_cvt_pk_bf16_f32 v167, v116, v117
	ds_read_b64_tr_b16 v[114:115], v232 offset:28672
	ds_read_b64_tr_b16 v[116:117], v232 offset:29184
	v_add_f32_e32 v66, v120, v66
	v_add_f32_e32 v66, v121, v66
	v_add_f32_e32 v66, v122, v66
	v_add_f32_e32 v146, v123, v66
	s_waitcnt lgkmcnt(10)
	v_mfma_f32_32x32x16_bf16 v[66:81], v[134:137], v[174:177], v[50:65]
	v_cvt_pk_bf16_f32 v168, v118, v119
	v_cvt_pk_bf16_f32 v169, v120, v121
	ds_read_b64_tr_b16 v[118:119], v232 offset:25600
	ds_read_b64_tr_b16 v[120:121], v232 offset:26112
	s_waitcnt lgkmcnt(11)
	v_mfma_f32_32x32x16_bf16 v[82:97], v[138:141], v[170:173], v[82:97]
	v_add_f32_e32 v134, v124, v146
	v_add_f32_e32 v134, v125, v134
	v_add_f32_e32 v134, v126, v134
	v_add_f32_e32 v134, v127, v134
	v_cvt_pk_bf16_f32 v158, v122, v123
	v_cvt_pk_bf16_f32 v159, v124, v125
	ds_read_b64_tr_b16 v[122:123], v232 offset:29696
	ds_read_b64_tr_b16 v[124:125], v232 offset:30208
	s_waitcnt lgkmcnt(12)
	v_mfma_f32_32x32x16_bf16 v[66:81], v[142:145], v[170:173], v[66:81]
	v_add_f32_e32 v134, v128, v134
	v_add_f32_e32 v134, v129, v134
	v_add_f32_e32 v134, v98, v134
	v_add_f32_e32 v134, v99, v134
	v_cvt_pk_bf16_f32 v160, v126, v127
	v_cvt_pk_bf16_f32 v161, v128, v129
	ds_read_b64_tr_b16 v[126:127], v232 offset:26624
	ds_read_b64_tr_b16 v[128:129], v232 offset:27136
	s_waitcnt lgkmcnt(13)
	v_mfma_f32_32x32x16_bf16 v[82:97], v[178:181], v[162:165], v[82:97]
	v_add_f32_e32 v134, v100, v134
	v_add_f32_e32 v134, v101, v134
	v_add_f32_e32 v134, v102, v134
	v_add_f32_e32 v134, v103, v134
	v_cvt_pk_bf16_f32 v150, v98, v99
	v_cvt_pk_bf16_f32 v151, v100, v101
	ds_read_b64_tr_b16 v[238:239], v232 offset:30720
	ds_read_b64_tr_b16 v[240:241], v232 offset:31232
	s_waitcnt lgkmcnt(14)
	v_mfma_f32_32x32x16_bf16 v[66:81], v[182:185], v[162:165], v[66:81]
	v_add_f32_e32 v98, v104, v134
	v_add_f32_e32 v98, v105, v98
	v_add_f32_e32 v98, v106, v98
	v_add_f32_e32 v98, v107, v98
	v_cvt_pk_bf16_f32 v152, v102, v103
	v_cvt_pk_bf16_f32 v153, v104, v105
	ds_read_b64_tr_b16 v[102:103], v232 offset:27648
	ds_read_b64_tr_b16 v[104:105], v232 offset:28160
	s_waitcnt lgkmcnt(14)
; #define WAIT_BAR(N) asm volatile("s_waitcnt vmcnt(" #N ") lgkmcnt(0)\n\ts_barrier":::"memory")
;   #define RESC() do{ if(!FIXREF&&resc){ asm volatile("s_waitcnt lgkmcnt(0)":::"memory"); \
;       _Pragma("unroll") for(int d_=0;d_<2;++d_) _Pragma("unroll") for(int r=0;r<16;++r)o[d_][r]*=wsf[crow(r,hi)]; } }while(0)
;   #define ROT() do{sl_prev=sl_cur;sl_cur=sl_next;sl_next=(sl_next==(NSLOT-1)*SLOTB)?0:sl_next+SLOTB;}while(0)
;   #define ENDW(tt) do{ if((tt)+3<NT){WAIT_BAR(2);} else if((tt)+2<NT){WAIT_BAR(1);} else {WAIT_BAR(0);} }while(0)
; template<int THRL,bool FIXREF,bool HALFK> __device__ __forceinline__ void attn_unit(float mref,long rowbase,int q0,const bf16*Qh,int PQ,const bf16*__restrict__ Kh_,int PK,const bf16*__restrict__ Vh_,int PV,bf16*Oh,int PO,const bf16*Gh,int PG,u32x4(&okeep)[4],int omode,float lam,float oml,const float ...
;     ...
;   int t=1;
;     ...
;   for(;t+5<NT;t+=2){
;     STEP(pB0,pB1,pA0,pA1,t,true,true,true);     WAIT_BAR(2); RESC(); ROT();
;     STEP(pA0,pA1,pB0,pB1,t+1,true,true,true);   WAIT_BAR(2); RESC(); ROT();
;     ...
;   for(;t+1<NT;t+=2){
;     STEP(pB0,pB1,pA0,pA1,t,(t+3<NT),(t+1<NT),(t+1<NT));       ENDW(t);   RESC(); ROT();
	v_mfma_f32_32x32x16_bf16 v[82:97], v[186:189], v[154:157], v[82:97]
	v_add_f32_e32 v98, v108, v98
	v_add_f32_e32 v98, v109, v98
	v_add_f32_e32 v98, v110, v98
	v_add_f32_e32 v98, v111, v98
	v_cvt_pk_bf16_f32 v146, v106, v107
	v_cvt_pk_bf16_f32 v147, v108, v109
	ds_read_b64_tr_b16 v[106:107], v232 offset:31744
	ds_read_b64_tr_b16 v[108:109], v232 offset:32256
	v_mfma_f32_32x32x16_bf16 v[66:81], v[130:133], v[154:157], v[66:81]
	v_add_f32_e32 v98, v112, v98
	v_add_f32_e32 v98, v113, v98
	v_cvt_pk_bf16_f32 v148, v110, v111
	v_cvt_pk_bf16_f32 v149, v112, v113
	s_nop 0
	v_add_f32_e32 v232, v0, v98
	v_lshl_add_u64 v[98:99], v[214:215], 0, s[92:93]
	s_add_i32 s41, s49, s62
	s_mov_b32 s42, m0
	s_mov_b32 m0, s41
	s_nop 0
	global_load_lds_dwordx4 v[98:99], off
	s_mov_b32 m0, s42
	v_lshl_add_u64 v[212:213], v[212:213], 0, s[4:5]
	s_add_i32 s41, s40, s61
	s_mov_b32 s42, m0
	s_mov_b32 m0, s41
	s_nop 0
	global_load_lds_dwordx4 v[212:213], off
	s_mov_b32 m0, s42
	s_waitcnt lgkmcnt(14)
	v_mfma_f32_32x32x16_bf16 v[18:33], v[166:169], v[234:237], v[18:33]
	v_exp_f32_e32 v82, v82
	v_exp_f32_e32 v83, v83
	v_exp_f32_e32 v84, v84
	v_exp_f32_e32 v85, v85
	s_waitcnt lgkmcnt(12)
	v_mfma_f32_32x32x16_bf16 v[34:49], v[166:169], v[114:117], v[34:49]
	v_exp_f32_e32 v86, v86
	v_exp_f32_e32 v87, v87
	v_exp_f32_e32 v88, v88
	v_exp_f32_e32 v89, v89
	v_add_u32_e32 v0, s40, v228
	ds_read_b128 v[98:101], v0
	ds_read_b128 v[182:185], v0 offset:512
	s_waitcnt lgkmcnt(12)
	v_mfma_f32_32x32x16_bf16 v[18:33], v[158:161], v[118:121], v[18:33]
	v_exp_f32_e32 v90, v90
	v_exp_f32_e32 v91, v91
	v_exp_f32_e32 v92, v92
	v_exp_f32_e32 v93, v93
	ds_read_b128 v[186:189], v0 offset:2048
	ds_read_b128 v[178:181], v0 offset:2560
	s_waitcnt lgkmcnt(12)
	v_mfma_f32_32x32x16_bf16 v[34:49], v[158:161], v[122:125], v[34:49]
	v_exp_f32_e32 v94, v94
	v_exp_f32_e32 v95, v95
	v_exp_f32_e32 v96, v96
	v_exp_f32_e32 v97, v97
	ds_read_b128 v[142:145], v0 offset:4096
	ds_read_b128 v[138:141], v0 offset:4608
	s_waitcnt lgkmcnt(12)
	v_mfma_f32_32x32x16_bf16 v[18:33], v[150:153], v[126:129], v[18:33]
	v_exp_f32_e32 v66, v66
	v_exp_f32_e32 v67, v67
	v_exp_f32_e32 v68, v68
	v_exp_f32_e32 v69, v69
	ds_read_b128 v[134:137], v0 offset:6144
	ds_read_b128 v[130:133], v0 offset:6656
	s_waitcnt lgkmcnt(12)
	v_mfma_f32_32x32x16_bf16 v[34:49], v[150:153], v[238:241], v[34:49]
	v_exp_f32_e32 v70, v70
	v_exp_f32_e32 v71, v71
	v_exp_f32_e32 v72, v72
	v_exp_f32_e32 v73, v73
	s_waitcnt lgkmcnt(10)
	v_mfma_f32_32x32x16_bf16 v[18:33], v[146:149], v[102:105], v[18:33]
	v_exp_f32_e32 v74, v74
	v_exp_f32_e32 v75, v75
	v_exp_f32_e32 v76, v76
	v_exp_f32_e32 v77, v77
	s_waitcnt lgkmcnt(8)
	v_mfma_f32_32x32x16_bf16 v[34:49], v[146:149], v[106:109], v[34:49]
	v_exp_f32_e32 v78, v78
	v_exp_f32_e32 v79, v79
	v_exp_f32_e32 v80, v80
	v_exp_f32_e32 v81, v81
	s_add_i32 s41, s40, 0x2000
	s_cmpk_lg_i32 s40, 0x4000
	s_mov_b32 s66, s49
	v_add_u32_e32 v0, s66, v227
	s_cselect_b32 s49, s41, 0
	s_add_i32 s48, s48, 2
	v_lshl_add_u64 v[214:215], v[214:215], 0, s[10:11]
	s_mov_b32 s65, s40
	s_cmp_gt_u32 s48, 56
	s_waitcnt vmcnt(2) lgkmcnt(0)
	s_barrier
	s_cbranch_scc0 .LBB0_451
	s_and_b32 s41, s64, 0x3fffffc0
	s_cmp_lg_u32 0, -1
	s_cselect_b32 s40, 0, 0
	s_add_i32 s42, s40, 0x6000
	v_add_u32_e32 v0, s42, v231
	s_lshl_b32 s41, s41, 2
	s_add_i32 s42, s41, 0
	v_add3_u32 v0, v0, v229, v230
	ds_read_b64_tr_b16 v[212:213], v227 offset:32768
	ds_read_b64_tr_b16 v[214:215], v227 offset:33280
	v_add_f32_e32 v102, v82, v83
	v_add_f32_e32 v102, v84, v102
	v_add_f32_e32 v102, v85, v102
	v_add_f32_e32 v102, v86, v102
	v_add_f32_e32 v102, v87, v102
	v_cvt_pk_bf16_f32 v166, v82, v83
	v_cvt_pk_bf16_f32 v167, v84, v85
	s_waitcnt lgkmcnt(9)
	v_mfma_f32_32x32x16_bf16 v[114:129], v[98:101], v[174:177], v[50:65]
	ds_read_b64_tr_b16 v[82:83], v227 offset:36864
	ds_read_b64_tr_b16 v[84:85], v227 offset:37376
	v_add_f32_e32 v98, v88, v102
	v_add_f32_e32 v98, v89, v98
	v_add_f32_e32 v98, v90, v98
	v_add_f32_e32 v146, v91, v98
	v_cvt_pk_bf16_f32 v168, v86, v87
	v_cvt_pk_bf16_f32 v169, v88, v89
	s_waitcnt lgkmcnt(10)
	v_mfma_f32_32x32x16_bf16 v[98:113], v[182:185], v[174:177], v[50:65]
	ds_read_b64_tr_b16 v[86:87], v227 offset:33792
	ds_read_b64_tr_b16 v[88:89], v227 offset:34304
	v_add_f32_e32 v146, v92, v146
	v_add_f32_e32 v146, v93, v146
	v_add_f32_e32 v146, v94, v146
	v_add_f32_e32 v146, v95, v146
	v_cvt_pk_bf16_f32 v158, v90, v91
	v_cvt_pk_bf16_f32 v159, v92, v93
	s_waitcnt lgkmcnt(11)
	v_mfma_f32_32x32x16_bf16 v[114:129], v[186:189], v[170:173], v[114:129]
	ds_read_b64_tr_b16 v[90:91], v227 offset:37888
	ds_read_b64_tr_b16 v[92:93], v227 offset:38400
	v_add_f32_e32 v146, v96, v146
	v_add_f32_e32 v146, v97, v146
	v_add_f32_e32 v146, v66, v146
	v_add_f32_e32 v146, v67, v146
	v_cvt_pk_bf16_f32 v160, v94, v95
	v_cvt_pk_bf16_f32 v161, v96, v97
	s_waitcnt lgkmcnt(12)
	v_mfma_f32_32x32x16_bf16 v[98:113], v[178:181], v[170:173], v[98:113]
	ds_read_b64_tr_b16 v[94:95], v227 offset:34816
	ds_read_b64_tr_b16 v[96:97], v227 offset:35328
	s_waitcnt lgkmcnt(13)
	v_mfma_f32_32x32x16_bf16 v[114:129], v[142:145], v[162:165], v[114:129]
	v_add_f32_e32 v142, v68, v146
	v_add_f32_e32 v142, v69, v142
	v_add_f32_e32 v142, v70, v142
	v_add_f32_e32 v142, v71, v142
	v_cvt_pk_bf16_f32 v150, v66, v67
	v_cvt_pk_bf16_f32 v151, v68, v69
	ds_read_b64_tr_b16 v[66:67], v227 offset:38912
	ds_read_b64_tr_b16 v[68:69], v227 offset:39424
	s_waitcnt lgkmcnt(14)
	v_mfma_f32_32x32x16_bf16 v[98:113], v[138:141], v[162:165], v[98:113]
	v_add_f32_e32 v138, v72, v142
	v_add_f32_e32 v138, v73, v138
	v_add_f32_e32 v138, v74, v138
	v_add_f32_e32 v138, v75, v138
	v_cvt_pk_bf16_f32 v152, v70, v71
	v_cvt_pk_bf16_f32 v153, v72, v73
	ds_read_b64_tr_b16 v[70:71], v227 offset:35840
	ds_read_b64_tr_b16 v[72:73], v227 offset:36352
	s_waitcnt lgkmcnt(14)
	v_mfma_f32_32x32x16_bf16 v[114:129], v[134:137], v[154:157], v[114:129]
	v_add_f32_e32 v134, v76, v138
	v_add_f32_e32 v134, v77, v134
	v_add_f32_e32 v134, v78, v134
	v_add_f32_e32 v134, v79, v134
	v_cvt_pk_bf16_f32 v146, v74, v75
	v_cvt_pk_bf16_f32 v147, v76, v77
	ds_read_b64_tr_b16 v[74:75], v227 offset:39936
	ds_read_b64_tr_b16 v[76:77], v227 offset:40448
	v_mfma_f32_32x32x16_bf16 v[98:113], v[130:133], v[154:157], v[98:113]
	v_add_f32_e32 v130, v80, v134
	v_add_f32_e32 v130, v81, v130
	v_add_f32_e32 v130, 0, v130
	v_cvt_pk_bf16_f32 v148, v78, v79
	v_cvt_pk_bf16_f32 v149, v80, v81
	s_mov_b64 s[46:47], 0xf8000
	s_add_i32 s40, s40, s63
	v_lshl_add_u64 v[78:79], v[210:211], 0, s[46:47]
	s_add_i32 s41, s40, 0x4000
	s_mov_b32 s43, m0
	s_mov_b32 m0, s41
	s_nop 0
	global_load_lds_dwordx4 v[78:79], off
	s_mov_b32 m0, s43
	v_lshl_add_u64 v[78:79], v[208:209], 0, s[18:19]
	s_mov_b32 s41, m0
	s_mov_b32 m0, s61
	s_nop 0
	global_load_lds_dwordx4 v[78:79], off
	s_mov_b32 m0, s41
	v_add_f32_e32 v229, v232, v130
	s_waitcnt lgkmcnt(14)
	v_mfma_f32_32x32x16_bf16 v[18:33], v[166:169], v[212:215], v[18:33]
	v_exp_f32_e32 v114, v114
	v_exp_f32_e32 v115, v115
	v_exp_f32_e32 v116, v116
	v_exp_f32_e32 v117, v117
	s_waitcnt lgkmcnt(12)
	v_mfma_f32_32x32x16_bf16 v[34:49], v[166:169], v[82:85], v[34:49]
	v_exp_f32_e32 v118, v118
	v_exp_f32_e32 v119, v119
	v_exp_f32_e32 v120, v120
	v_exp_f32_e32 v121, v121
	ds_read_b128 v[78:81], v228
	ds_read_b128 v[178:181], v228 offset:512
	s_waitcnt lgkmcnt(12)
	v_mfma_f32_32x32x16_bf16 v[18:33], v[158:161], v[86:89], v[18:33]
	v_exp_f32_e32 v122, v122
	v_exp_f32_e32 v123, v123
	v_exp_f32_e32 v124, v124
	v_exp_f32_e32 v125, v125
	ds_read_b128 v[86:89], v228 offset:2048
	ds_read_b128 v[182:185], v228 offset:2560
	s_waitcnt lgkmcnt(12)
	v_mfma_f32_32x32x16_bf16 v[34:49], v[158:161], v[90:93], v[34:49]
	v_exp_f32_e32 v126, v126
	v_exp_f32_e32 v127, v127
	v_exp_f32_e32 v128, v128
	v_exp_f32_e32 v129, v129
	ds_read_b128 v[90:93], v228 offset:4096
	ds_read_b128 v[186:189], v228 offset:4608
	s_waitcnt lgkmcnt(12)
	v_mfma_f32_32x32x16_bf16 v[18:33], v[150:153], v[94:97], v[18:33]
	v_exp_f32_e32 v98, v98
	v_exp_f32_e32 v99, v99
	v_exp_f32_e32 v100, v100
	v_exp_f32_e32 v101, v101
	ds_read_b128 v[94:97], v228 offset:6144
	ds_read_b128 v[82:85], v228 offset:6656
	s_waitcnt lgkmcnt(12)
	v_mfma_f32_32x32x16_bf16 v[34:49], v[150:153], v[66:69], v[34:49]
	v_exp_f32_e32 v102, v102
	v_exp_f32_e32 v103, v103
	v_exp_f32_e32 v104, v104
	v_exp_f32_e32 v105, v105
	s_waitcnt lgkmcnt(10)
	v_mfma_f32_32x32x16_bf16 v[18:33], v[146:149], v[70:73], v[18:33]
	v_exp_f32_e32 v106, v106
	v_exp_f32_e32 v107, v107
	v_exp_f32_e32 v108, v108
	v_exp_f32_e32 v109, v109
	s_waitcnt lgkmcnt(8)
	v_mfma_f32_32x32x16_bf16 v[34:49], v[146:149], v[74:77], v[34:49]
	v_exp_f32_e32 v110, v110
	v_exp_f32_e32 v111, v111
	v_exp_f32_e32 v112, v112
	v_exp_f32_e32 v113, v113
	s_waitcnt vmcnt(2) lgkmcnt(0)
	s_barrier
	ds_read_b64_tr_b16 v[212:213], v227 offset:40960
	ds_read_b64_tr_b16 v[214:215], v227 offset:41472
	v_add_f32_e32 v66, v114, v115
	v_add_f32_e32 v66, v116, v66
	v_add_f32_e32 v66, v117, v66
	v_add_f32_e32 v66, v118, v66
	v_add_f32_e32 v66, v119, v66
	v_cvt_pk_bf16_f32 v166, v114, v115
	v_cvt_pk_bf16_f32 v167, v116, v117
	s_waitcnt lgkmcnt(9)
	v_mfma_f32_32x32x16_bf16 v[130:145], v[78:81], v[174:177], v[50:65]
	ds_read_b64_tr_b16 v[114:115], v227 offset:45056
	ds_read_b64_tr_b16 v[116:117], v227 offset:45568
	v_add_f32_e32 v66, v120, v66
	v_add_f32_e32 v66, v121, v66
	v_add_f32_e32 v66, v122, v66
	v_add_f32_e32 v146, v123, v66
	s_waitcnt lgkmcnt(10)
	v_mfma_f32_32x32x16_bf16 v[66:81], v[178:181], v[174:177], v[50:65]
	v_cvt_pk_bf16_f32 v168, v118, v119
	v_cvt_pk_bf16_f32 v169, v120, v121
	ds_read_b64_tr_b16 v[118:119], v227 offset:41984
	ds_read_b64_tr_b16 v[120:121], v227 offset:42496
	s_waitcnt lgkmcnt(11)
	v_mfma_f32_32x32x16_bf16 v[130:145], v[86:89], v[170:173], v[130:145]
	v_add_f32_e32 v86, v124, v146
	v_add_f32_e32 v86, v125, v86
	v_add_f32_e32 v86, v126, v86
	v_add_f32_e32 v146, v127, v86
	v_cvt_pk_bf16_f32 v158, v122, v123
	v_cvt_pk_bf16_f32 v159, v124, v125
	ds_read_b64_tr_b16 v[86:87], v227 offset:46080
	ds_read_b64_tr_b16 v[88:89], v227 offset:46592
	s_waitcnt lgkmcnt(12)
	v_mfma_f32_32x32x16_bf16 v[66:81], v[182:185], v[170:173], v[66:81]
	v_add_f32_e32 v122, v128, v146
	v_add_f32_e32 v122, v129, v122
	v_add_f32_e32 v122, v98, v122
	v_add_f32_e32 v146, v99, v122
	v_cvt_pk_bf16_f32 v160, v126, v127
	v_cvt_pk_bf16_f32 v161, v128, v129
	ds_read_b64_tr_b16 v[122:123], v227 offset:43008
	ds_read_b64_tr_b16 v[124:125], v227 offset:43520
	s_waitcnt lgkmcnt(13)
	v_mfma_f32_32x32x16_bf16 v[130:145], v[90:93], v[162:165], v[130:145]
	v_add_f32_e32 v90, v100, v146
	v_add_f32_e32 v90, v101, v90
	v_add_f32_e32 v90, v102, v90
	v_add_f32_e32 v126, v103, v90
	v_cvt_pk_bf16_f32 v150, v98, v99
	v_cvt_pk_bf16_f32 v151, v100, v101
	ds_read_b64_tr_b16 v[90:91], v227 offset:47104
	ds_read_b64_tr_b16 v[92:93], v227 offset:47616
	s_waitcnt lgkmcnt(14)
	v_mfma_f32_32x32x16_bf16 v[66:81], v[186:189], v[162:165], v[66:81]
	v_add_f32_e32 v98, v104, v126
	v_add_f32_e32 v98, v105, v98
	v_add_f32_e32 v98, v106, v98
	v_add_f32_e32 v98, v107, v98
	v_cvt_pk_bf16_f32 v152, v102, v103
	v_cvt_pk_bf16_f32 v153, v104, v105
	ds_read_b64_tr_b16 v[102:103], v227 offset:44032
	ds_read_b64_tr_b16 v[104:105], v227 offset:44544
	s_waitcnt lgkmcnt(14)
	v_mfma_f32_32x32x16_bf16 v[130:145], v[94:97], v[154:157], v[130:145]
	v_add_f32_e32 v94, v108, v98
	v_add_f32_e32 v94, v109, v94
	v_add_f32_e32 v94, v110, v94
	v_add_f32_e32 v98, v111, v94
	v_cvt_pk_bf16_f32 v146, v106, v107
	v_cvt_pk_bf16_f32 v147, v108, v109
	ds_read_b64_tr_b16 v[94:95], v227 offset:48128
	ds_read_b64_tr_b16 v[96:97], v227 offset:48640
	v_mfma_f32_32x32x16_bf16 v[66:81], v[82:85], v[154:157], v[66:81]
	v_add_f32_e32 v82, v112, v98
	v_add_f32_e32 v82, v113, v82
	v_add_f32_e32 v82, 0, v82
	v_cvt_pk_bf16_f32 v148, v110, v111
	v_cvt_pk_bf16_f32 v149, v112, v113
	s_mov_b64 s[46:47], 0xfc000
	v_add_f32_e32 v229, v229, v82
	v_lshl_add_u64 v[82:83], v[210:211], 0, s[46:47]
	s_mov_b32 s41, m0
	s_mov_b32 m0, s62
	s_nop 0
	global_load_lds_dwordx4 v[82:83], off
	s_mov_b32 m0, s41
	v_lshl_add_u64 v[82:83], v[208:209], 0, s[6:7]
	s_add_i32 s41, s40, 0x8000
	s_mov_b32 s43, m0
	s_mov_b32 m0, s41
	s_nop 0
	global_load_lds_dwordx4 v[82:83], off
	s_mov_b32 m0, s43
	s_waitcnt lgkmcnt(14)
	v_mfma_f32_32x32x16_bf16 v[18:33], v[166:169], v[212:215], v[18:33]
	v_exp_f32_e32 v130, v130
	v_exp_f32_e32 v131, v131
	v_exp_f32_e32 v132, v132
	v_exp_f32_e32 v133, v133
	s_waitcnt lgkmcnt(12)
	v_mfma_f32_32x32x16_bf16 v[34:49], v[166:169], v[114:117], v[34:49]
	v_exp_f32_e32 v134, v134
	v_exp_f32_e32 v135, v135
	v_exp_f32_e32 v136, v136
	v_exp_f32_e32 v137, v137
	ds_read_b128 v[82:85], v228 offset:8192
	ds_read_b128 v[106:109], v228 offset:8704
	s_waitcnt lgkmcnt(12)
	v_mfma_f32_32x32x16_bf16 v[18:33], v[158:161], v[118:121], v[18:33]
	v_exp_f32_e32 v138, v138
	v_exp_f32_e32 v139, v139
	v_exp_f32_e32 v140, v140
	v_exp_f32_e32 v141, v141
	ds_read_b128 v[110:113], v228 offset:10240
	ds_read_b128 v[178:181], v228 offset:10752
	s_waitcnt lgkmcnt(12)
	v_mfma_f32_32x32x16_bf16 v[34:49], v[158:161], v[86:89], v[34:49]
	v_exp_f32_e32 v142, v142
	v_exp_f32_e32 v143, v143
	v_exp_f32_e32 v144, v144
	v_exp_f32_e32 v145, v145
	ds_read_b128 v[182:185], v228 offset:12288
	ds_read_b128 v[186:189], v228 offset:12800
	s_waitcnt lgkmcnt(12)
	v_mfma_f32_32x32x16_bf16 v[18:33], v[150:153], v[122:125], v[18:33]
	v_exp_f32_e32 v66, v66
	v_exp_f32_e32 v67, v67
	v_exp_f32_e32 v68, v68
	v_exp_f32_e32 v69, v69
	ds_read_b128 v[210:213], v228 offset:14336
	ds_read_b128 v[98:101], v228 offset:14848
	s_waitcnt lgkmcnt(12)
	v_mfma_f32_32x32x16_bf16 v[34:49], v[150:153], v[90:93], v[34:49]
	v_exp_f32_e32 v70, v70
	v_exp_f32_e32 v71, v71
	v_exp_f32_e32 v72, v72
	v_exp_f32_e32 v73, v73
	s_waitcnt lgkmcnt(10)
	v_mfma_f32_32x32x16_bf16 v[18:33], v[146:149], v[102:105], v[18:33]
	v_exp_f32_e32 v74, v74
	v_exp_f32_e32 v75, v75
	v_exp_f32_e32 v76, v76
	v_exp_f32_e32 v77, v77
	s_waitcnt lgkmcnt(8)
	v_mfma_f32_32x32x16_bf16 v[34:49], v[146:149], v[94:97], v[34:49]
	v_exp_f32_e32 v78, v78
	v_exp_f32_e32 v79, v79
	v_exp_f32_e32 v80, v80
	v_exp_f32_e32 v81, v81
	s_waitcnt vmcnt(2) lgkmcnt(0)
	s_barrier
	ds_read_b64_tr_b16 v[102:103], v227 offset:24576
	ds_read_b64_tr_b16 v[104:105], v227 offset:25088
	v_add_f32_e32 v86, v130, v131
	v_add_f32_e32 v86, v132, v86
	v_add_f32_e32 v86, v133, v86
	v_add_f32_e32 v86, v134, v86
	v_add_f32_e32 v86, v135, v86
	v_cvt_pk_bf16_f32 v166, v130, v131
	v_cvt_pk_bf16_f32 v167, v132, v133
	s_waitcnt lgkmcnt(9)
	v_mfma_f32_32x32x16_bf16 v[114:129], v[82:85], v[174:177], v[50:65]
	ds_read_b64_tr_b16 v[130:131], v227 offset:28672
	ds_read_b64_tr_b16 v[132:133], v227 offset:29184
	v_add_f32_e32 v82, v136, v86
	v_add_f32_e32 v82, v137, v82
	v_add_f32_e32 v82, v138, v82
	v_add_f32_e32 v146, v139, v82
	v_cvt_pk_bf16_f32 v168, v134, v135
	v_cvt_pk_bf16_f32 v169, v136, v137
	s_waitcnt lgkmcnt(10)
	v_mfma_f32_32x32x16_bf16 v[82:97], v[106:109], v[174:177], v[50:65]
	ds_read_b64_tr_b16 v[106:107], v227 offset:25600
	ds_read_b64_tr_b16 v[108:109], v227 offset:26112
	s_waitcnt lgkmcnt(11)
	v_mfma_f32_32x32x16_bf16 v[114:129], v[110:113], v[170:173], v[114:129]
	v_add_f32_e32 v110, v140, v146
	v_add_f32_e32 v110, v141, v110
	v_add_f32_e32 v110, v142, v110
	v_add_f32_e32 v134, v143, v110
	v_cvt_pk_bf16_f32 v158, v138, v139
	v_cvt_pk_bf16_f32 v159, v140, v141
	ds_read_b64_tr_b16 v[110:111], v227 offset:29696
	ds_read_b64_tr_b16 v[112:113], v227 offset:30208
	v_add_f32_e32 v134, v144, v134
	v_add_f32_e32 v134, v145, v134
	v_add_f32_e32 v134, v66, v134
	v_add_f32_e32 v138, v67, v134
	v_cvt_pk_bf16_f32 v160, v142, v143
	v_cvt_pk_bf16_f32 v161, v144, v145
	s_waitcnt lgkmcnt(12)
	v_mfma_f32_32x32x16_bf16 v[82:97], v[178:181], v[170:173], v[82:97]
	ds_read_b64_tr_b16 v[134:135], v227 offset:26624
	ds_read_b64_tr_b16 v[136:137], v227 offset:27136
	v_add_f32_e32 v138, v68, v138
	v_add_f32_e32 v138, v69, v138
	v_add_f32_e32 v138, v70, v138
	v_add_f32_e32 v138, v71, v138
	v_cvt_pk_bf16_f32 v150, v66, v67
	v_cvt_pk_bf16_f32 v151, v68, v69
	s_waitcnt lgkmcnt(13)
	v_mfma_f32_32x32x16_bf16 v[114:129], v[182:185], v[162:165], v[114:129]
	ds_read_b64_tr_b16 v[66:67], v227 offset:30720
	ds_read_b64_tr_b16 v[68:69], v227 offset:31232
	v_add_f32_e32 v138, v72, v138
	v_add_f32_e32 v138, v73, v138
	v_add_f32_e32 v138, v74, v138
	v_add_f32_e32 v138, v75, v138
	v_cvt_pk_bf16_f32 v152, v70, v71
	v_cvt_pk_bf16_f32 v153, v72, v73
	s_waitcnt lgkmcnt(14)
	v_mfma_f32_32x32x16_bf16 v[82:97], v[186:189], v[162:165], v[82:97]
	ds_read_b64_tr_b16 v[70:71], v227 offset:27648
	ds_read_b64_tr_b16 v[72:73], v227 offset:28160
	v_add_f32_e32 v138, v76, v138
	v_add_f32_e32 v138, v77, v138
	v_add_f32_e32 v138, v78, v138
	v_add_f32_e32 v138, v79, v138
	v_cvt_pk_bf16_f32 v146, v74, v75
	v_cvt_pk_bf16_f32 v147, v76, v77
	s_waitcnt lgkmcnt(14)
	v_mfma_f32_32x32x16_bf16 v[114:129], v[210:213], v[154:157], v[114:129]
	ds_read_b64_tr_b16 v[74:75], v227 offset:31744
	ds_read_b64_tr_b16 v[76:77], v227 offset:32256
	v_mfma_f32_32x32x16_bf16 v[82:97], v[98:101], v[154:157], v[82:97]
	v_add_f32_e32 v98, v80, v138
	v_add_f32_e32 v98, v81, v98
	v_add_f32_e32 v98, 0, v98
	v_cvt_pk_bf16_f32 v148, v78, v79
	v_cvt_pk_bf16_f32 v149, v80, v81
	v_lshl_add_u64 v[78:79], v[208:209], 0, s[94:95]
	s_add_i32 s40, s40, 0xa000
	s_mov_b32 s41, m0
	s_mov_b32 m0, s40
	s_nop 0
	global_load_lds_dwordx4 v[78:79], off
	s_mov_b32 m0, s41
	v_add_f32_e32 v214, v229, v98
	s_waitcnt lgkmcnt(14)
	v_mfma_f32_32x32x16_bf16 v[18:33], v[166:169], v[102:105], v[18:33]
	v_exp_f32_e32 v114, v114
	v_exp_f32_e32 v115, v115
	v_exp_f32_e32 v116, v116
	v_exp_f32_e32 v117, v117
	s_waitcnt lgkmcnt(12)
	v_mfma_f32_32x32x16_bf16 v[34:49], v[166:169], v[130:133], v[34:49]
	v_exp_f32_e32 v118, v118
	v_exp_f32_e32 v119, v119
	v_exp_f32_e32 v120, v120
	v_exp_f32_e32 v121, v121
	ds_read_b128 v[78:81], v228 offset:16384
	ds_read_b128 v[138:141], v228 offset:16896
	s_waitcnt lgkmcnt(12)
	v_mfma_f32_32x32x16_bf16 v[18:33], v[158:161], v[106:109], v[18:33]
	v_exp_f32_e32 v122, v122
	v_exp_f32_e32 v123, v123
	v_exp_f32_e32 v124, v124
	v_exp_f32_e32 v125, v125
	ds_read_b128 v[142:145], v228 offset:18432
	ds_read_b128 v[178:181], v228 offset:18944
	s_waitcnt lgkmcnt(12)
	v_mfma_f32_32x32x16_bf16 v[34:49], v[158:161], v[110:113], v[34:49]
	v_exp_f32_e32 v126, v126
	v_exp_f32_e32 v127, v127
	v_exp_f32_e32 v128, v128
	v_exp_f32_e32 v129, v129
	ds_read_b128 v[182:185], v228 offset:20480
	ds_read_b128 v[186:189], v228 offset:20992
	s_waitcnt lgkmcnt(12)
	v_mfma_f32_32x32x16_bf16 v[18:33], v[150:153], v[134:137], v[18:33]
	v_exp_f32_e32 v82, v82
	v_exp_f32_e32 v83, v83
	v_exp_f32_e32 v84, v84
	v_exp_f32_e32 v85, v85
	ds_read_b128 v[134:137], v228 offset:22528
	ds_read_b128 v[130:133], v228 offset:23040
	s_waitcnt lgkmcnt(12)
	v_mfma_f32_32x32x16_bf16 v[34:49], v[150:153], v[66:69], v[34:49]
	v_exp_f32_e32 v86, v86
	v_exp_f32_e32 v87, v87
	v_exp_f32_e32 v88, v88
	v_exp_f32_e32 v89, v89
	s_waitcnt lgkmcnt(10)
	v_mfma_f32_32x32x16_bf16 v[18:33], v[146:149], v[70:73], v[18:33]
	v_exp_f32_e32 v90, v90
	v_exp_f32_e32 v91, v91
	v_exp_f32_e32 v92, v92
	v_exp_f32_e32 v93, v93
	s_waitcnt lgkmcnt(8)
	v_mfma_f32_32x32x16_bf16 v[34:49], v[146:149], v[74:77], v[34:49]
	v_exp_f32_e32 v94, v94
	v_exp_f32_e32 v95, v95
	v_exp_f32_e32 v96, v96
	v_exp_f32_e32 v97, v97
	s_waitcnt vmcnt(1) lgkmcnt(0)
	s_barrier
	ds_read_b64_tr_b16 v[210:211], v227 offset:32768
	ds_read_b64_tr_b16 v[212:213], v227 offset:33280
	v_add_f32_e32 v66, v114, v115
	v_add_f32_e32 v66, v116, v66
	v_add_f32_e32 v66, v117, v66
	v_add_f32_e32 v66, v118, v66
	v_add_f32_e32 v66, v119, v66
	v_cvt_pk_bf16_f32 v166, v114, v115
	v_cvt_pk_bf16_f32 v167, v116, v117
	s_waitcnt lgkmcnt(9)
	v_mfma_f32_32x32x16_bf16 v[98:113], v[78:81], v[174:177], v[50:65]
	ds_read_b64_tr_b16 v[114:115], v227 offset:36864
	ds_read_b64_tr_b16 v[116:117], v227 offset:37376
	v_add_f32_e32 v66, v120, v66
	v_add_f32_e32 v66, v121, v66
	v_add_f32_e32 v66, v122, v66
	v_add_f32_e32 v146, v123, v66
	s_waitcnt lgkmcnt(10)
	v_mfma_f32_32x32x16_bf16 v[66:81], v[138:141], v[174:177], v[50:65]
	v_cvt_pk_bf16_f32 v168, v118, v119
	v_cvt_pk_bf16_f32 v169, v120, v121
	ds_read_b64_tr_b16 v[138:139], v227 offset:33792
	ds_read_b64_tr_b16 v[140:141], v227 offset:34304
	v_add_f32_e32 v118, v124, v146
	v_add_f32_e32 v118, v125, v118
	v_add_f32_e32 v118, v126, v118
	v_add_f32_e32 v118, v127, v118
	v_cvt_pk_bf16_f32 v158, v122, v123
	v_cvt_pk_bf16_f32 v159, v124, v125
	s_waitcnt lgkmcnt(11)
	v_mfma_f32_32x32x16_bf16 v[98:113], v[142:145], v[170:173], v[98:113]
	ds_read_b64_tr_b16 v[120:121], v227 offset:37888
	ds_read_b64_tr_b16 v[122:123], v227 offset:38400
	s_waitcnt lgkmcnt(12)
	v_mfma_f32_32x32x16_bf16 v[66:81], v[178:181], v[170:173], v[66:81]
	v_add_f32_e32 v118, v128, v118
	v_add_f32_e32 v118, v129, v118
	v_add_f32_e32 v118, v82, v118
	v_add_f32_e32 v118, v83, v118
	v_cvt_pk_bf16_f32 v160, v126, v127
	v_cvt_pk_bf16_f32 v161, v128, v129
	ds_read_b64_tr_b16 v[124:125], v227 offset:34816
	ds_read_b64_tr_b16 v[126:127], v227 offset:35328
	v_add_f32_e32 v118, v84, v118
	v_add_f32_e32 v118, v85, v118
	v_add_f32_e32 v118, v86, v118
	v_add_f32_e32 v118, v87, v118
	v_cvt_pk_bf16_f32 v150, v82, v83
	v_cvt_pk_bf16_f32 v151, v84, v85
	s_waitcnt lgkmcnt(13)
	v_mfma_f32_32x32x16_bf16 v[98:113], v[182:185], v[162:165], v[98:113]
	ds_read_b64_tr_b16 v[82:83], v227 offset:38912
	ds_read_b64_tr_b16 v[84:85], v227 offset:39424
	s_waitcnt lgkmcnt(14)
	v_mfma_f32_32x32x16_bf16 v[66:81], v[186:189], v[162:165], v[66:81]
	v_add_f32_e32 v118, v88, v118
	v_add_f32_e32 v118, v89, v118
	v_add_f32_e32 v118, v90, v118
	v_add_f32_e32 v118, v91, v118
	v_cvt_pk_bf16_f32 v152, v86, v87
	v_cvt_pk_bf16_f32 v153, v88, v89
	ds_read_b64_tr_b16 v[86:87], v227 offset:35840
	ds_read_b64_tr_b16 v[88:89], v227 offset:36352
	v_add_f32_e32 v118, v92, v118
	v_add_f32_e32 v118, v93, v118
	v_add_f32_e32 v118, v94, v118
	v_add_f32_e32 v118, v95, v118
	v_cvt_pk_bf16_f32 v146, v90, v91
	v_cvt_pk_bf16_f32 v147, v92, v93
	s_waitcnt lgkmcnt(14)
	v_mfma_f32_32x32x16_bf16 v[98:113], v[134:137], v[154:157], v[98:113]
	ds_read_b64_tr_b16 v[90:91], v227 offset:39936
	ds_read_b64_tr_b16 v[92:93], v227 offset:40448
	v_mfma_f32_32x32x16_bf16 v[66:81], v[130:133], v[154:157], v[66:81]
	v_add_f32_e32 v118, v96, v118
	v_add_f32_e32 v118, v97, v118
	v_add_f32_e32 v118, 0, v118
	v_cvt_pk_bf16_f32 v148, v94, v95
	v_cvt_pk_bf16_f32 v149, v96, v97
	v_lshl_add_u64 v[94:95], v[208:209], 0, s[26:27]
	s_mov_b32 s40, m0
	s_mov_b32 m0, s61
	s_nop 0
	global_load_lds_dwordx4 v[94:95], off
	s_mov_b32 m0, s40
	v_add_f32_e32 v118, v214, v118
	s_waitcnt lgkmcnt(14)
	v_mfma_f32_32x32x16_bf16 v[18:33], v[166:169], v[210:213], v[18:33]
	v_exp_f32_e32 v98, v98
	v_exp_f32_e32 v99, v99
	v_exp_f32_e32 v100, v100
	v_exp_f32_e32 v101, v101
	s_waitcnt lgkmcnt(12)
	v_mfma_f32_32x32x16_bf16 v[34:49], v[166:169], v[114:117], v[34:49]
	v_exp_f32_e32 v102, v102
	v_exp_f32_e32 v103, v103
	v_exp_f32_e32 v104, v104
	v_exp_f32_e32 v105, v105
	ds_read_b128 v[128:131], v228
	ds_read_b128 v[132:135], v228 offset:512
	s_waitcnt lgkmcnt(12)
	v_mfma_f32_32x32x16_bf16 v[18:33], v[158:161], v[138:141], v[18:33]
	v_exp_f32_e32 v106, v106
	v_exp_f32_e32 v107, v107
	v_exp_f32_e32 v108, v108
	v_exp_f32_e32 v109, v109
	ds_read_b128 v[136:139], v228 offset:2048
	ds_read_b128 v[140:143], v228 offset:2560
	s_waitcnt lgkmcnt(12)
	v_mfma_f32_32x32x16_bf16 v[34:49], v[158:161], v[120:123], v[34:49]
	v_exp_f32_e32 v110, v110
	v_exp_f32_e32 v111, v111
	v_exp_f32_e32 v112, v112
	v_exp_f32_e32 v113, v113
	ds_read_b128 v[120:123], v228 offset:4096
	ds_read_b128 v[178:181], v228 offset:4608
	s_waitcnt lgkmcnt(12)
	v_mfma_f32_32x32x16_bf16 v[18:33], v[150:153], v[124:127], v[18:33]
	v_exp_f32_e32 v66, v66
	v_exp_f32_e32 v67, v67
	v_exp_f32_e32 v68, v68
	v_exp_f32_e32 v69, v69
	ds_read_b128 v[124:127], v228 offset:6144
	ds_read_b128 v[114:117], v228 offset:6656
	s_waitcnt lgkmcnt(12)
	v_mfma_f32_32x32x16_bf16 v[34:49], v[150:153], v[82:85], v[34:49]
	v_exp_f32_e32 v70, v70
	v_exp_f32_e32 v71, v71
	v_exp_f32_e32 v72, v72
	v_exp_f32_e32 v73, v73
	s_waitcnt lgkmcnt(10)
	v_mfma_f32_32x32x16_bf16 v[18:33], v[146:149], v[86:89], v[18:33]
	v_exp_f32_e32 v74, v74
	v_exp_f32_e32 v75, v75
	v_exp_f32_e32 v76, v76
	v_exp_f32_e32 v77, v77
	s_waitcnt lgkmcnt(8)
	v_mfma_f32_32x32x16_bf16 v[34:49], v[146:149], v[90:93], v[34:49]
	v_exp_f32_e32 v78, v78
	v_exp_f32_e32 v79, v79
	v_exp_f32_e32 v80, v80
	v_exp_f32_e32 v81, v81
	s_waitcnt vmcnt(0) lgkmcnt(0)
	s_barrier
	ds_read_b64_tr_b16 v[182:183], v227 offset:40960
	ds_read_b64_tr_b16 v[184:185], v227 offset:41472
	v_add_f32_e32 v82, v98, v99
	v_add_f32_e32 v82, v100, v82
	v_add_f32_e32 v82, v101, v82
	v_add_f32_e32 v82, v102, v82
	v_add_f32_e32 v119, v103, v82
	v_cvt_pk_bf16_f32 v166, v98, v99
	v_cvt_pk_bf16_f32 v167, v100, v101
	s_waitcnt lgkmcnt(9)
	v_mfma_f32_32x32x16_bf16 v[82:97], v[128:131], v[174:177], v[50:65]
	ds_read_b64_tr_b16 v[98:99], v227 offset:45056
	ds_read_b64_tr_b16 v[100:101], v227 offset:45568
	v_add_f32_e32 v119, v104, v119
	v_add_f32_e32 v119, v105, v119
	v_add_f32_e32 v119, v106, v119
	v_add_f32_e32 v119, v107, v119
	v_cvt_pk_bf16_f32 v168, v102, v103
	v_cvt_pk_bf16_f32 v169, v104, v105
	s_waitcnt lgkmcnt(10)
	v_mfma_f32_32x32x16_bf16 v[50:65], v[132:135], v[174:177], v[50:65]
	ds_read_b64_tr_b16 v[102:103], v227 offset:41984
	ds_read_b64_tr_b16 v[104:105], v227 offset:42496
	v_add_f32_e32 v119, v108, v119
	v_add_f32_e32 v119, v109, v119
	v_add_f32_e32 v119, v110, v119
	v_add_f32_e32 v119, v111, v119
	v_cvt_pk_bf16_f32 v158, v106, v107
	v_cvt_pk_bf16_f32 v159, v108, v109
	s_waitcnt lgkmcnt(11)
	v_mfma_f32_32x32x16_bf16 v[82:97], v[136:139], v[170:173], v[82:97]
	ds_read_b64_tr_b16 v[106:107], v227 offset:46080
	ds_read_b64_tr_b16 v[108:109], v227 offset:46592
	v_add_f32_e32 v119, v112, v119
	v_add_f32_e32 v119, v113, v119
	v_add_f32_e32 v119, v66, v119
	v_add_f32_e32 v119, v67, v119
	v_cvt_pk_bf16_f32 v160, v110, v111
	v_cvt_pk_bf16_f32 v161, v112, v113
	s_waitcnt lgkmcnt(12)
	v_mfma_f32_32x32x16_bf16 v[50:65], v[140:143], v[170:173], v[50:65]
	ds_read_b64_tr_b16 v[110:111], v227 offset:43008
	ds_read_b64_tr_b16 v[112:113], v227 offset:43520
	v_add_f32_e32 v119, v68, v119
	v_add_f32_e32 v119, v69, v119
	v_add_f32_e32 v119, v70, v119
	v_add_f32_e32 v119, v71, v119
	v_cvt_pk_bf16_f32 v150, v66, v67
	v_cvt_pk_bf16_f32 v151, v68, v69
	s_waitcnt lgkmcnt(13)
	v_mfma_f32_32x32x16_bf16 v[82:97], v[120:123], v[162:165], v[82:97]
	ds_read_b64_tr_b16 v[66:67], v227 offset:47104
	ds_read_b64_tr_b16 v[68:69], v227 offset:47616
	v_add_f32_e32 v119, v72, v119
	v_add_f32_e32 v119, v73, v119
	v_add_f32_e32 v119, v74, v119
	v_add_f32_e32 v119, v75, v119
	v_cvt_pk_bf16_f32 v152, v70, v71
	v_cvt_pk_bf16_f32 v153, v72, v73
	s_waitcnt lgkmcnt(14)
	v_mfma_f32_32x32x16_bf16 v[50:65], v[178:181], v[162:165], v[50:65]
	ds_read_b64_tr_b16 v[70:71], v227 offset:44032
	ds_read_b64_tr_b16 v[72:73], v227 offset:44544
	v_add_f32_e32 v119, v76, v119
	v_add_f32_e32 v119, v77, v119
	v_add_f32_e32 v119, v78, v119
	v_add_f32_e32 v119, v79, v119
	v_cvt_pk_bf16_f32 v146, v74, v75
	v_cvt_pk_bf16_f32 v147, v76, v77
	s_waitcnt lgkmcnt(14)
; #define SBAR() __builtin_amdgcn_sched_barrier(0)
;   #define RESC() do{ if(!FIXREF&&resc){ asm volatile("s_waitcnt lgkmcnt(0)":::"memory"); \
;       _Pragma("unroll") for(int d_=0;d_<2;++d_) _Pragma("unroll") for(int r=0;r<16;++r)o[d_][r]*=wsf[crow(r,hi)]; } }while(0)
;   #define PKW(P,B) cvtpk_s(P[B],P[B+1])
; __device__ __forceinline__ void pv(f32x16*o,int vb,bf16x8 pa0,bf16x8 pa1,bf16x8 pa2,bf16x8 pa3){
;   #pragma unroll
;   for(int d0=0;d0<2;++d0){s16x4 lo[4],hi[4];
;     #pragma unroll
;     for(int ks=0;ks<4;++ks){
;       asm volatile("ds_read_b64_tr_b16 %0,%1 offset:%c2":"=&v"(lo[ks]):"v"(vb),"i"(d0*4096+ks*1024):"memory");
;       asm volatile("ds_read_b64_tr_b16 %0,%1 offset:%c2":"=&v"(hi[ks]):"v"(vb),"i"(d0*4096+ks*1024+512):"memory");}
;     asm volatile("s_waitcnt lgkmcnt(0)":::"memory");SBAR();
;     ...
;     o[d0]=__builtin_amdgcn_mfma_f32_32x32x16_bf16(pa0,PK(0),o[d0],0,0,0);
;     o[d0]=__builtin_amdgcn_mfma_f32_32x32x16_bf16(pa1,PK(1),o[d0],0,0,0);
;     o[d0]=__builtin_amdgcn_mfma_f32_32x32x16_bf16(pa2,PK(2),o[d0],0,0,0);
;     o[d0]=__builtin_amdgcn_mfma_f32_32x32x16_bf16(pa3,PK(3),o[d0],0,0,0);
;     ...
;   }
; }
; template<int THRL,bool FIXREF,bool HALFK> __device__ __forceinline__ void attn_unit(float mref,long rowbase,int q0,const bf16*Qh,int PQ,const bf16*__restrict__ Kh_,int PK,const bf16*__restrict__ Vh_,int PV,bf16*Oh,int PO,const bf16*Gh,int PG,u32x4(&okeep)[4],int omode,float lam,float oml,const float ...
;     ...
;   STEP(pB0,pB1,pA0,pA1,NT-1,false,false,false); RESC();
;   { float sacc=pB0[0]+pB0[1]; _Pragma("unroll") for(int r=2;r<16;++r)sacc+=pB0[r]; _Pragma("unroll") for(int r=0;r<16;++r)sacc+=pB1[r]; l_reg+=sacc;
;     pw0=(u32x4){PKW(pB0,0),PKW(pB0,2),PKW(pB0,4),PKW(pB0,6)};pw1=(u32x4){PKW(pB0,8),PKW(pB0,10),PKW(pB0,12),PKW(pB0,14)};pw2=(u32x4){PKW(pB1,0),PKW(pB1,2),PKW(pB1,4),PKW(pB1,6)};pw3=(u32x4){PKW(pB1,8),PKW(pB1,10),PKW(pB1,12),PKW(pB1,14)};
;     SBAR(); pv(o,vb0+sl_cur,PAF(0),PAF(1),PAF(2),PAF(3)); }
;     ...
;   {auto rr=__builtin_amdgcn_permlane32_swap(__float_as_uint(l_reg),__float_as_uint(l_reg),false,false);l_reg=__uint_as_float(rr[0])+__uint_as_float(rr[1]);}
;   if(hi==0)wsf[32+r32]=l_reg;asm volatile("s_waitcnt lgkmcnt(0)":::"memory");
	v_mfma_f32_32x32x16_bf16 v[82:97], v[124:127], v[154:157], v[82:97]
	ds_read_b64_tr_b16 v[74:75], v227 offset:48128
	ds_read_b64_tr_b16 v[76:77], v227 offset:48640
	v_mfma_f32_32x32x16_bf16 v[50:65], v[114:117], v[154:157], v[50:65]
	v_add_f32_e32 v114, v80, v119
	v_add_f32_e32 v114, v81, v114
	v_add_f32_e32 v114, 0, v114
	v_cvt_pk_bf16_f32 v148, v78, v79
	v_cvt_pk_bf16_f32 v149, v80, v81
	s_waitcnt lgkmcnt(14)
	v_mfma_f32_32x32x16_bf16 v[18:33], v[166:169], v[182:185], v[18:33]
	s_nop 1
	v_exp_f32_e32 v82, v82
	v_exp_f32_e32 v83, v83
	v_exp_f32_e32 v84, v84
	v_exp_f32_e32 v85, v85
	s_waitcnt lgkmcnt(12)
	v_mfma_f32_32x32x16_bf16 v[34:49], v[166:169], v[98:101], v[34:49]
	v_exp_f32_e32 v86, v86
	v_exp_f32_e32 v87, v87
	v_exp_f32_e32 v88, v88
	v_exp_f32_e32 v89, v89
	s_waitcnt lgkmcnt(10)
	v_mfma_f32_32x32x16_bf16 v[18:33], v[158:161], v[102:105], v[18:33]
	v_exp_f32_e32 v90, v90
	v_exp_f32_e32 v91, v91
	v_exp_f32_e32 v92, v92
	v_exp_f32_e32 v93, v93
	s_waitcnt lgkmcnt(8)
	v_mfma_f32_32x32x16_bf16 v[34:49], v[158:161], v[106:109], v[34:49]
	v_exp_f32_e32 v94, v94
	v_exp_f32_e32 v95, v95
	v_exp_f32_e32 v96, v96
	v_exp_f32_e32 v97, v97
	s_waitcnt lgkmcnt(6)
	v_mfma_f32_32x32x16_bf16 v[18:33], v[150:153], v[110:113], v[18:33]
	v_exp_f32_e32 v50, v50
	v_exp_f32_e32 v51, v51
	v_exp_f32_e32 v52, v52
	v_exp_f32_e32 v53, v53
	s_waitcnt lgkmcnt(4)
	v_mfma_f32_32x32x16_bf16 v[34:49], v[150:153], v[66:69], v[34:49]
	v_exp_f32_e32 v54, v54
	v_exp_f32_e32 v55, v55
	v_exp_f32_e32 v56, v56
	v_exp_f32_e32 v57, v57
	s_waitcnt lgkmcnt(2)
	v_mfma_f32_32x32x16_bf16 v[18:33], v[146:149], v[70:73], v[18:33]
	v_exp_f32_e32 v58, v58
	v_exp_f32_e32 v59, v59
	v_exp_f32_e32 v60, v60
	v_exp_f32_e32 v61, v61
	s_waitcnt lgkmcnt(0)
	v_mfma_f32_32x32x16_bf16 v[34:49], v[146:149], v[74:77], v[34:49]
	v_exp_f32_e32 v62, v62
	v_exp_f32_e32 v63, v63
	v_exp_f32_e32 v64, v64
	v_exp_f32_e32 v65, v65
	v_add_f32_e32 v66, v82, v83
	v_add_f32_e32 v66, v84, v66
	v_add_f32_e32 v66, v85, v66
	v_add_f32_e32 v66, v86, v66
	v_add_f32_e32 v66, v87, v66
	v_add_f32_e32 v66, v88, v66
	v_add_f32_e32 v66, v89, v66
	v_add_f32_e32 v66, v90, v66
	v_add_f32_e32 v66, v91, v66
	v_add_f32_e32 v66, v92, v66
	v_add_f32_e32 v66, v93, v66
	v_add_f32_e32 v66, v94, v66
	v_add_f32_e32 v66, v95, v66
	v_add_f32_e32 v66, v96, v66
	v_add_f32_e32 v66, v97, v66
	v_add_f32_e32 v66, v50, v66
	v_add_f32_e32 v66, v51, v66
	v_add_f32_e32 v66, v52, v66
	v_add_f32_e32 v66, v53, v66
	v_add_f32_e32 v66, v54, v66
	v_add_f32_e32 v66, v55, v66
	v_add_f32_e32 v66, v56, v66
	v_add_f32_e32 v66, v57, v66
	v_add_f32_e32 v66, v58, v66
	v_add_f32_e32 v66, v59, v66
	v_add_f32_e32 v66, v60, v66
	v_add_f32_e32 v66, v61, v66
	v_add_f32_e32 v66, v62, v66
	v_add_f32_e32 v66, v63, v66
	v_add_f32_e32 v66, v64, v66
	v_add_f32_e32 v66, v65, v66
	v_add_f32_e32 v67, v118, v114
	v_add_f32_e32 v66, v67, v66
	v_cvt_pk_bf16_f32 v68, v82, v83
	v_cvt_pk_bf16_f32 v69, v84, v85
	v_cvt_pk_bf16_f32 v70, v86, v87
	v_cvt_pk_bf16_f32 v71, v88, v89
	v_cvt_pk_bf16_f32 v72, v90, v91
	v_cvt_pk_bf16_f32 v73, v92, v93
	v_cvt_pk_bf16_f32 v74, v94, v95
	v_cvt_pk_bf16_f32 v75, v96, v97
	v_cvt_pk_bf16_f32 v50, v50, v51
	v_cvt_pk_bf16_f32 v51, v52, v53
	v_cvt_pk_bf16_f32 v52, v54, v55
	v_cvt_pk_bf16_f32 v53, v56, v57
	v_cvt_pk_bf16_f32 v54, v58, v59
	v_cvt_pk_bf16_f32 v55, v60, v61
	v_cvt_pk_bf16_f32 v56, v62, v63
	v_cvt_pk_bf16_f32 v57, v64, v65
	ds_read_b64_tr_b16 v[58:59],v0 offset:0
	ds_read_b64_tr_b16 v[60:61],v0 offset:512
	ds_read_b64_tr_b16 v[62:63],v0 offset:1024
	ds_read_b64_tr_b16 v[64:65],v0 offset:1536
	ds_read_b64_tr_b16 v[76:77],v0 offset:2048
	ds_read_b64_tr_b16 v[78:79],v0 offset:2560
	ds_read_b64_tr_b16 v[80:81],v0 offset:3072
	ds_read_b64_tr_b16 v[82:83],v0 offset:3584
	s_waitcnt lgkmcnt(0)
	s_nop 0
	v_mfma_f32_32x32x16_bf16 v[18:33], v[68:71], v[58:61], v[18:33]
	ds_read_b64_tr_b16 v[58:59],v0 offset:4096
	ds_read_b64_tr_b16 v[60:61],v0 offset:4608
	v_mfma_f32_32x32x16_bf16 v[18:33], v[72:75], v[62:65], v[18:33]
	ds_read_b64_tr_b16 v[62:63],v0 offset:5120
	ds_read_b64_tr_b16 v[64:65],v0 offset:5632
	v_mfma_f32_32x32x16_bf16 v[18:33], v[50:53], v[76:79], v[18:33]
	ds_read_b64_tr_b16 v[76:77],v0 offset:6144
	ds_read_b64_tr_b16 v[78:79],v0 offset:6656
	v_mfma_f32_32x32x16_bf16 v[18:33], v[54:57], v[80:83], v[18:33]
	ds_read_b64_tr_b16 v[80:81],v0 offset:7168
	ds_read_b64_tr_b16 v[82:83],v0 offset:7680
	s_waitcnt lgkmcnt(0)
	v_mfma_f32_32x32x16_bf16 v[34:49], v[68:71], v[58:61], v[34:49]
	v_mov_b32_e32 v0, v66
	s_nop 1
	v_permlane32_swap_b32_e32 v66, v0
	v_cmp_gt_u32_e32 vcc, 32, v205
	v_mfma_f32_32x32x16_bf16 v[34:49], v[72:75], v[62:65], v[34:49]
	v_mfma_f32_32x32x16_bf16 v[34:49], v[50:53], v[76:79], v[34:49]
	v_mfma_f32_32x32x16_bf16 v[34:49], v[54:57], v[80:83], v[34:49]
	s_and_saveexec_b64 s[40:41], vcc
	s_cbranch_execz .LBB0_449
	v_lshl_add_u32 v50, v216, 2, s42
	v_add_f32_e32 v0, v66, v0
	ds_write_b32 v50, v0 offset:49280
	s_branch .LBB0_449

;   #define CMASK(P0,P1,t) do{}while(0)
;   #define CMASK(P0,P1,t) do{}while(0)
; template<int THRL,bool FIXREF,bool HALFK> __device__ __forceinline__ void attn_unit(float mref,long rowbase,int q0,const bf16*Qh,int PQ,const bf16*__restrict__ Kh_,int PK,const bf16*__restrict__ Vh_,int PV,bf16*Oh,int PO,const bf16*Gh,int PG,u32x4(&okeep)[4],int omode,float lam,float oml,const float ...
;   const int tid=fresh_tid(),lane=tid&63,r32=lane&31,hi=lane>>5; const int wid=__builtin_amdgcn_readfirstlane(tid>>6);
;   const bf16*Qw=Qh+(rowbase+q0+wid*QBLK)*PQ;
;   const bf16*Kh=Kh_+rowbase*PK,*Vh=Vh_+rowbase*PV;
;   const unsigned lds0=(unsigned)(uintptr_t)shm;
;   float*wsf=(float*)(shm+LDS_WS)+wid*64;
;   const bf16*ksrc=Kh+(long)lane*PK+wid*8;
;   const bf16*vsrc=Vh+(long)(16*(wid&3)+(lane>>2))*PV+(wid>>2)*32+(lane&3)*8;
;   const unsigned kdst=lds0+LDS_K+wid*1024, vdst=lds0+LDS_V+wid*1024;
;     ...
;   const int vb0=(int)(lds0+LDS_V)+((lane>>4)&1)*32+(lane&3)*8+(4*hi+((lane&15)>>2))*64;
;   const char*Kbase=shm+LDS_K; bf16x8 kf[8];
;   const lds_cptr shm3=(lds_cptr)shm; const lds_cptr kp0=shm3+LDS_K+hi*1024+r32*16; const lds_cptr vp0=shm3+LDS_V+((lane>>4)&1)*32+(lane&3)*8+(4*hi+((lane&15)>>2))*64;
;   constexpr int NT=SEQ/KVBLK;
;   if(Gh){ const bf16*Gw=Gh+(rowbase+q0+wid*QBLK)*PG;
;     #pragma unroll
;     for(int i=0;i<4;++i) glds16(Gw+(long)(i*8+(lane>>3))*PG+(lane&7)*8,(unsigned)__builtin_amdgcn_readfirstlane(lds0+LDS_GST+wid*4096+i*1024)); }
;   DMA_K(0,0);DMA_V(0,0);DMA_K(1,SLOTB);
;   bf16x8 qr[4];
;   #pragma unroll
;   for(int d0=0;d0<4;++d0)qr[d0]=*reinterpret_cast<const bf16x8*>(&Qw[(long)r32*PQ+d0*16+hi*8]);
;   float mhat=0.f,l_reg=0.f;f32x16 o[2];o[0]=f32x16{};o[1]=f32x16{};f32x16 negm=f32x16{};
;   if constexpr(FIXREF){ mhat=mref; _Pragma("unroll") for(int r=0;r<16;++r)negm[r]=-mref; }
;   asm volatile("":"+v"(negm));
;     ...
;   bool resc=false;
;     ...
;   f32x16 pA0,pA1,pB0,pB1;
;   int sl_prev=0,sl_cur=0,sl_next=SLOTB;
;     ...
;   DMA_K(2,2*SLOTB);
;   WAIT_BAR(3);
;   qkt<HALFK?2:4>(pA0,pA1,Kbase,qr,negm,r32,hi);asm volatile("s_nop 15\n\ts_nop 7":"+v"(pA0),"+v"(pA1));CMASK(pA0,pA1,0);
;   START(pA0,pA1);
;   _Pragma("unroll") for(int r=0;r<16;++r)pA1[r]=__builtin_amdgcn_exp2f(pA1[r]);
;   WAIT_BAR(0);
;   DMA_K(3,0);DMA_V(1,SLOTB);
;   ROT();
;   if constexpr(HALFK){ kload2(kf,kp0+sl_cur,0); kload2(kf,kp0+sl_cur,1); } else kload8(kf,kp0+sl_cur);
;   WAIT_BAR(2);
.LBB0_460:
	s_or_b32 s20, s88, s68
	s_xor_b64 s[42:43], s[42:43], -1
	s_xor_b64 s[40:41], s[48:49], -1
	s_lshl_b64 s[48:49], s[20:21], 1
	s_add_u32 s20, s2, s48
	s_addc_u32 s80, s3, s49
	s_lshl_b64 s[50:51], s[46:47], 9
	s_add_u32 s84, s20, s50
	s_addc_u32 s85, s80, s51
	s_add_u32 s48, s71, s48
	s_addc_u32 s49, s73, s49
	v_lshlrev_b32_e32 v0, 9, v209
	v_lshl_add_u64 v[18:19], s[48:49], 0, v[0:1]
	s_lshl_b32 s48, s79, 3
	s_ashr_i32 s49, s48, 31
	s_lshl_b64 s[48:49], s[48:49], 1
	v_lshl_add_u64 v[174:175], v[18:19], 0, s[48:49]
	s_lshl_b32 s20, s79, 4
	v_lshrrev_b32_e32 v18, 2, v209
	v_and_or_b32 v18, s20, 48, v18
	s_ashr_i32 s20, s83, 3
	s_and_b32 s50, s20, 0xffffffe0
	s_ashr_i32 s51, s50, 31
	v_mul_u32_u24_e32 v18, 0xf00, v18
	s_lshl_b64 s[50:51], s[50:51], 1
	s_lshl_b32 s82, s79, 10
	v_lshlrev_b32_e32 v104, 1, v18
	v_mov_b32_e32 v105, v1
	s_cmp_lg_u32 0, -1
	v_lshl_add_u64 v[18:19], s[16:17], 0, v[104:105]
	v_and_b32_e32 v215, 24, v211
	s_cselect_b32 s20, 0, 0
	v_lshl_add_u64 v[18:19], v[18:19], 0, s[50:51]
	v_lshlrev_b32_e32 v20, 1, v215
	v_mov_b32_e32 v21, v1
	s_add_i32 s81, s82, s20
	s_mov_b32 s20, m0
	s_mov_b32 m0, s81
	s_nop 0
	global_load_lds_dwordx4 v[174:175], off
	s_mov_b32 m0, s20
	v_and_b32_e32 v171, 31, v102
	v_lshl_add_u64 v[172:173], v[18:19], 0, v[20:21]
	s_add_i32 s80, s81, 0x6000
	s_mov_b32 s20, m0
	s_mov_b32 m0, s80
	s_nop 0
	global_load_lds_dwordx4 v[172:173], off
	s_mov_b32 m0, s20
	v_lshl_add_u64 v[18:19], v[174:175], 0, s[10:11]
	v_lshrrev_b32_e32 v212, 5, v209
	s_add_i32 s20, s81, 0x2000
	s_mov_b32 s86, m0
	s_mov_b32 m0, s20
	s_nop 0
	global_load_lds_dwordx4 v[18:19], off
	s_mov_b32 m0, s86
	v_lshlrev_b32_e32 v18, 9, v171
	v_lshl_or_b32 v18, v212, 4, v18
	global_load_dwordx4 v[166:169], v18, s[84:85]
	global_load_dwordx4 v[162:165], v18, s[84:85] offset:32
	v_mov_b64_e32 v[64:65], v[16:17]
	v_mov_b64_e32 v[62:63], v[14:15]
	v_mov_b64_e32 v[60:61], v[12:13]
	v_mov_b64_e32 v[58:59], v[10:11]
	v_mov_b64_e32 v[56:57], v[8:9]
	v_mov_b64_e32 v[54:55], v[6:7]
	v_mov_b64_e32 v[52:53], v[4:5]
	v_mov_b64_e32 v[50:51], v[2:3]
	v_lshlrev_b32_e32 v18, 10, v212
	v_lshlrev_b32_e32 v19, 4, v171
	v_add3_u32 v214, 0, v18, v19
	v_lshl_add_u64 v[18:19], v[174:175], 0, s[92:93]
	s_add_i32 s20, s81, 0x4000
	s_mov_b32 s84, m0
	s_mov_b32 m0, s20
	s_nop 0
	global_load_lds_dwordx4 v[18:19], off
	s_mov_b32 m0, s84
	s_waitcnt vmcnt(3) lgkmcnt(0)
	s_barrier
	ds_read_b128 v[18:21], v214
	ds_read_b128 v[66:69], v214 offset:512
	ds_read_b128 v[70:73], v214 offset:2560
	ds_read_b128 v[74:77], v214 offset:2048
	v_lshl_add_u64 v[98:99], v[174:175], 0, s[36:37]
	v_lshl_add_u64 v[100:101], v[172:173], 0, s[22:23]
	s_add_i32 s20, s81, 0x8000
	v_mov_b32_e32 v227, 0
	s_mov_b32 s84, -1
	s_mov_b32 s87, 0
	s_movk_i32 s86, 0x2000
	s_movk_i32 s85, 0x4000
	s_waitcnt vmcnt(1) lgkmcnt(3)
	v_mfma_f32_32x32x16_bf16 v[34:49], v[18:21], v[166:169], v[50:65]
	s_waitcnt lgkmcnt(2)
	v_mfma_f32_32x32x16_bf16 v[18:33], v[66:69], v[166:169], v[50:65]
	v_lshlrev_b32_e32 v66, 1, v102
	v_lshlrev_b32_e32 v67, 4, v102
	v_and_b32_e32 v216, 32, v66
	v_and_b32_e32 v66, 0xc0, v67
	v_lshl_or_b32 v217, v212, 8, v66
	v_add_u32_e32 v66, 0, v216
	v_add3_u32 v213, v66, v215, v217
	s_waitcnt vmcnt(0) lgkmcnt(0)
	v_mfma_f32_32x32x16_bf16 v[34:49], v[74:77], v[162:165], v[34:49]
	v_mfma_f32_32x32x16_bf16 v[18:33], v[70:73], v[162:165], v[18:33]
	s_nop 15
	s_nop 7
	s_waitcnt vmcnt(0) lgkmcnt(0)
	s_barrier
	s_mov_b32 s89, m0
	s_mov_b32 m0, s81
	s_nop 0
	global_load_lds_dwordx4 v[98:99], off
	s_mov_b32 m0, s89
	s_nop 0
	s_mov_b32 s89, m0
	s_mov_b32 m0, s20
	s_nop 0
	global_load_lds_dwordx4 v[100:101], off
	s_mov_b32 m0, s89
	s_nop 10
	v_exp_f32_e32 v66, v18
	ds_read_b128 v[98:101], v214 offset:8192
	ds_read_b128 v[134:137], v214 offset:8704
	ds_read_b128 v[138:141], v214 offset:10240
	ds_read_b128 v[130:133], v214 offset:10752
	v_and_b32_e32 v18, 3, v102
	s_add_i32 s20, s67, s88
	v_exp_f32_e32 v67, v19
	v_lshl_or_b32 v18, v18, 4, s50
	v_mov_b32_e32 v19, s51
	s_lshl_b64 s[50:51], s[20:21], 1
	s_add_u32 s20, s77, s50
	v_exp_f32_e32 v82, v34
	v_exp_f32_e32 v83, v35
	v_exp_f32_e32 v84, v36
	v_exp_f32_e32 v85, v37
	v_exp_f32_e32 v86, v38
	v_exp_f32_e32 v87, v39
	v_exp_f32_e32 v88, v40
	v_exp_f32_e32 v89, v41
	v_exp_f32_e32 v90, v42
	v_exp_f32_e32 v91, v43
	v_exp_f32_e32 v92, v44
	v_exp_f32_e32 v93, v45
	v_exp_f32_e32 v94, v46
	v_exp_f32_e32 v95, v47
	v_exp_f32_e32 v96, v48
	v_exp_f32_e32 v97, v49
	v_exp_f32_e32 v68, v20
	v_exp_f32_e32 v69, v21
	v_exp_f32_e32 v70, v22
	v_exp_f32_e32 v71, v23
	v_exp_f32_e32 v72, v24
	v_exp_f32_e32 v73, v25
	v_exp_f32_e32 v74, v26
	v_exp_f32_e32 v75, v27
	v_exp_f32_e32 v76, v28
	v_exp_f32_e32 v77, v29
	v_exp_f32_e32 v78, v30
	v_exp_f32_e32 v79, v31
	v_exp_f32_e32 v80, v32
	v_exp_f32_e32 v81, v33
	s_addc_u32 s50, s78, s51
	s_waitcnt vmcnt(2) lgkmcnt(0)
	s_barrier
	s_add_u32 s48, s20, s48
	v_lshl_add_u64 v[18:19], v[18:19], 0, v[104:105]
	s_addc_u32 s49, s50, s49
	v_lshl_add_u64 v[142:143], s[34:35], 0, v[18:19]
	v_lshl_add_u64 v[144:145], s[48:49], 0, v[0:1]
	v_mov_b32_e32 v18, 0
	v_mov_b32_e32 v19, v227
	v_mov_b32_e32 v20, v227
	v_mov_b32_e32 v21, v227
	v_mov_b32_e32 v22, v227
	v_mov_b32_e32 v23, v227
	v_mov_b32_e32 v24, v227
	v_mov_b32_e32 v25, v227
	v_mov_b32_e32 v26, v227
	v_mov_b32_e32 v27, v227
	v_mov_b32_e32 v28, v227
	v_mov_b32_e32 v29, v227
	v_mov_b32_e32 v30, v227
	v_mov_b32_e32 v31, v227
	v_mov_b32_e32 v32, v227
	v_mov_b32_e32 v33, v227
	v_mov_b32_e32 v34, 0
	v_mov_b32_e32 v35, v227
	v_mov_b32_e32 v36, v227
	v_mov_b32_e32 v37, v227
	v_mov_b32_e32 v38, v227
	v_mov_b32_e32 v39, v227
	v_mov_b32_e32 v40, v227
	v_mov_b32_e32 v41, v227
	v_mov_b32_e32 v42, v227
	v_mov_b32_e32 v43, v227
	v_mov_b32_e32 v44, v227
	v_mov_b32_e32 v45, v227
	v_mov_b32_e32 v46, v227
	v_mov_b32_e32 v47, v227
	v_mov_b32_e32 v48, v227
	v_mov_b32_e32 v49, v227
	v_add_u32_e32 v0, s87, v213
.LBB0_461:
	ds_read_b64_tr_b16 v[228:229], v0 offset:24576
	ds_read_b64_tr_b16 v[230:231], v0 offset:25088
	v_add_f32_e32 v102, v82, v83
	v_add_f32_e32 v102, v84, v102
	v_add_f32_e32 v102, v85, v102
	v_add_f32_e32 v102, v86, v102
	v_add_f32_e32 v102, v87, v102
	v_cvt_pk_bf16_f32 v158, v82, v83
	v_cvt_pk_bf16_f32 v159, v84, v85
	s_waitcnt lgkmcnt(5)
	v_mfma_f32_32x32x16_bf16 v[114:129], v[98:101], v[166:169], v[50:65]
	ds_read_b64_tr_b16 v[82:83], v0 offset:28672
	ds_read_b64_tr_b16 v[84:85], v0 offset:29184
	v_add_f32_e32 v98, v88, v102
	v_add_f32_e32 v98, v89, v98
	v_add_f32_e32 v98, v90, v98
	v_add_f32_e32 v146, v91, v98
	s_waitcnt lgkmcnt(6)
	v_mfma_f32_32x32x16_bf16 v[98:113], v[134:137], v[166:169], v[50:65]
	v_cvt_pk_bf16_f32 v160, v86, v87
	v_cvt_pk_bf16_f32 v161, v88, v89
	ds_read_b64_tr_b16 v[86:87], v0 offset:25600
	ds_read_b64_tr_b16 v[88:89], v0 offset:26112
	v_add_f32_e32 v134, v92, v146
	v_add_f32_e32 v134, v93, v134
	v_add_f32_e32 v134, v94, v134
	v_add_f32_e32 v134, v95, v134
	v_cvt_pk_bf16_f32 v154, v90, v91
	v_cvt_pk_bf16_f32 v155, v92, v93
	s_waitcnt lgkmcnt(7)
	v_mfma_f32_32x32x16_bf16 v[114:129], v[138:141], v[162:165], v[114:129]
	ds_read_b64_tr_b16 v[90:91], v0 offset:29696
	ds_read_b64_tr_b16 v[92:93], v0 offset:30208
	s_waitcnt lgkmcnt(8)
	v_mfma_f32_32x32x16_bf16 v[98:113], v[130:133], v[162:165], v[98:113]
	v_add_f32_e32 v130, v96, v134
	v_add_f32_e32 v130, v97, v130
	v_add_f32_e32 v130, v66, v130
	v_add_f32_e32 v130, v67, v130
	v_cvt_pk_bf16_f32 v156, v94, v95
	v_cvt_pk_bf16_f32 v157, v96, v97
	ds_read_b64_tr_b16 v[94:95], v0 offset:26624
	ds_read_b64_tr_b16 v[96:97], v0 offset:27136
	v_add_f32_e32 v130, v68, v130
	v_add_f32_e32 v130, v69, v130
	v_add_f32_e32 v130, v70, v130
	v_add_f32_e32 v130, v71, v130
	v_cvt_pk_bf16_f32 v150, v66, v67
	v_cvt_pk_bf16_f32 v151, v68, v69
	ds_read_b64_tr_b16 v[66:67], v0 offset:30720
	ds_read_b64_tr_b16 v[68:69], v0 offset:31232
	v_add_f32_e32 v130, v72, v130
	v_add_f32_e32 v130, v73, v130
	v_add_f32_e32 v130, v74, v130
	v_add_f32_e32 v130, v75, v130
	v_cvt_pk_bf16_f32 v152, v70, v71
	v_cvt_pk_bf16_f32 v153, v72, v73
	ds_read_b64_tr_b16 v[70:71], v0 offset:27648
	ds_read_b64_tr_b16 v[72:73], v0 offset:28160
	v_add_f32_e32 v130, v76, v130
	v_add_f32_e32 v130, v77, v130
	v_add_f32_e32 v130, v78, v130
	v_add_f32_e32 v130, v79, v130
	v_cvt_pk_bf16_f32 v146, v74, v75
	v_cvt_pk_bf16_f32 v147, v76, v77
	ds_read_b64_tr_b16 v[74:75], v0 offset:31744
	ds_read_b64_tr_b16 v[76:77], v0 offset:32256
	v_add_f32_e32 v0, v80, v130
	v_add_f32_e32 v0, v81, v0
	v_cvt_pk_bf16_f32 v148, v78, v79
	v_cvt_pk_bf16_f32 v149, v80, v81
	v_lshl_add_u64 v[78:79], v[144:145], 0, s[36:37]
	s_add_i32 s20, s86, s81
	s_mov_b32 s48, m0
	s_mov_b32 m0, s20
	s_nop 0
	global_load_lds_dwordx4 v[78:79], off
	s_mov_b32 m0, s48
	v_lshl_add_u64 v[78:79], v[142:143], 0, s[22:23]
	s_add_i32 s20, s85, s80
	s_mov_b32 s48, m0
	s_mov_b32 m0, s20
	s_nop 0
	global_load_lds_dwordx4 v[78:79], off
	s_mov_b32 m0, s48
	v_add_f32_e32 v0, v227, v0
	s_waitcnt lgkmcnt(14)
	v_mfma_f32_32x32x16_bf16 v[18:33], v[158:161], v[228:231], v[18:33]
	v_exp_f32_e32 v114, v114
	v_exp_f32_e32 v115, v115
	v_exp_f32_e32 v116, v116
	v_exp_f32_e32 v117, v117
	s_waitcnt lgkmcnt(12)
	v_mfma_f32_32x32x16_bf16 v[34:49], v[158:161], v[82:85], v[34:49]
	v_exp_f32_e32 v118, v118
	v_exp_f32_e32 v119, v119
	v_exp_f32_e32 v120, v120
	v_exp_f32_e32 v121, v121
	v_add_u32_e32 v82, s85, v214
	ds_read_b128 v[78:81], v82
	ds_read_b128 v[130:133], v82 offset:512
	s_waitcnt lgkmcnt(12)
	v_mfma_f32_32x32x16_bf16 v[18:33], v[154:157], v[86:89], v[18:33]
	v_exp_f32_e32 v122, v122
	v_exp_f32_e32 v123, v123
	v_exp_f32_e32 v124, v124
	v_exp_f32_e32 v125, v125
	ds_read_b128 v[134:137], v82 offset:2048
	ds_read_b128 v[138:141], v82 offset:2560
	s_waitcnt lgkmcnt(12)
	v_mfma_f32_32x32x16_bf16 v[34:49], v[154:157], v[90:93], v[34:49]
	v_exp_f32_e32 v126, v126
	v_exp_f32_e32 v127, v127
	v_exp_f32_e32 v128, v128
	v_exp_f32_e32 v129, v129
	s_waitcnt lgkmcnt(10)
	v_mfma_f32_32x32x16_bf16 v[18:33], v[150:153], v[94:97], v[18:33]
	v_exp_f32_e32 v98, v98
	v_exp_f32_e32 v99, v99
	v_exp_f32_e32 v100, v100
	v_exp_f32_e32 v101, v101
	s_waitcnt lgkmcnt(8)
	v_mfma_f32_32x32x16_bf16 v[34:49], v[150:153], v[66:69], v[34:49]
	v_exp_f32_e32 v102, v102
	v_exp_f32_e32 v103, v103
	v_exp_f32_e32 v104, v104
	v_exp_f32_e32 v105, v105
	s_waitcnt lgkmcnt(6)
	v_mfma_f32_32x32x16_bf16 v[18:33], v[146:149], v[70:73], v[18:33]
	v_exp_f32_e32 v106, v106
	v_exp_f32_e32 v107, v107
	v_exp_f32_e32 v108, v108
	v_exp_f32_e32 v109, v109
	s_waitcnt lgkmcnt(4)
	v_mfma_f32_32x32x16_bf16 v[34:49], v[146:149], v[74:77], v[34:49]
	v_exp_f32_e32 v110, v110
	v_exp_f32_e32 v111, v111
	v_exp_f32_e32 v112, v112
	v_exp_f32_e32 v113, v113
	s_add_i32 s20, s85, 0x2000
	s_cmpk_lg_i32 s85, 0x4000
	s_cselect_b32 s20, s20, 0
	v_add_u32_e32 v227, s86, v213
	s_waitcnt vmcnt(2) lgkmcnt(0)
	s_barrier
; #define WAIT_BAR(N) asm volatile("s_waitcnt vmcnt(" #N ") lgkmcnt(0)\n\ts_barrier":::"memory")
;   #define RESC() do{ if(!FIXREF&&resc){ asm volatile("s_waitcnt lgkmcnt(0)":::"memory"); \
;       _Pragma("unroll") for(int d_=0;d_<2;++d_) _Pragma("unroll") for(int r=0;r<16;++r)o[d_][r]*=wsf[crow(r,hi)]; } }while(0)
;   #define ROT() do{sl_prev=sl_cur;sl_cur=sl_next;sl_next=(sl_next==(NSLOT-1)*SLOTB)?0:sl_next+SLOTB;}while(0)
; template<int THRL,bool FIXREF,bool HALFK> __device__ __forceinline__ void attn_unit(float mref,long rowbase,int q0,const bf16*Qh,int PQ,const bf16*__restrict__ Kh_,int PK,const bf16*__restrict__ Vh_,int PV,bf16*Oh,int PO,const bf16*Gh,int PG,u32x4(&okeep)[4],int omode,float lam,float oml,const float ...
;     ...
;   int t=1;
;     ...
;   for(;t+5<NT;t+=2){
;     STEP(pB0,pB1,pA0,pA1,t,true,true,true);     WAIT_BAR(2); RESC(); ROT();
;     STEP(pA0,pA1,pB0,pB1,t+1,true,true,true);   WAIT_BAR(2); RESC(); ROT();
	ds_read_b64_tr_b16 v[228:229], v227 offset:24576
	ds_read_b64_tr_b16 v[230:231], v227 offset:25088
	s_waitcnt lgkmcnt(5)
	v_mfma_f32_32x32x16_bf16 v[82:97], v[78:81], v[166:169], v[50:65]
	v_add_f32_e32 v66, v114, v115
	v_add_f32_e32 v66, v116, v66
	v_add_f32_e32 v66, v117, v66
	v_add_f32_e32 v66, v118, v66
	v_add_f32_e32 v66, v119, v66
	v_cvt_pk_bf16_f32 v158, v114, v115
	v_cvt_pk_bf16_f32 v159, v116, v117
	ds_read_b64_tr_b16 v[114:115], v227 offset:28672
	ds_read_b64_tr_b16 v[116:117], v227 offset:29184
	v_add_f32_e32 v66, v120, v66
	v_add_f32_e32 v66, v121, v66
	v_add_f32_e32 v66, v122, v66
	v_add_f32_e32 v146, v123, v66
	s_waitcnt lgkmcnt(6)
	v_mfma_f32_32x32x16_bf16 v[66:81], v[130:133], v[166:169], v[50:65]
	v_cvt_pk_bf16_f32 v160, v118, v119
	v_cvt_pk_bf16_f32 v161, v120, v121
	ds_read_b64_tr_b16 v[118:119], v227 offset:25600
	ds_read_b64_tr_b16 v[120:121], v227 offset:26112
	s_waitcnt lgkmcnt(7)
	v_mfma_f32_32x32x16_bf16 v[82:97], v[134:137], v[162:165], v[82:97]
	v_add_f32_e32 v130, v124, v146
	v_add_f32_e32 v130, v125, v130
	v_add_f32_e32 v130, v126, v130
	v_add_f32_e32 v130, v127, v130
	v_cvt_pk_bf16_f32 v154, v122, v123
	v_cvt_pk_bf16_f32 v155, v124, v125
	ds_read_b64_tr_b16 v[122:123], v227 offset:29696
	ds_read_b64_tr_b16 v[124:125], v227 offset:30208
	s_waitcnt lgkmcnt(8)
	v_mfma_f32_32x32x16_bf16 v[66:81], v[138:141], v[162:165], v[66:81]
	v_add_f32_e32 v130, v128, v130
	v_add_f32_e32 v130, v129, v130
	v_add_f32_e32 v130, v98, v130
	v_add_f32_e32 v130, v99, v130
	v_cvt_pk_bf16_f32 v156, v126, v127
	v_cvt_pk_bf16_f32 v157, v128, v129
	ds_read_b64_tr_b16 v[126:127], v227 offset:26624
	ds_read_b64_tr_b16 v[128:129], v227 offset:27136
	v_add_f32_e32 v130, v100, v130
	v_add_f32_e32 v130, v101, v130
	v_add_f32_e32 v130, v102, v130
	v_add_f32_e32 v130, v103, v130
	v_cvt_pk_bf16_f32 v150, v98, v99
	v_cvt_pk_bf16_f32 v151, v100, v101
	ds_read_b64_tr_b16 v[232:233], v227 offset:30720
	ds_read_b64_tr_b16 v[234:235], v227 offset:31232
	v_add_f32_e32 v98, v104, v130
	v_add_f32_e32 v98, v105, v98
	v_add_f32_e32 v98, v106, v98
	v_add_f32_e32 v98, v107, v98
	v_cvt_pk_bf16_f32 v152, v102, v103
	v_cvt_pk_bf16_f32 v153, v104, v105
	ds_read_b64_tr_b16 v[102:103], v227 offset:27648
	ds_read_b64_tr_b16 v[104:105], v227 offset:28160
	v_add_f32_e32 v98, v108, v98
	v_add_f32_e32 v98, v109, v98
	v_add_f32_e32 v98, v110, v98
	v_add_f32_e32 v98, v111, v98
	v_cvt_pk_bf16_f32 v146, v106, v107
	v_cvt_pk_bf16_f32 v147, v108, v109
	ds_read_b64_tr_b16 v[106:107], v227 offset:31744
	ds_read_b64_tr_b16 v[108:109], v227 offset:32256
	v_add_f32_e32 v98, v112, v98
	v_add_f32_e32 v98, v113, v98
	v_cvt_pk_bf16_f32 v148, v110, v111
	v_cvt_pk_bf16_f32 v149, v112, v113
	s_nop 0
	v_add_f32_e32 v227, v0, v98
	v_lshl_add_u64 v[98:99], v[144:145], 0, s[96:97]
	s_add_i32 s48, s85, s81
	s_mov_b32 s49, m0
	s_mov_b32 m0, s48
	s_nop 0
	global_load_lds_dwordx4 v[98:99], off
	s_mov_b32 m0, s49
	v_lshl_add_u64 v[142:143], v[142:143], 0, s[4:5]
	s_add_i32 s48, s20, s80
	s_mov_b32 s49, m0
	s_mov_b32 m0, s48
	s_nop 0
	global_load_lds_dwordx4 v[142:143], off
	s_mov_b32 m0, s49
	s_waitcnt lgkmcnt(14)
	v_mfma_f32_32x32x16_bf16 v[18:33], v[158:161], v[228:231], v[18:33]
	v_exp_f32_e32 v82, v82
	v_exp_f32_e32 v83, v83
	v_exp_f32_e32 v84, v84
	v_exp_f32_e32 v85, v85
	s_waitcnt lgkmcnt(12)
	v_mfma_f32_32x32x16_bf16 v[34:49], v[158:161], v[114:117], v[34:49]
	v_exp_f32_e32 v86, v86
	v_exp_f32_e32 v87, v87
	v_exp_f32_e32 v88, v88
	v_exp_f32_e32 v89, v89
	v_add_u32_e32 v0, s20, v214
	ds_read_b128 v[98:101], v0
	ds_read_b128 v[134:137], v0 offset:512
	s_waitcnt lgkmcnt(12)
	v_mfma_f32_32x32x16_bf16 v[18:33], v[154:157], v[118:121], v[18:33]
	v_exp_f32_e32 v90, v90
	v_exp_f32_e32 v91, v91
	v_exp_f32_e32 v92, v92
	v_exp_f32_e32 v93, v93
	ds_read_b128 v[138:141], v0 offset:2048
	ds_read_b128 v[130:133], v0 offset:2560
	s_waitcnt lgkmcnt(12)
	v_mfma_f32_32x32x16_bf16 v[34:49], v[154:157], v[122:125], v[34:49]
	v_exp_f32_e32 v94, v94
	v_exp_f32_e32 v95, v95
	v_exp_f32_e32 v96, v96
	v_exp_f32_e32 v97, v97
	s_waitcnt lgkmcnt(10)
	v_mfma_f32_32x32x16_bf16 v[18:33], v[150:153], v[126:129], v[18:33]
	v_exp_f32_e32 v66, v66
	v_exp_f32_e32 v67, v67
	v_exp_f32_e32 v68, v68
	v_exp_f32_e32 v69, v69
	s_waitcnt lgkmcnt(8)
	v_mfma_f32_32x32x16_bf16 v[34:49], v[150:153], v[232:235], v[34:49]
	v_exp_f32_e32 v70, v70
	v_exp_f32_e32 v71, v71
	v_exp_f32_e32 v72, v72
	v_exp_f32_e32 v73, v73
	s_waitcnt lgkmcnt(6)
	v_mfma_f32_32x32x16_bf16 v[18:33], v[146:149], v[102:105], v[18:33]
	v_exp_f32_e32 v74, v74
	v_exp_f32_e32 v75, v75
	v_exp_f32_e32 v76, v76
	v_exp_f32_e32 v77, v77
	s_waitcnt lgkmcnt(4)
	v_mfma_f32_32x32x16_bf16 v[34:49], v[146:149], v[106:109], v[34:49]
	v_exp_f32_e32 v78, v78
	v_exp_f32_e32 v79, v79
	v_exp_f32_e32 v80, v80
	v_exp_f32_e32 v81, v81
	s_add_i32 s48, s20, 0x2000
	s_cmpk_lg_i32 s20, 0x4000
	s_mov_b32 s87, s85
	v_add_u32_e32 v0, s87, v213
	s_cselect_b32 s85, s48, 0
	s_add_i32 s84, s84, 2
	v_lshl_add_u64 v[144:145], v[144:145], 0, s[92:93]
	s_mov_b32 s86, s20
	s_cmp_gt_u32 s84, 56
	s_waitcnt vmcnt(2) lgkmcnt(0)
	s_barrier
	s_cbranch_scc0 .LBB0_461
;   #define RESC() do{ if(!FIXREF&&resc){ asm volatile("s_waitcnt lgkmcnt(0)":::"memory"); \
;       _Pragma("unroll") for(int d_=0;d_<2;++d_) _Pragma("unroll") for(int r=0;r<16;++r)o[d_][r]*=wsf[crow(r,hi)]; } }while(0)
;   #define ROT() do{sl_prev=sl_cur;sl_cur=sl_next;sl_next=(sl_next==(NSLOT-1)*SLOTB)?0:sl_next+SLOTB;}while(0)
;   #define ENDW(tt) do{ if((tt)+3<NT){WAIT_BAR(2);} else if((tt)+2<NT){WAIT_BAR(1);} else {WAIT_BAR(0);} }while(0)
; template<int THRL,bool FIXREF,bool HALFK> __device__ __forceinline__ void attn_unit(float mref,long rowbase,int q0,const bf16*Qh,int PQ,const bf16*__restrict__ Kh_,int PK,const bf16*__restrict__ Vh_,int PV,bf16*Oh,int PO,const bf16*Gh,int PG,u32x4(&okeep)[4],int omode,float lam,float oml,const float ...
;     ...
;   for(;t+1<NT;t+=2){
;     STEP(pB0,pB1,pA0,pA1,t,(t+3<NT),(t+1<NT),(t+1<NT));       ENDW(t);   RESC(); ROT();
	s_and_b32 s20, s83, 0x3fffffc0
	s_lshl_b32 s20, s20, 2
	s_add_i32 s20, s20, 0
	s_cmp_lg_u32 0, -1
	s_cselect_b32 s50, 0, 0
	s_add_i32 s48, s50, 0x6000
	v_add_u32_e32 v0, s48, v216
	v_add3_u32 v0, v0, v215, v217
	ds_read_b64_tr_b16 v[142:143], v213 offset:32768
	ds_read_b64_tr_b16 v[144:145], v213 offset:33280
	v_add_f32_e32 v102, v82, v83
	v_add_f32_e32 v102, v84, v102
	v_add_f32_e32 v102, v85, v102
	v_add_f32_e32 v102, v86, v102
	v_add_f32_e32 v102, v87, v102
	v_cvt_pk_bf16_f32 v158, v82, v83
	v_cvt_pk_bf16_f32 v159, v84, v85
	s_waitcnt lgkmcnt(5)
	v_mfma_f32_32x32x16_bf16 v[114:129], v[98:101], v[166:169], v[50:65]
	ds_read_b64_tr_b16 v[82:83], v213 offset:36864
	ds_read_b64_tr_b16 v[84:85], v213 offset:37376
	v_add_f32_e32 v98, v88, v102
	v_add_f32_e32 v98, v89, v98
	v_add_f32_e32 v98, v90, v98
	v_add_f32_e32 v146, v91, v98
	v_cvt_pk_bf16_f32 v160, v86, v87
	v_cvt_pk_bf16_f32 v161, v88, v89
	s_waitcnt lgkmcnt(6)
	v_mfma_f32_32x32x16_bf16 v[98:113], v[134:137], v[166:169], v[50:65]
	ds_read_b64_tr_b16 v[86:87], v213 offset:33792
	ds_read_b64_tr_b16 v[88:89], v213 offset:34304
	v_add_f32_e32 v134, v92, v146
	v_add_f32_e32 v134, v93, v134
	v_add_f32_e32 v134, v94, v134
	v_add_f32_e32 v134, v95, v134
	v_cvt_pk_bf16_f32 v154, v90, v91
	v_cvt_pk_bf16_f32 v155, v92, v93
	s_waitcnt lgkmcnt(7)
	v_mfma_f32_32x32x16_bf16 v[114:129], v[138:141], v[162:165], v[114:129]
	ds_read_b64_tr_b16 v[90:91], v213 offset:37888
	ds_read_b64_tr_b16 v[92:93], v213 offset:38400
	s_waitcnt lgkmcnt(8)
	v_mfma_f32_32x32x16_bf16 v[98:113], v[130:133], v[162:165], v[98:113]
	v_add_f32_e32 v130, v96, v134
	v_add_f32_e32 v130, v97, v130
	v_add_f32_e32 v130, v66, v130
	v_add_f32_e32 v130, v67, v130
	v_cvt_pk_bf16_f32 v156, v94, v95
	v_cvt_pk_bf16_f32 v157, v96, v97
	ds_read_b64_tr_b16 v[94:95], v213 offset:34816
	ds_read_b64_tr_b16 v[96:97], v213 offset:35328
	v_add_f32_e32 v130, v68, v130
	v_add_f32_e32 v130, v69, v130
	v_add_f32_e32 v130, v70, v130
	v_add_f32_e32 v130, v71, v130
	v_cvt_pk_bf16_f32 v150, v66, v67
	v_cvt_pk_bf16_f32 v151, v68, v69
	ds_read_b64_tr_b16 v[66:67], v213 offset:38912
	ds_read_b64_tr_b16 v[68:69], v213 offset:39424
	v_add_f32_e32 v130, v72, v130
	v_add_f32_e32 v130, v73, v130
	v_add_f32_e32 v130, v74, v130
	v_add_f32_e32 v130, v75, v130
	v_cvt_pk_bf16_f32 v152, v70, v71
	v_cvt_pk_bf16_f32 v153, v72, v73
	ds_read_b64_tr_b16 v[70:71], v213 offset:35840
	ds_read_b64_tr_b16 v[72:73], v213 offset:36352
	v_add_f32_e32 v130, v76, v130
	v_add_f32_e32 v130, v77, v130
	v_add_f32_e32 v130, v78, v130
	v_add_f32_e32 v130, v79, v130
	v_cvt_pk_bf16_f32 v146, v74, v75
	v_cvt_pk_bf16_f32 v147, v76, v77
	ds_read_b64_tr_b16 v[74:75], v213 offset:39936
	ds_read_b64_tr_b16 v[76:77], v213 offset:40448
	v_add_f32_e32 v130, v80, v130
	v_add_f32_e32 v130, v81, v130
	v_add_f32_e32 v130, 0, v130
	v_cvt_pk_bf16_f32 v148, v78, v79
	v_cvt_pk_bf16_f32 v149, v80, v81
	s_mov_b64 s[48:49], 0x1f0000
	v_lshl_add_u64 v[78:79], v[174:175], 0, s[48:49]
	s_add_i32 s48, s50, s82
	s_add_i32 s49, s48, 0x4000
	s_mov_b32 s50, m0
	s_mov_b32 m0, s49
	s_nop 0
	global_load_lds_dwordx4 v[78:79], off
	s_mov_b32 m0, s50
	v_lshl_add_u64 v[78:79], v[172:173], 0, s[18:19]
	s_mov_b32 s49, m0
	s_mov_b32 m0, s80
	s_nop 0
	global_load_lds_dwordx4 v[78:79], off
	s_mov_b32 m0, s49
	v_add_f32_e32 v215, v227, v130
	s_waitcnt lgkmcnt(14)
	v_mfma_f32_32x32x16_bf16 v[18:33], v[158:161], v[142:145], v[18:33]
	v_exp_f32_e32 v114, v114
	v_exp_f32_e32 v115, v115
	v_exp_f32_e32 v116, v116
	v_exp_f32_e32 v117, v117
	s_waitcnt lgkmcnt(12)
	v_mfma_f32_32x32x16_bf16 v[34:49], v[158:161], v[82:85], v[34:49]
	v_exp_f32_e32 v118, v118
	v_exp_f32_e32 v119, v119
	v_exp_f32_e32 v120, v120
	v_exp_f32_e32 v121, v121
	ds_read_b128 v[78:81], v214
	ds_read_b128 v[82:85], v214 offset:512
	s_waitcnt lgkmcnt(12)
	v_mfma_f32_32x32x16_bf16 v[18:33], v[154:157], v[86:89], v[18:33]
	v_exp_f32_e32 v122, v122
	v_exp_f32_e32 v123, v123
	v_exp_f32_e32 v124, v124
	v_exp_f32_e32 v125, v125
	ds_read_b128 v[86:89], v214 offset:2048
	ds_read_b128 v[228:231], v214 offset:2560
	s_waitcnt lgkmcnt(12)
	v_mfma_f32_32x32x16_bf16 v[34:49], v[154:157], v[90:93], v[34:49]
	v_exp_f32_e32 v126, v126
	v_exp_f32_e32 v127, v127
	v_exp_f32_e32 v128, v128
	v_exp_f32_e32 v129, v129
	s_waitcnt lgkmcnt(10)
	v_mfma_f32_32x32x16_bf16 v[18:33], v[150:153], v[94:97], v[18:33]
	v_exp_f32_e32 v98, v98
	v_exp_f32_e32 v99, v99
	v_exp_f32_e32 v100, v100
	v_exp_f32_e32 v101, v101
	s_waitcnt lgkmcnt(8)
	v_mfma_f32_32x32x16_bf16 v[34:49], v[150:153], v[66:69], v[34:49]
	v_exp_f32_e32 v102, v102
	v_exp_f32_e32 v103, v103
	v_exp_f32_e32 v104, v104
	v_exp_f32_e32 v105, v105
	s_waitcnt lgkmcnt(6)
	v_mfma_f32_32x32x16_bf16 v[18:33], v[146:149], v[70:73], v[18:33]
	v_exp_f32_e32 v106, v106
	v_exp_f32_e32 v107, v107
	v_exp_f32_e32 v108, v108
	v_exp_f32_e32 v109, v109
	s_waitcnt lgkmcnt(4)
	v_mfma_f32_32x32x16_bf16 v[34:49], v[146:149], v[74:77], v[34:49]
	v_exp_f32_e32 v110, v110
	v_exp_f32_e32 v111, v111
	v_exp_f32_e32 v112, v112
	v_exp_f32_e32 v113, v113
	s_waitcnt vmcnt(2) lgkmcnt(0)
	s_barrier
;   #define RESC() do{ if(!FIXREF&&resc){ asm volatile("s_waitcnt lgkmcnt(0)":::"memory"); \
;       _Pragma("unroll") for(int d_=0;d_<2;++d_) _Pragma("unroll") for(int r=0;r<16;++r)o[d_][r]*=wsf[crow(r,hi)]; } }while(0)
;   #define ROT() do{sl_prev=sl_cur;sl_cur=sl_next;sl_next=(sl_next==(NSLOT-1)*SLOTB)?0:sl_next+SLOTB;}while(0)
;   #define ENDW(tt) do{ if((tt)+3<NT){WAIT_BAR(2);} else if((tt)+2<NT){WAIT_BAR(1);} else {WAIT_BAR(0);} }while(0)
; template<int THRL,bool FIXREF,bool HALFK> __device__ __forceinline__ void attn_unit(float mref,long rowbase,int q0,const bf16*Qh,int PQ,const bf16*__restrict__ Kh_,int PK,const bf16*__restrict__ Vh_,int PV,bf16*Oh,int PO,const bf16*Gh,int PG,u32x4(&okeep)[4],int omode,float lam,float oml,const float ...
;     ...
;   for(;t+1<NT;t+=2){
;     STEP(pB0,pB1,pA0,pA1,t,(t+3<NT),(t+1<NT),(t+1<NT));       ENDW(t);   RESC(); ROT();
	ds_read_b64_tr_b16 v[90:91], v213 offset:40960
	ds_read_b64_tr_b16 v[92:93], v213 offset:41472
	v_add_f32_e32 v66, v114, v115
	v_add_f32_e32 v66, v116, v66
	v_add_f32_e32 v66, v117, v66
	v_add_f32_e32 v66, v118, v66
	v_add_f32_e32 v66, v119, v66
	v_cvt_pk_bf16_f32 v158, v114, v115
	v_cvt_pk_bf16_f32 v159, v116, v117
	s_waitcnt lgkmcnt(5)
	v_mfma_f32_32x32x16_bf16 v[130:145], v[78:81], v[166:169], v[50:65]
	ds_read_b64_tr_b16 v[94:95], v213 offset:45056
	ds_read_b64_tr_b16 v[96:97], v213 offset:45568
	v_add_f32_e32 v66, v120, v66
	v_add_f32_e32 v66, v121, v66
	v_add_f32_e32 v66, v122, v66
	v_add_f32_e32 v114, v123, v66
	s_waitcnt lgkmcnt(6)
	v_mfma_f32_32x32x16_bf16 v[66:81], v[82:85], v[166:169], v[50:65]
	v_cvt_pk_bf16_f32 v160, v118, v119
	v_cvt_pk_bf16_f32 v161, v120, v121
	ds_read_b64_tr_b16 v[82:83], v213 offset:41984
	ds_read_b64_tr_b16 v[84:85], v213 offset:42496
	s_waitcnt lgkmcnt(7)
	v_mfma_f32_32x32x16_bf16 v[130:145], v[86:89], v[162:165], v[130:145]
	v_add_f32_e32 v86, v124, v114
	v_add_f32_e32 v86, v125, v86
	v_add_f32_e32 v86, v126, v86
	v_add_f32_e32 v114, v127, v86
	v_cvt_pk_bf16_f32 v154, v122, v123
	v_cvt_pk_bf16_f32 v155, v124, v125
	ds_read_b64_tr_b16 v[86:87], v213 offset:46080
	ds_read_b64_tr_b16 v[88:89], v213 offset:46592
	s_waitcnt lgkmcnt(8)
	v_mfma_f32_32x32x16_bf16 v[66:81], v[228:231], v[162:165], v[66:81]
	v_add_f32_e32 v114, v128, v114
	v_add_f32_e32 v114, v129, v114
	v_add_f32_e32 v114, v98, v114
	v_add_f32_e32 v118, v99, v114
	v_cvt_pk_bf16_f32 v156, v126, v127
	v_cvt_pk_bf16_f32 v157, v128, v129
	ds_read_b64_tr_b16 v[114:115], v213 offset:43008
	ds_read_b64_tr_b16 v[116:117], v213 offset:43520
	v_add_f32_e32 v118, v100, v118
	v_add_f32_e32 v118, v101, v118
	v_add_f32_e32 v118, v102, v118
	v_add_f32_e32 v118, v103, v118
	v_cvt_pk_bf16_f32 v150, v98, v99
	v_cvt_pk_bf16_f32 v151, v100, v101
	ds_read_b64_tr_b16 v[98:99], v213 offset:47104
	ds_read_b64_tr_b16 v[100:101], v213 offset:47616
	v_add_f32_e32 v118, v104, v118
	v_add_f32_e32 v118, v105, v118
	v_add_f32_e32 v118, v106, v118
	v_add_f32_e32 v118, v107, v118
	v_cvt_pk_bf16_f32 v152, v102, v103
	v_cvt_pk_bf16_f32 v153, v104, v105
	ds_read_b64_tr_b16 v[102:103], v213 offset:44032
	ds_read_b64_tr_b16 v[104:105], v213 offset:44544
	v_add_f32_e32 v118, v108, v118
	v_add_f32_e32 v118, v109, v118
	v_add_f32_e32 v118, v110, v118
	v_add_f32_e32 v118, v111, v118
	v_cvt_pk_bf16_f32 v146, v106, v107
	v_cvt_pk_bf16_f32 v147, v108, v109
	ds_read_b64_tr_b16 v[106:107], v213 offset:48128
	ds_read_b64_tr_b16 v[108:109], v213 offset:48640
	v_add_f32_e32 v118, v112, v118
	v_add_f32_e32 v118, v113, v118
	v_add_f32_e32 v118, 0, v118
	v_cvt_pk_bf16_f32 v148, v110, v111
	v_cvt_pk_bf16_f32 v149, v112, v113
	s_mov_b64 s[50:51], 0x1f8000
	v_lshl_add_u64 v[110:111], v[174:175], 0, s[50:51]
	s_mov_b32 s49, m0
	s_mov_b32 m0, s81
	s_nop 0
	global_load_lds_dwordx4 v[110:111], off
	s_mov_b32 m0, s49
	v_lshl_add_u64 v[110:111], v[172:173], 0, s[6:7]
	s_add_i32 s49, s48, 0x8000
	s_mov_b32 s50, m0
	s_mov_b32 m0, s49
	s_nop 0
	global_load_lds_dwordx4 v[110:111], off
	s_mov_b32 m0, s50
	v_add_f32_e32 v215, v215, v118
	s_waitcnt lgkmcnt(14)
	v_mfma_f32_32x32x16_bf16 v[18:33], v[158:161], v[90:93], v[18:33]
	v_exp_f32_e32 v130, v130
	v_exp_f32_e32 v131, v131
	v_exp_f32_e32 v132, v132
	v_exp_f32_e32 v133, v133
	s_waitcnt lgkmcnt(12)
	v_mfma_f32_32x32x16_bf16 v[34:49], v[158:161], v[94:97], v[34:49]
	v_exp_f32_e32 v134, v134
	v_exp_f32_e32 v135, v135
	v_exp_f32_e32 v136, v136
	v_exp_f32_e32 v137, v137
	ds_read_b128 v[90:93], v214 offset:8192
	ds_read_b128 v[110:113], v214 offset:8704
	s_waitcnt lgkmcnt(12)
	v_mfma_f32_32x32x16_bf16 v[18:33], v[154:157], v[82:85], v[18:33]
	v_exp_f32_e32 v138, v138
	v_exp_f32_e32 v139, v139
	v_exp_f32_e32 v140, v140
	v_exp_f32_e32 v141, v141
	ds_read_b128 v[228:231], v214 offset:10240
	ds_read_b128 v[232:235], v214 offset:10752
	s_waitcnt lgkmcnt(12)
	v_mfma_f32_32x32x16_bf16 v[34:49], v[154:157], v[86:89], v[34:49]
	v_exp_f32_e32 v142, v142
	v_exp_f32_e32 v143, v143
	v_exp_f32_e32 v144, v144
	v_exp_f32_e32 v145, v145
	s_waitcnt lgkmcnt(10)
	v_mfma_f32_32x32x16_bf16 v[18:33], v[150:153], v[114:117], v[18:33]
	v_exp_f32_e32 v66, v66
	v_exp_f32_e32 v67, v67
	v_exp_f32_e32 v68, v68
	v_exp_f32_e32 v69, v69
	s_waitcnt lgkmcnt(8)
	v_mfma_f32_32x32x16_bf16 v[34:49], v[150:153], v[98:101], v[34:49]
	v_exp_f32_e32 v70, v70
	v_exp_f32_e32 v71, v71
	v_exp_f32_e32 v72, v72
	v_exp_f32_e32 v73, v73
	s_waitcnt lgkmcnt(6)
	v_mfma_f32_32x32x16_bf16 v[18:33], v[146:149], v[102:105], v[18:33]
	v_exp_f32_e32 v74, v74
	v_exp_f32_e32 v75, v75
	v_exp_f32_e32 v76, v76
	v_exp_f32_e32 v77, v77
	s_waitcnt lgkmcnt(4)
	v_mfma_f32_32x32x16_bf16 v[34:49], v[146:149], v[106:109], v[34:49]
	v_exp_f32_e32 v78, v78
	v_exp_f32_e32 v79, v79
	v_exp_f32_e32 v80, v80
	v_exp_f32_e32 v81, v81
	s_waitcnt vmcnt(2) lgkmcnt(0)
	s_barrier
;   #define RESC() do{ if(!FIXREF&&resc){ asm volatile("s_waitcnt lgkmcnt(0)":::"memory"); \
;       _Pragma("unroll") for(int d_=0;d_<2;++d_) _Pragma("unroll") for(int r=0;r<16;++r)o[d_][r]*=wsf[crow(r,hi)]; } }while(0)
;   #define ROT() do{sl_prev=sl_cur;sl_cur=sl_next;sl_next=(sl_next==(NSLOT-1)*SLOTB)?0:sl_next+SLOTB;}while(0)
;   #define ENDW(tt) do{ if((tt)+3<NT){WAIT_BAR(2);} else if((tt)+2<NT){WAIT_BAR(1);} else {WAIT_BAR(0);} }while(0)
; template<int THRL,bool FIXREF,bool HALFK> __device__ __forceinline__ void attn_unit(float mref,long rowbase,int q0,const bf16*Qh,int PQ,const bf16*__restrict__ Kh_,int PK,const bf16*__restrict__ Vh_,int PV,bf16*Oh,int PO,const bf16*Gh,int PG,u32x4(&okeep)[4],int omode,float lam,float oml,const float ...
;     ...
;   for(;t+1<NT;t+=2){
;     STEP(pB0,pB1,pA0,pA1,t,(t+3<NT),(t+1<NT),(t+1<NT));       ENDW(t);   RESC(); ROT();
;     STEP(pA0,pA1,pB0,pB1,t+1,(t+4<NT),(t+2<NT),(t+2<NT));     ENDW(t+1); RESC(); ROT();
	ds_read_b64_tr_b16 v[98:99], v213 offset:24576
	ds_read_b64_tr_b16 v[100:101], v213 offset:25088
	v_add_f32_e32 v82, v130, v131
	v_add_f32_e32 v82, v132, v82
	v_add_f32_e32 v82, v133, v82
	v_add_f32_e32 v82, v134, v82
	v_add_f32_e32 v82, v135, v82
	v_cvt_pk_bf16_f32 v158, v130, v131
	v_cvt_pk_bf16_f32 v159, v132, v133
	s_waitcnt lgkmcnt(5)
	v_mfma_f32_32x32x16_bf16 v[114:129], v[90:93], v[166:169], v[50:65]
	ds_read_b64_tr_b16 v[102:103], v213 offset:28672
	ds_read_b64_tr_b16 v[104:105], v213 offset:29184
	v_add_f32_e32 v82, v136, v82
	v_add_f32_e32 v82, v137, v82
	v_add_f32_e32 v82, v138, v82
	v_add_f32_e32 v130, v139, v82
	v_cvt_pk_bf16_f32 v160, v134, v135
	v_cvt_pk_bf16_f32 v161, v136, v137
	s_waitcnt lgkmcnt(6)
	v_mfma_f32_32x32x16_bf16 v[82:97], v[110:113], v[166:169], v[50:65]
	ds_read_b64_tr_b16 v[106:107], v213 offset:25600
	ds_read_b64_tr_b16 v[108:109], v213 offset:26112
	v_add_f32_e32 v110, v140, v130
	v_add_f32_e32 v110, v141, v110
	v_add_f32_e32 v110, v142, v110
	v_add_f32_e32 v130, v143, v110
	v_cvt_pk_bf16_f32 v154, v138, v139
	v_cvt_pk_bf16_f32 v155, v140, v141
	s_waitcnt lgkmcnt(7)
	v_mfma_f32_32x32x16_bf16 v[114:129], v[228:231], v[162:165], v[114:129]
	ds_read_b64_tr_b16 v[110:111], v213 offset:29696
	ds_read_b64_tr_b16 v[112:113], v213 offset:30208
	v_add_f32_e32 v130, v144, v130
	v_add_f32_e32 v130, v145, v130
	v_add_f32_e32 v130, v66, v130
	v_add_f32_e32 v134, v67, v130
	v_cvt_pk_bf16_f32 v156, v142, v143
	v_cvt_pk_bf16_f32 v157, v144, v145
	s_waitcnt lgkmcnt(8)
	v_mfma_f32_32x32x16_bf16 v[82:97], v[232:235], v[162:165], v[82:97]
	ds_read_b64_tr_b16 v[130:131], v213 offset:26624
	ds_read_b64_tr_b16 v[132:133], v213 offset:27136
	v_add_f32_e32 v134, v68, v134
	v_add_f32_e32 v134, v69, v134
	v_add_f32_e32 v134, v70, v134
	v_add_f32_e32 v134, v71, v134
	v_cvt_pk_bf16_f32 v150, v66, v67
	v_cvt_pk_bf16_f32 v151, v68, v69
	ds_read_b64_tr_b16 v[66:67], v213 offset:30720
	ds_read_b64_tr_b16 v[68:69], v213 offset:31232
	v_add_f32_e32 v134, v72, v134
	v_add_f32_e32 v134, v73, v134
	v_add_f32_e32 v134, v74, v134
	v_add_f32_e32 v134, v75, v134
	v_cvt_pk_bf16_f32 v152, v70, v71
	v_cvt_pk_bf16_f32 v153, v72, v73
	ds_read_b64_tr_b16 v[70:71], v213 offset:27648
	ds_read_b64_tr_b16 v[72:73], v213 offset:28160
	v_add_f32_e32 v134, v76, v134
	v_add_f32_e32 v134, v77, v134
	v_add_f32_e32 v134, v78, v134
	v_add_f32_e32 v134, v79, v134
	v_cvt_pk_bf16_f32 v146, v74, v75
	v_cvt_pk_bf16_f32 v147, v76, v77
	ds_read_b64_tr_b16 v[74:75], v213 offset:31744
	ds_read_b64_tr_b16 v[76:77], v213 offset:32256
	v_add_f32_e32 v134, v80, v134
	v_add_f32_e32 v134, v81, v134
	v_add_f32_e32 v134, 0, v134
	v_cvt_pk_bf16_f32 v148, v78, v79
	v_cvt_pk_bf16_f32 v149, v80, v81
	v_lshl_add_u64 v[78:79], v[172:173], 0, s[94:95]
	s_add_i32 s48, s48, 0xa000
	s_mov_b32 s49, m0
	s_mov_b32 m0, s48
	s_nop 0
	global_load_lds_dwordx4 v[78:79], off
	s_mov_b32 m0, s49
	v_add_f32_e32 v174, v215, v134
	s_waitcnt lgkmcnt(14)
	v_mfma_f32_32x32x16_bf16 v[18:33], v[158:161], v[98:101], v[18:33]
	v_exp_f32_e32 v114, v114
	v_exp_f32_e32 v115, v115
	v_exp_f32_e32 v116, v116
	v_exp_f32_e32 v117, v117
	s_waitcnt lgkmcnt(12)
	v_mfma_f32_32x32x16_bf16 v[34:49], v[158:161], v[102:105], v[34:49]
	v_exp_f32_e32 v118, v118
	v_exp_f32_e32 v119, v119
	v_exp_f32_e32 v120, v120
	v_exp_f32_e32 v121, v121
	ds_read_b128 v[78:81], v214 offset:16384
	ds_read_b128 v[134:137], v214 offset:16896
	s_waitcnt lgkmcnt(12)
	v_mfma_f32_32x32x16_bf16 v[18:33], v[154:157], v[106:109], v[18:33]
	v_exp_f32_e32 v122, v122
	v_exp_f32_e32 v123, v123
	v_exp_f32_e32 v124, v124
	v_exp_f32_e32 v125, v125
	ds_read_b128 v[138:141], v214 offset:18432
	ds_read_b128 v[142:145], v214 offset:18944
	s_waitcnt lgkmcnt(12)
	v_mfma_f32_32x32x16_bf16 v[34:49], v[154:157], v[110:113], v[34:49]
	v_exp_f32_e32 v126, v126
	v_exp_f32_e32 v127, v127
	v_exp_f32_e32 v128, v128
	v_exp_f32_e32 v129, v129
	s_waitcnt lgkmcnt(10)
	v_mfma_f32_32x32x16_bf16 v[18:33], v[150:153], v[130:133], v[18:33]
	v_exp_f32_e32 v82, v82
	v_exp_f32_e32 v83, v83
	v_exp_f32_e32 v84, v84
	v_exp_f32_e32 v85, v85
	s_waitcnt lgkmcnt(8)
	v_mfma_f32_32x32x16_bf16 v[34:49], v[150:153], v[66:69], v[34:49]
	v_exp_f32_e32 v86, v86
	v_exp_f32_e32 v87, v87
	v_exp_f32_e32 v88, v88
	v_exp_f32_e32 v89, v89
	s_waitcnt lgkmcnt(6)
	v_mfma_f32_32x32x16_bf16 v[18:33], v[146:149], v[70:73], v[18:33]
	v_exp_f32_e32 v90, v90
	v_exp_f32_e32 v91, v91
	v_exp_f32_e32 v92, v92
	v_exp_f32_e32 v93, v93
	s_waitcnt lgkmcnt(4)
	v_mfma_f32_32x32x16_bf16 v[34:49], v[146:149], v[74:77], v[34:49]
	v_exp_f32_e32 v94, v94
	v_exp_f32_e32 v95, v95
	v_exp_f32_e32 v96, v96
	v_exp_f32_e32 v97, v97
	s_waitcnt vmcnt(1) lgkmcnt(0)
	s_barrier
;   #define RESC() do{ if(!FIXREF&&resc){ asm volatile("s_waitcnt lgkmcnt(0)":::"memory"); \
;       _Pragma("unroll") for(int d_=0;d_<2;++d_) _Pragma("unroll") for(int r=0;r<16;++r)o[d_][r]*=wsf[crow(r,hi)]; } }while(0)
;   #define ROT() do{sl_prev=sl_cur;sl_cur=sl_next;sl_next=(sl_next==(NSLOT-1)*SLOTB)?0:sl_next+SLOTB;}while(0)
;   #define ENDW(tt) do{ if((tt)+3<NT){WAIT_BAR(2);} else if((tt)+2<NT){WAIT_BAR(1);} else {WAIT_BAR(0);} }while(0)
; template<int THRL,bool FIXREF,bool HALFK> __device__ __forceinline__ void attn_unit(float mref,long rowbase,int q0,const bf16*Qh,int PQ,const bf16*__restrict__ Kh_,int PK,const bf16*__restrict__ Vh_,int PV,bf16*Oh,int PO,const bf16*Gh,int PG,u32x4(&okeep)[4],int omode,float lam,float oml,const float ...
;     ...
;   for(;t+1<NT;t+=2){
;     STEP(pB0,pB1,pA0,pA1,t,(t+3<NT),(t+1<NT),(t+1<NT));       ENDW(t);   RESC(); ROT();
;     STEP(pA0,pA1,pB0,pB1,t+1,(t+4<NT),(t+2<NT),(t+2<NT));     ENDW(t+1); RESC(); ROT();
	ds_read_b64_tr_b16 v[130:131], v213 offset:32768
	ds_read_b64_tr_b16 v[132:133], v213 offset:33280
	v_add_f32_e32 v66, v114, v115
	v_add_f32_e32 v66, v116, v66
	v_add_f32_e32 v66, v117, v66
	v_add_f32_e32 v66, v118, v66
	v_add_f32_e32 v66, v119, v66
	v_cvt_pk_bf16_f32 v158, v114, v115
	v_cvt_pk_bf16_f32 v159, v116, v117
	s_waitcnt lgkmcnt(5)
	v_mfma_f32_32x32x16_bf16 v[98:113], v[78:81], v[166:169], v[50:65]
	ds_read_b64_tr_b16 v[114:115], v213 offset:36864
	ds_read_b64_tr_b16 v[116:117], v213 offset:37376
	v_add_f32_e32 v66, v120, v66
	v_add_f32_e32 v66, v121, v66
	v_add_f32_e32 v66, v122, v66
	v_add_f32_e32 v146, v123, v66
	s_waitcnt lgkmcnt(6)
	v_mfma_f32_32x32x16_bf16 v[66:81], v[134:137], v[166:169], v[50:65]
	v_cvt_pk_bf16_f32 v160, v118, v119
	v_cvt_pk_bf16_f32 v161, v120, v121
	ds_read_b64_tr_b16 v[118:119], v213 offset:33792
	ds_read_b64_tr_b16 v[120:121], v213 offset:34304
	v_add_f32_e32 v134, v124, v146
	v_add_f32_e32 v134, v125, v134
	v_add_f32_e32 v134, v126, v134
	s_waitcnt lgkmcnt(7)
	v_mfma_f32_32x32x16_bf16 v[98:113], v[138:141], v[162:165], v[98:113]
	v_add_f32_e32 v138, v127, v134
	v_cvt_pk_bf16_f32 v154, v122, v123
	v_cvt_pk_bf16_f32 v155, v124, v125
	ds_read_b64_tr_b16 v[134:135], v213 offset:37888
	ds_read_b64_tr_b16 v[136:137], v213 offset:38400
	s_waitcnt lgkmcnt(8)
	v_mfma_f32_32x32x16_bf16 v[66:81], v[142:145], v[162:165], v[66:81]
	v_add_f32_e32 v122, v128, v138
	v_add_f32_e32 v122, v129, v122
	v_add_f32_e32 v122, v82, v122
	v_add_f32_e32 v122, v83, v122
	v_cvt_pk_bf16_f32 v156, v126, v127
	v_cvt_pk_bf16_f32 v157, v128, v129
	ds_read_b64_tr_b16 v[124:125], v213 offset:34816
	ds_read_b64_tr_b16 v[126:127], v213 offset:35328
	v_add_f32_e32 v122, v84, v122
	v_add_f32_e32 v122, v85, v122
	v_add_f32_e32 v122, v86, v122
	v_add_f32_e32 v122, v87, v122
	v_cvt_pk_bf16_f32 v150, v82, v83
	v_cvt_pk_bf16_f32 v151, v84, v85
	ds_read_b64_tr_b16 v[82:83], v213 offset:38912
	ds_read_b64_tr_b16 v[84:85], v213 offset:39424
	v_add_f32_e32 v122, v88, v122
	v_add_f32_e32 v122, v89, v122
	v_add_f32_e32 v122, v90, v122
	v_add_f32_e32 v122, v91, v122
	v_cvt_pk_bf16_f32 v152, v86, v87
	v_cvt_pk_bf16_f32 v153, v88, v89
	ds_read_b64_tr_b16 v[86:87], v213 offset:35840
	ds_read_b64_tr_b16 v[88:89], v213 offset:36352
	v_add_f32_e32 v122, v92, v122
	v_add_f32_e32 v122, v93, v122
	v_add_f32_e32 v122, v94, v122
	v_add_f32_e32 v122, v95, v122
	v_cvt_pk_bf16_f32 v146, v90, v91
	v_cvt_pk_bf16_f32 v147, v92, v93
	ds_read_b64_tr_b16 v[90:91], v213 offset:39936
	ds_read_b64_tr_b16 v[92:93], v213 offset:40448
	v_add_f32_e32 v122, v96, v122
	v_add_f32_e32 v122, v97, v122
	v_add_f32_e32 v122, 0, v122
	v_cvt_pk_bf16_f32 v148, v94, v95
	v_cvt_pk_bf16_f32 v149, v96, v97
	v_lshl_add_u64 v[94:95], v[172:173], 0, s[26:27]
	s_mov_b32 s48, m0
	s_mov_b32 m0, s80
	s_nop 0
	global_load_lds_dwordx4 v[94:95], off
	s_mov_b32 m0, s48
	v_add_f32_e32 v122, v174, v122
	s_waitcnt lgkmcnt(14)
	v_mfma_f32_32x32x16_bf16 v[18:33], v[158:161], v[130:133], v[18:33]
	v_exp_f32_e32 v98, v98
	v_exp_f32_e32 v99, v99
	v_exp_f32_e32 v100, v100
	v_exp_f32_e32 v101, v101
	s_waitcnt lgkmcnt(12)
	v_mfma_f32_32x32x16_bf16 v[34:49], v[158:161], v[114:117], v[34:49]
	v_exp_f32_e32 v102, v102
	v_exp_f32_e32 v103, v103
	v_exp_f32_e32 v104, v104
	v_exp_f32_e32 v105, v105
	ds_read_b128 v[128:131], v214
	ds_read_b128 v[138:141], v214 offset:512
	s_waitcnt lgkmcnt(12)
	v_mfma_f32_32x32x16_bf16 v[18:33], v[154:157], v[118:121], v[18:33]
	v_exp_f32_e32 v106, v106
	v_exp_f32_e32 v107, v107
	v_exp_f32_e32 v108, v108
	v_exp_f32_e32 v109, v109
	ds_read_b128 v[142:145], v214 offset:2048
	ds_read_b128 v[172:175], v214 offset:2560
	s_waitcnt lgkmcnt(12)
	v_mfma_f32_32x32x16_bf16 v[34:49], v[154:157], v[134:137], v[34:49]
	v_exp_f32_e32 v110, v110
	v_exp_f32_e32 v111, v111
	v_exp_f32_e32 v112, v112
	v_exp_f32_e32 v113, v113
	s_waitcnt lgkmcnt(10)
	v_mfma_f32_32x32x16_bf16 v[18:33], v[150:153], v[124:127], v[18:33]
	v_exp_f32_e32 v66, v66
	v_exp_f32_e32 v67, v67
	v_exp_f32_e32 v68, v68
	v_exp_f32_e32 v69, v69
	s_waitcnt lgkmcnt(8)
	v_mfma_f32_32x32x16_bf16 v[34:49], v[150:153], v[82:85], v[34:49]
	v_exp_f32_e32 v70, v70
	v_exp_f32_e32 v71, v71
	v_exp_f32_e32 v72, v72
	v_exp_f32_e32 v73, v73
	s_waitcnt lgkmcnt(6)
	v_mfma_f32_32x32x16_bf16 v[18:33], v[146:149], v[86:89], v[18:33]
	v_exp_f32_e32 v74, v74
	v_exp_f32_e32 v75, v75
	v_exp_f32_e32 v76, v76
	v_exp_f32_e32 v77, v77
	s_waitcnt lgkmcnt(4)
	v_mfma_f32_32x32x16_bf16 v[34:49], v[146:149], v[90:93], v[34:49]
	v_exp_f32_e32 v78, v78
	v_exp_f32_e32 v79, v79
	v_exp_f32_e32 v80, v80
	v_exp_f32_e32 v81, v81
	s_waitcnt vmcnt(0) lgkmcnt(0)
	s_barrier
; #define SBAR() __builtin_amdgcn_sched_barrier(0)
;   #define RESC() do{ if(!FIXREF&&resc){ asm volatile("s_waitcnt lgkmcnt(0)":::"memory"); \
;       _Pragma("unroll") for(int d_=0;d_<2;++d_) _Pragma("unroll") for(int r=0;r<16;++r)o[d_][r]*=wsf[crow(r,hi)]; } }while(0)
;   #define PKW(P,B) cvtpk_s(P[B],P[B+1])
; template<int THRL,bool FIXREF,bool HALFK> __device__ __forceinline__ void attn_unit(float mref,long rowbase,int q0,const bf16*Qh,int PQ,const bf16*__restrict__ Kh_,int PK,const bf16*__restrict__ Vh_,int PV,bf16*Oh,int PO,const bf16*Gh,int PG,u32x4(&okeep)[4],int omode,float lam,float oml,const float ...
;     ...
;   STEP(pB0,pB1,pA0,pA1,NT-1,false,false,false); RESC();
;   { float sacc=pB0[0]+pB0[1]; _Pragma("unroll") for(int r=2;r<16;++r)sacc+=pB0[r]; _Pragma("unroll") for(int r=0;r<16;++r)sacc+=pB1[r]; l_reg+=sacc;
;     pw0=(u32x4){PKW(pB0,0),PKW(pB0,2),PKW(pB0,4),PKW(pB0,6)};pw1=(u32x4){PKW(pB0,8),PKW(pB0,10),PKW(pB0,12),PKW(pB0,14)};pw2=(u32x4){PKW(pB1,0),PKW(pB1,2),PKW(pB1,4),PKW(pB1,6)};pw3=(u32x4){PKW(pB1,8),PKW(pB1,10),PKW(pB1,12),PKW(pB1,14)};
;     SBAR(); pv(o,vb0+sl_cur,PAF(0),PAF(1),PAF(2),PAF(3)); }
	ds_read_b64_tr_b16 v[114:115], v213 offset:40960
	ds_read_b64_tr_b16 v[116:117], v213 offset:41472
	v_add_f32_e32 v82, v98, v99
	v_add_f32_e32 v82, v100, v82
	v_add_f32_e32 v82, v101, v82
	v_add_f32_e32 v82, v102, v82
	v_add_f32_e32 v118, v103, v82
	v_cvt_pk_bf16_f32 v158, v98, v99
	v_cvt_pk_bf16_f32 v159, v100, v101
	s_waitcnt lgkmcnt(5)
	v_mfma_f32_32x32x16_bf16 v[82:97], v[128:131], v[166:169], v[50:65]
	ds_read_b64_tr_b16 v[98:99], v213 offset:45056
	ds_read_b64_tr_b16 v[100:101], v213 offset:45568
	v_add_f32_e32 v118, v104, v118
	v_add_f32_e32 v118, v105, v118
	v_add_f32_e32 v118, v106, v118
	v_add_f32_e32 v123, v107, v118
	v_cvt_pk_bf16_f32 v160, v102, v103
	v_cvt_pk_bf16_f32 v161, v104, v105
	s_waitcnt lgkmcnt(6)
	v_mfma_f32_32x32x16_bf16 v[50:65], v[138:141], v[166:169], v[50:65]
	ds_read_b64_tr_b16 v[118:119], v213 offset:41984
	ds_read_b64_tr_b16 v[120:121], v213 offset:42496
	v_add_f32_e32 v102, v108, v123
	v_add_f32_e32 v102, v109, v102
	v_add_f32_e32 v102, v110, v102
	v_add_f32_e32 v123, v111, v102
	v_cvt_pk_bf16_f32 v154, v106, v107
	v_cvt_pk_bf16_f32 v155, v108, v109
	s_waitcnt lgkmcnt(7)
	v_mfma_f32_32x32x16_bf16 v[82:97], v[142:145], v[162:165], v[82:97]
	ds_read_b64_tr_b16 v[102:103], v213 offset:46080
	ds_read_b64_tr_b16 v[104:105], v213 offset:46592
	v_add_f32_e32 v106, v112, v123
	v_add_f32_e32 v106, v113, v106
	v_add_f32_e32 v106, v66, v106
	v_add_f32_e32 v123, v67, v106
	v_cvt_pk_bf16_f32 v156, v110, v111
	v_cvt_pk_bf16_f32 v157, v112, v113
	s_waitcnt lgkmcnt(8)
	v_mfma_f32_32x32x16_bf16 v[50:65], v[172:175], v[162:165], v[50:65]
	ds_read_b64_tr_b16 v[106:107], v213 offset:43008
	ds_read_b64_tr_b16 v[108:109], v213 offset:43520
	v_add_f32_e32 v110, v68, v123
	v_add_f32_e32 v110, v69, v110
	v_add_f32_e32 v110, v70, v110
	v_add_f32_e32 v110, v71, v110
	v_cvt_pk_bf16_f32 v150, v66, v67
	v_cvt_pk_bf16_f32 v151, v68, v69
	ds_read_b64_tr_b16 v[66:67], v213 offset:47104
	ds_read_b64_tr_b16 v[68:69], v213 offset:47616
	v_add_f32_e32 v110, v72, v110
	v_add_f32_e32 v110, v73, v110
	v_add_f32_e32 v110, v74, v110
	v_add_f32_e32 v123, v75, v110
	v_cvt_pk_bf16_f32 v152, v70, v71
	v_cvt_pk_bf16_f32 v153, v72, v73
	ds_read_b64_tr_b16 v[110:111], v213 offset:44032
	ds_read_b64_tr_b16 v[112:113], v213 offset:44544
	v_add_f32_e32 v70, v76, v123
	v_add_f32_e32 v70, v77, v70
	v_add_f32_e32 v70, v78, v70
	v_add_f32_e32 v123, v79, v70
	v_cvt_pk_bf16_f32 v146, v74, v75
	v_cvt_pk_bf16_f32 v147, v76, v77
	ds_read_b64_tr_b16 v[70:71], v213 offset:48128
	ds_read_b64_tr_b16 v[72:73], v213 offset:48640
	v_add_f32_e32 v74, v80, v123
	v_add_f32_e32 v74, v81, v74
	v_add_f32_e32 v74, 0, v74
	v_cvt_pk_bf16_f32 v148, v78, v79
	v_cvt_pk_bf16_f32 v149, v80, v81
	v_exp_f32_e32 v82, v82
	v_exp_f32_e32 v83, v83
	v_exp_f32_e32 v84, v84
	v_exp_f32_e32 v85, v85
	s_nop 0
	v_exp_f32_e32 v86, v86
	v_exp_f32_e32 v87, v87
	v_exp_f32_e32 v88, v88
	v_exp_f32_e32 v89, v89
	s_nop 0
	v_exp_f32_e32 v90, v90
	v_exp_f32_e32 v91, v91
	v_exp_f32_e32 v92, v92
	v_exp_f32_e32 v93, v93
	s_nop 0
	v_exp_f32_e32 v94, v94
	v_exp_f32_e32 v95, v95
	v_exp_f32_e32 v96, v96
	v_exp_f32_e32 v97, v97
	v_exp_f32_e32 v50, v50
	v_exp_f32_e32 v51, v51
	v_exp_f32_e32 v52, v52
	v_exp_f32_e32 v53, v53
	s_nop 0
	v_exp_f32_e32 v54, v54
	v_exp_f32_e32 v55, v55
	v_exp_f32_e32 v56, v56
	v_exp_f32_e32 v57, v57
	s_nop 0
	v_exp_f32_e32 v58, v58
	v_exp_f32_e32 v59, v59
	v_exp_f32_e32 v60, v60
	v_exp_f32_e32 v61, v61
	s_nop 0
	v_exp_f32_e32 v62, v62
	v_exp_f32_e32 v63, v63
	v_exp_f32_e32 v64, v64
	v_exp_f32_e32 v65, v65
	s_waitcnt lgkmcnt(14)
	v_mfma_f32_32x32x16_bf16 v[18:33], v[158:161], v[114:117], v[18:33]
	v_add_f32_e32 v75, v82, v83
	v_add_f32_e32 v75, v84, v75
	v_add_f32_e32 v75, v85, v75
	v_add_f32_e32 v75, v86, v75
	v_add_f32_e32 v75, v87, v75
	v_add_f32_e32 v75, v88, v75
	v_add_f32_e32 v75, v89, v75
	s_waitcnt lgkmcnt(12)
	v_mfma_f32_32x32x16_bf16 v[34:49], v[158:161], v[98:101], v[34:49]
	v_add_f32_e32 v75, v90, v75
	v_add_f32_e32 v75, v91, v75
	v_add_f32_e32 v75, v92, v75
	v_add_f32_e32 v75, v93, v75
	v_add_f32_e32 v75, v94, v75
	v_add_f32_e32 v75, v95, v75
	v_add_f32_e32 v75, v96, v75
	s_waitcnt lgkmcnt(10)
	v_mfma_f32_32x32x16_bf16 v[18:33], v[154:157], v[118:121], v[18:33]
	v_add_f32_e32 v75, v97, v75
	v_add_f32_e32 v75, v50, v75
	v_add_f32_e32 v75, v51, v75
	v_add_f32_e32 v75, v52, v75
	v_add_f32_e32 v75, v53, v75
	v_add_f32_e32 v75, v54, v75
	v_add_f32_e32 v75, v55, v75
	s_waitcnt lgkmcnt(8)
	v_mfma_f32_32x32x16_bf16 v[34:49], v[154:157], v[102:105], v[34:49]
	v_add_f32_e32 v75, v56, v75
	v_add_f32_e32 v75, v57, v75
	v_add_f32_e32 v75, v58, v75
	v_add_f32_e32 v75, v59, v75
	v_add_f32_e32 v75, v60, v75
	v_add_f32_e32 v75, v61, v75
	v_add_f32_e32 v75, v62, v75
	s_waitcnt lgkmcnt(6)
	v_mfma_f32_32x32x16_bf16 v[18:33], v[150:153], v[106:109], v[18:33]
	v_add_f32_e32 v75, v63, v75
	v_add_f32_e32 v75, v64, v75
	v_add_f32_e32 v75, v65, v75
	v_add_f32_e32 v74, v122, v74
	v_add_f32_e32 v74, v74, v75
	v_cvt_pk_bf16_f32 v76, v82, v83
	v_cvt_pk_bf16_f32 v77, v84, v85
	s_waitcnt lgkmcnt(4)
	v_mfma_f32_32x32x16_bf16 v[34:49], v[150:153], v[66:69], v[34:49]
	v_cvt_pk_bf16_f32 v78, v86, v87
	v_cvt_pk_bf16_f32 v79, v88, v89
	v_cvt_pk_bf16_f32 v80, v90, v91
	v_cvt_pk_bf16_f32 v81, v92, v93
	v_cvt_pk_bf16_f32 v82, v94, v95
	v_cvt_pk_bf16_f32 v83, v96, v97
	v_cvt_pk_bf16_f32 v50, v50, v51
	s_waitcnt lgkmcnt(2)
	v_mfma_f32_32x32x16_bf16 v[18:33], v[146:149], v[110:113], v[18:33]
	v_cvt_pk_bf16_f32 v51, v52, v53
	v_cvt_pk_bf16_f32 v52, v54, v55
	v_cvt_pk_bf16_f32 v53, v56, v57
	v_cvt_pk_bf16_f32 v54, v58, v59
	v_cvt_pk_bf16_f32 v55, v60, v61
	v_cvt_pk_bf16_f32 v56, v62, v63
	v_cvt_pk_bf16_f32 v57, v64, v65
	s_waitcnt lgkmcnt(0)
; __device__ __forceinline__ int crow(int r,int hi){return (r&3)+8*(r>>2)+4*hi;}
; #define SBAR() __builtin_amdgcn_sched_barrier(0)
; __device__ __forceinline__ void pv(f32x16*o,int vb,bf16x8 pa0,bf16x8 pa1,bf16x8 pa2,bf16x8 pa3){
;   #pragma unroll
;   for(int d0=0;d0<2;++d0){s16x4 lo[4],hi[4];
;     #pragma unroll
;     for(int ks=0;ks<4;++ks){
;       asm volatile("ds_read_b64_tr_b16 %0,%1 offset:%c2":"=&v"(lo[ks]):"v"(vb),"i"(d0*4096+ks*1024):"memory");
;       asm volatile("ds_read_b64_tr_b16 %0,%1 offset:%c2":"=&v"(hi[ks]):"v"(vb),"i"(d0*4096+ks*1024+512):"memory");}
;     asm volatile("s_waitcnt lgkmcnt(0)":::"memory");SBAR();
;     ...
;     o[d0]=__builtin_amdgcn_mfma_f32_32x32x16_bf16(pa0,PK(0),o[d0],0,0,0);
;     o[d0]=__builtin_amdgcn_mfma_f32_32x32x16_bf16(pa1,PK(1),o[d0],0,0,0);
;     o[d0]=__builtin_amdgcn_mfma_f32_32x32x16_bf16(pa2,PK(2),o[d0],0,0,0);
;     o[d0]=__builtin_amdgcn_mfma_f32_32x32x16_bf16(pa3,PK(3),o[d0],0,0,0);
;     ...
;   }
; }
; template<int THRL,bool FIXREF,bool HALFK> __device__ __forceinline__ void attn_unit(float mref,long rowbase,int q0,const bf16*Qh,int PQ,const bf16*__restrict__ Kh_,int PK,const bf16*__restrict__ Vh_,int PV,bf16*Oh,int PO,const bf16*Gh,int PG,u32x4(&okeep)[4],int omode,float lam,float oml,const float ...
;     ...
;   {auto rr=__builtin_amdgcn_permlane32_swap(__float_as_uint(l_reg),__float_as_uint(l_reg),false,false);l_reg=__uint_as_float(rr[0])+__uint_as_float(rr[1]);}
;   if(hi==0)wsf[32+r32]=l_reg;asm volatile("s_waitcnt lgkmcnt(0)":::"memory");
;   float rli[16];
;   #pragma unroll
;   for(int r=0;r<16;++r)rli[r]=__builtin_amdgcn_rcpf(wsf[32+crow(r,hi)]);
;   bf16*Ow=Oh+(rowbase+q0+wid*QBLK)*PO;
;   { bf16*stg=(bf16*)(shm+LDS_OST)+wid*2048;
;     #pragma unroll
;     for(int r=0;r<16;++r){const int orow=crow(r,hi);
;       #pragma unroll
;       for(int d0=0;d0<2;++d0)stg[orow*64+d0*32+r32]=__float2bfloat16(o[d0][r]*rli[r]);}
;     asm volatile("s_waitcnt lgkmcnt(0)":::"memory");
;     if(omode==2){
	v_mfma_f32_32x32x16_bf16 v[34:49], v[146:149], v[70:73], v[34:49]
	ds_read_b64_tr_b16 v[58:59],v0 offset:0
	ds_read_b64_tr_b16 v[60:61],v0 offset:512
	ds_read_b64_tr_b16 v[62:63],v0 offset:1024
	ds_read_b64_tr_b16 v[64:65],v0 offset:1536
	ds_read_b64_tr_b16 v[66:67],v0 offset:2048
	ds_read_b64_tr_b16 v[68:69],v0 offset:2560
	ds_read_b64_tr_b16 v[70:71],v0 offset:3072
	ds_read_b64_tr_b16 v[72:73],v0 offset:3584
	s_waitcnt lgkmcnt(0)
	s_nop 0
	v_mfma_f32_32x32x16_bf16 v[18:33], v[76:79], v[58:61], v[18:33]
	ds_read_b64_tr_b16 v[58:59],v0 offset:4096
	ds_read_b64_tr_b16 v[60:61],v0 offset:4608
	v_mfma_f32_32x32x16_bf16 v[18:33], v[80:83], v[62:65], v[18:33]
	ds_read_b64_tr_b16 v[62:63],v0 offset:5120
	ds_read_b64_tr_b16 v[64:65],v0 offset:5632
	v_mfma_f32_32x32x16_bf16 v[18:33], v[50:53], v[66:69], v[18:33]
	ds_read_b64_tr_b16 v[66:67],v0 offset:6144
	ds_read_b64_tr_b16 v[68:69],v0 offset:6656
	v_mfma_f32_32x32x16_bf16 v[18:33], v[54:57], v[70:73], v[18:33]
	ds_read_b64_tr_b16 v[70:71],v0 offset:7168
	ds_read_b64_tr_b16 v[72:73],v0 offset:7680
	s_waitcnt lgkmcnt(0)
	v_mfma_f32_32x32x16_bf16 v[34:49], v[76:79], v[58:61], v[34:49]
	v_mov_b32_e32 v0, v74
	s_nop 1
	v_permlane32_swap_b32_e32 v74, v0
	v_cmp_gt_u32_e32 vcc, 32, v209
	v_mfma_f32_32x32x16_bf16 v[34:49], v[80:83], v[62:65], v[34:49]
	v_mfma_f32_32x32x16_bf16 v[34:49], v[50:53], v[66:69], v[34:49]
	v_mfma_f32_32x32x16_bf16 v[34:49], v[54:57], v[70:73], v[34:49]
	s_and_saveexec_b64 s[48:49], vcc
	v_lshl_add_u32 v50, v171, 2, s20
	v_add_f32_e32 v0, v74, v0
	ds_write_b32 v50, v0 offset:49280
	s_or_b64 exec, exec, s[48:49]
	s_waitcnt lgkmcnt(0)
	v_lshl_add_u32 v0, v212, 4, s20
	ds_read_b128 v[50:53], v0 offset:49280
	ds_read_b128 v[54:57], v0 offset:49312
	s_lshl_b32 s20, s79, 12
	s_add_i32 s20, s20, 0
	v_lshlrev_b32_e32 v66, 1, v171
	s_waitcnt lgkmcnt(1)
	v_rcp_f32_e32 v58, v50
	v_rcp_f32_e32 v59, v51
	v_rcp_f32_e32 v60, v52
	v_rcp_f32_e32 v61, v53
	s_waitcnt lgkmcnt(0)
	v_rcp_f32_e32 v62, v54
	ds_read_b128 v[50:53], v0 offset:49344
	v_rcp_f32_e32 v63, v55
	v_rcp_f32_e32 v64, v56
	v_rcp_f32_e32 v65, v57
	ds_read_b128 v[54:57], v0 offset:49376
	s_waitcnt lgkmcnt(1)
	v_rcp_f32_e32 v0, v50
	v_rcp_f32_e32 v50, v51
	v_rcp_f32_e32 v51, v52
	v_rcp_f32_e32 v52, v53
	s_waitcnt lgkmcnt(0)
	v_rcp_f32_e32 v53, v54
	v_rcp_f32_e32 v54, v55
	v_rcp_f32_e32 v55, v56
	v_rcp_f32_e32 v56, v57
	v_lshlrev_b32_e32 v57, 9, v212
	v_mul_f32_e32 v18, v18, v58
	v_add3_u32 v57, s20, v57, v66
	v_cvt_pk_bf16_f32 v18, v18, s0
	ds_write_b16 v57, v18 offset:51200
	v_mul_f32_e32 v18, v34, v58
	v_cvt_pk_bf16_f32 v18, v18, s0
	ds_write_b16 v57, v18 offset:51264
	v_mul_f32_e32 v18, v19, v59
	v_cvt_pk_bf16_f32 v18, v18, s0
	ds_write_b16 v57, v18 offset:51328
	v_mul_f32_e32 v18, v35, v59
	v_cvt_pk_bf16_f32 v18, v18, s0
	ds_write_b16 v57, v18 offset:51392
	v_mul_f32_e32 v18, v20, v60
	v_cvt_pk_bf16_f32 v18, v18, s0
	ds_write_b16 v57, v18 offset:51456
	v_mul_f32_e32 v18, v36, v60
	v_cvt_pk_bf16_f32 v18, v18, s0
	ds_write_b16 v57, v18 offset:51520
	v_mul_f32_e32 v18, v21, v61
	v_cvt_pk_bf16_f32 v18, v18, s0
	ds_write_b16 v57, v18 offset:51584
	v_mul_f32_e32 v18, v37, v61
	v_cvt_pk_bf16_f32 v18, v18, s0
	ds_write_b16 v57, v18 offset:51648
	v_mul_f32_e32 v18, v22, v62
	v_cvt_pk_bf16_f32 v18, v18, s0
	ds_write_b16 v57, v18 offset:52224
	v_mul_f32_e32 v18, v38, v62
	v_cvt_pk_bf16_f32 v18, v18, s0
	ds_write_b16 v57, v18 offset:52288
	v_mul_f32_e32 v18, v23, v63
	v_cvt_pk_bf16_f32 v18, v18, s0
	ds_write_b16 v57, v18 offset:52352
	v_mul_f32_e32 v18, v39, v63
	v_cvt_pk_bf16_f32 v18, v18, s0
	ds_write_b16 v57, v18 offset:52416
	v_mul_f32_e32 v18, v24, v64
	v_cvt_pk_bf16_f32 v18, v18, s0
	ds_write_b16 v57, v18 offset:52480
	v_mul_f32_e32 v18, v40, v64
	v_cvt_pk_bf16_f32 v18, v18, s0
	ds_write_b16 v57, v18 offset:52544
	v_mul_f32_e32 v18, v25, v65
	v_cvt_pk_bf16_f32 v18, v18, s0
	ds_write_b16 v57, v18 offset:52608
	v_mul_f32_e32 v18, v41, v65
	v_cvt_pk_bf16_f32 v18, v18, s0
	ds_write_b16 v57, v18 offset:52672
	v_mul_f32_e32 v18, v26, v0
	v_mul_f32_e32 v0, v42, v0
	v_cvt_pk_bf16_f32 v0, v0, s0
	ds_write_b16 v57, v0 offset:53312
	v_mul_f32_e32 v0, v27, v50
	v_cvt_pk_bf16_f32 v0, v0, s0
	ds_write_b16 v57, v0 offset:53376
	v_mul_f32_e32 v0, v43, v50
	v_cvt_pk_bf16_f32 v0, v0, s0
	ds_write_b16 v57, v0 offset:53440
	v_mul_f32_e32 v0, v28, v51
	v_cvt_pk_bf16_f32 v0, v0, s0
	ds_write_b16 v57, v0 offset:53504
	v_mul_f32_e32 v0, v44, v51
	v_cvt_pk_bf16_f32 v0, v0, s0
	ds_write_b16 v57, v0 offset:53568
	v_mul_f32_e32 v0, v29, v52
	v_cvt_pk_bf16_f32 v0, v0, s0
	ds_write_b16 v57, v0 offset:53632
	v_mul_f32_e32 v0, v45, v52
	v_cvt_pk_bf16_f32 v0, v0, s0
	ds_write_b16 v57, v0 offset:53696
	v_mul_f32_e32 v0, v30, v53
	v_cvt_pk_bf16_f32 v0, v0, s0
	ds_write_b16 v57, v0 offset:54272
	v_mul_f32_e32 v0, v46, v53
	v_cvt_pk_bf16_f32 v0, v0, s0
	ds_write_b16 v57, v0 offset:54336
	v_mul_f32_e32 v0, v31, v54
	v_cvt_pk_bf16_f32 v0, v0, s0
	ds_write_b16 v57, v0 offset:54400
	v_mul_f32_e32 v0, v47, v54
	v_cvt_pk_bf16_f32 v0, v0, s0
	ds_write_b16 v57, v0 offset:54464
	v_mul_f32_e32 v0, v32, v55
	v_cvt_pk_bf16_f32 v0, v0, s0
	ds_write_b16 v57, v0 offset:54528
	v_mul_f32_e32 v0, v48, v55
	v_cvt_pk_bf16_f32 v0, v0, s0
	ds_write_b16 v57, v0 offset:54592
	v_mul_f32_e32 v0, v33, v56
	v_cvt_pk_bf16_f32 v0, v0, s0
	ds_write_b16 v57, v0 offset:54656
	v_mul_f32_e32 v0, v49, v56
	v_cvt_pk_bf16_f32 v18, v18, s0
	v_cvt_pk_bf16_f32 v0, v0, s0
	ds_write_b16 v57, v18 offset:53248
	ds_write_b16 v57, v0 offset:54720
	s_lshl_b64 s[46:47], s[46:47], 11
	s_waitcnt lgkmcnt(0)
	s_add_u32 s46, s69, s46
	s_addc_u32 s47, s70, s47
	s_mov_b64 s[48:49], -1
	s_and_b64 vcc, exec, s[42:43]
	s_cbranch_vccz .LBB0_470
; __device__ __forceinline__ unsigned cvtpk_s(float lo,float hi){f32x2_t v={lo,hi};bf16x2_t b=__builtin_convertvector(v,bf16x2_t);return __builtin_bit_cast(unsigned,b);}
; template<int THRL,bool FIXREF,bool HALFK> __device__ __forceinline__ void attn_unit(float mref,long rowbase,int q0,const bf16*Qh,int PQ,const bf16*__restrict__ Kh_,int PK,const bf16*__restrict__ Vh_,int PV,bf16*Oh,int PO,const bf16*Gh,int PG,u32x4(&okeep)[4],int omode,float lam,float oml,const float ...
;     ...
;     else if(Gh){
;       u32x4 gv[4]; const char*gst=shm+LDS_GST+wid*4096+lane*16;
;       #pragma unroll
;       for(int i=0;i<4;++i) gv[i]=*(const u32x4*)(gst+i*1024);
;       #pragma unroll
;       for(int i=0;i<4;++i){const int row=i*8+(lane>>3),ch=lane&7; u32x4 v=*(const u32x4*)(stg+row*64+ch*8);
;         #pragma unroll
;         for(int k=0;k<4;++k){ const float g0=__uint_as_float(gv[i][k]<<16),g1=__uint_as_float(gv[i][k]&0xffff0000u),o0=__uint_as_float(v[k]<<16),o1=__uint_as_float(v[k]&0xffff0000u);
;           v[k]=cvtpk_s(o0*g0*__builtin_amdgcn_rcpf(1.f+__builtin_amdgcn_exp2f(-1.4426950408889634f*g0)),o1*g1*__builtin_amdgcn_rcpf(1.f+__builtin_amdgcn_exp2f(-1.4426950408889634f*g1))); }
;         ATTN_STORE16(Ow+(long)row*PO+ch*8,v);} }
	s_mov_b64 s[42:43], -1
	s_and_b64 vcc, exec, s[40:41]
	s_cbranch_vccz .LBB0_467
	v_lshl_add_u32 v0, v209, 4, s20
	v_add_u32_e32 v0, 0x14800, v0
	ds_read_b128 v[30:33], v0
	ds_read_b128 v[26:29], v0 offset:1024
	ds_read_b128 v[22:25], v0 offset:2048
	ds_read_b128 v[18:21], v0 offset:3072
	v_lshlrev_b32_e32 v0, 1, v211
	v_and_b32_e32 v0, 0x70, v0
	v_add_u32_e32 v36, s20, v0
	v_lshl_add_u64 v[34:35], s[46:47], 0, v[0:1]
	v_lshl_add_u32 v0, v208, 7, v36
	s_waitcnt lgkmcnt(3)
	v_lshlrev_b32_e32 v44, 16, v30
	ds_read_b128 v[38:41], v0 offset:51200
	v_mul_f32_e32 v0, 0xbfb8aa3b, v44
	v_exp_f32_e32 v0, v0
	v_and_b32_e32 v43, 0xffff0000, v30
	s_mov_b64 s[42:43], 0
	s_waitcnt lgkmcnt(0)
	v_lshlrev_b32_e32 v42, 16, v38
	v_add_f32_e32 v0, 1.0, v0
	v_rcp_f32_e32 v46, v0
	v_mul_f32_e32 v0, 0xbfb8aa3b, v43
	v_exp_f32_e32 v0, v0
	v_and_b32_e32 v45, 0xffff0000, v38
	v_lshlrev_b32_e32 v38, 16, v31
	v_pk_mul_f32 v[44:45], v[42:43], v[44:45]
	v_add_f32_e32 v0, 1.0, v0
	v_rcp_f32_e32 v47, v0
	v_mul_f32_e32 v0, 0xbfb8aa3b, v38
	v_exp_f32_e32 v0, v0
	v_pk_mul_f32 v[42:43], v[46:47], v[44:45]
	s_nop 0
	v_cvt_pk_bf16_f32 v30, v42, v43
	v_and_b32_e32 v43, 0xffff0000, v31
	v_add_f32_e32 v0, 1.0, v0
	v_rcp_f32_e32 v44, v0
	v_mul_f32_e32 v0, 0xbfb8aa3b, v43
	v_exp_f32_e32 v0, v0
	v_lshlrev_b32_e32 v42, 16, v39
	v_and_b32_e32 v39, 0xffff0000, v39
	v_pk_mul_f32 v[38:39], v[42:43], v[38:39]
	v_add_f32_e32 v0, 1.0, v0
	v_lshlrev_b32_e32 v42, 16, v32
	v_rcp_f32_e32 v45, v0
	v_mul_f32_e32 v0, 0xbfb8aa3b, v42
	v_exp_f32_e32 v0, v0
	v_and_b32_e32 v43, 0xffff0000, v40
	v_pk_mul_f32 v[38:39], v[44:45], v[38:39]
	v_add_f32_e32 v0, 1.0, v0
	v_cvt_pk_bf16_f32 v31, v38, v39
	v_and_b32_e32 v39, 0xffff0000, v32
	v_rcp_f32_e32 v44, v0
	v_mul_f32_e32 v0, 0xbfb8aa3b, v39
	v_exp_f32_e32 v0, v0
	v_lshlrev_b32_e32 v38, 16, v40
	v_lshlrev_b32_e32 v40, 16, v33
	v_pk_mul_f32 v[42:43], v[38:39], v[42:43]
	v_add_f32_e32 v0, 1.0, v0
	v_rcp_f32_e32 v45, v0
	v_mul_f32_e32 v0, 0xbfb8aa3b, v40
	v_exp_f32_e32 v0, v0
	v_pk_mul_f32 v[38:39], v[44:45], v[42:43]
	s_nop 0
	v_cvt_pk_bf16_f32 v32, v38, v39
	v_and_b32_e32 v39, 0xffff0000, v33
	v_add_f32_e32 v0, 1.0, v0
	v_rcp_f32_e32 v42, v0
	v_mul_f32_e32 v0, 0xbfb8aa3b, v39
	v_exp_f32_e32 v0, v0
	v_lshlrev_b32_e32 v38, 16, v41
	v_and_b32_e32 v41, 0xffff0000, v41
	v_pk_mul_f32 v[40:41], v[38:39], v[40:41]
	v_add_f32_e32 v0, 1.0, v0
	v_rcp_f32_e32 v43, v0
	v_lshlrev_b32_e32 v0, 11, v208
	v_pk_mul_f32 v[38:39], v[42:43], v[40:41]
	s_nop 0
	v_cvt_pk_bf16_f32 v33, v38, v39
	v_lshl_add_u64 v[38:39], v[34:35], 0, v[0:1]
	v_lshlrev_b32_e32 v40, 16, v26
	global_store_dwordx4 v[38:39], v[30:33], off
	v_and_b32_e32 v39, 0xffff0000, v26
	v_mul_f32_e32 v26, 0xbfb8aa3b, v40
	v_exp_f32_e32 v26, v26
	v_or_b32_e32 v0, 8, v208
	v_lshl_add_u32 v30, v0, 7, v36
	ds_read_b128 v[30:33], v30 offset:51200
	v_add_f32_e32 v26, 1.0, v26
	v_rcp_f32_e32 v42, v26
	v_mul_f32_e32 v26, 0xbfb8aa3b, v39
	v_exp_f32_e32 v26, v26
	s_waitcnt lgkmcnt(0)
	v_lshlrev_b32_e32 v38, 16, v30
	v_and_b32_e32 v41, 0xffff0000, v30
	v_pk_mul_f32 v[40:41], v[38:39], v[40:41]
	v_add_f32_e32 v26, 1.0, v26
	v_rcp_f32_e32 v43, v26
	v_lshlrev_b32_e32 v30, 16, v27
	v_lshlrev_b32_e32 v0, 11, v0
	v_pk_mul_f32 v[38:39], v[42:43], v[40:41]
	s_nop 0
	v_cvt_pk_bf16_f32 v26, v38, v39
	v_and_b32_e32 v39, 0xffff0000, v27
	v_mul_f32_e32 v27, 0xbfb8aa3b, v30
	v_exp_f32_e32 v27, v27
	v_lshlrev_b32_e32 v38, 16, v31
	v_and_b32_e32 v31, 0xffff0000, v31
	v_pk_mul_f32 v[30:31], v[38:39], v[30:31]
	v_add_f32_e32 v27, 1.0, v27
	v_rcp_f32_e32 v40, v27
	v_mul_f32_e32 v27, 0xbfb8aa3b, v39
	v_exp_f32_e32 v27, v27
	v_lshlrev_b32_e32 v38, 16, v28
	v_and_b32_e32 v39, 0xffff0000, v32
	v_add_f32_e32 v27, 1.0, v27
	v_rcp_f32_e32 v41, v27
	s_nop 0
	v_pk_mul_f32 v[30:31], v[40:41], v[30:31]
	s_nop 0
	v_cvt_pk_bf16_f32 v27, v30, v31
	v_and_b32_e32 v31, 0xffff0000, v28
	v_mul_f32_e32 v28, 0xbfb8aa3b, v38
	v_exp_f32_e32 v28, v28
	v_lshlrev_b32_e32 v30, 16, v32
	v_pk_mul_f32 v[38:39], v[30:31], v[38:39]
	v_lshlrev_b32_e32 v32, 16, v29
	v_add_f32_e32 v28, 1.0, v28
	v_rcp_f32_e32 v40, v28
	v_mul_f32_e32 v28, 0xbfb8aa3b, v31
	v_exp_f32_e32 v28, v28
	s_nop 0
	v_add_f32_e32 v28, 1.0, v28
	v_rcp_f32_e32 v41, v28
	s_nop 0
	v_pk_mul_f32 v[30:31], v[40:41], v[38:39]
	s_nop 0
	v_cvt_pk_bf16_f32 v28, v30, v31
	v_and_b32_e32 v31, 0xffff0000, v29
	v_mul_f32_e32 v29, 0xbfb8aa3b, v32
	v_exp_f32_e32 v29, v29
	v_lshlrev_b32_e32 v30, 16, v33
	v_and_b32_e32 v33, 0xffff0000, v33
	v_pk_mul_f32 v[32:33], v[30:31], v[32:33]
	v_add_f32_e32 v29, 1.0, v29
	v_rcp_f32_e32 v38, v29
	v_mul_f32_e32 v29, 0xbfb8aa3b, v31
	v_exp_f32_e32 v29, v29
	s_nop 0
	v_add_f32_e32 v29, 1.0, v29
	v_rcp_f32_e32 v39, v29
	s_nop 0
	v_pk_mul_f32 v[30:31], v[38:39], v[32:33]
	s_nop 0
	v_cvt_pk_bf16_f32 v29, v30, v31
	v_lshl_add_u64 v[30:31], v[34:35], 0, v[0:1]
	v_lshlrev_b32_e32 v32, 16, v22
	global_store_dwordx4 v[30:31], v[26:29], off
	v_and_b32_e32 v31, 0xffff0000, v22
	v_mul_f32_e32 v22, 0xbfb8aa3b, v32
	v_exp_f32_e32 v22, v22
	v_or_b32_e32 v0, 16, v208
	v_lshl_add_u32 v26, v0, 7, v36
	ds_read_b128 v[26:29], v26 offset:51200
	v_add_f32_e32 v22, 1.0, v22
	v_rcp_f32_e32 v38, v22
	v_mul_f32_e32 v22, 0xbfb8aa3b, v31
	v_exp_f32_e32 v22, v22
	s_waitcnt lgkmcnt(0)
; __device__ __forceinline__ unsigned cvtpk_s(float lo,float hi){f32x2_t v={lo,hi};bf16x2_t b=__builtin_convertvector(v,bf16x2_t);return __builtin_bit_cast(unsigned,b);}
; template<int THRL,bool FIXREF,bool HALFK> __device__ __forceinline__ void attn_unit(float mref,long rowbase,int q0,const bf16*Qh,int PQ,const bf16*__restrict__ Kh_,int PK,const bf16*__restrict__ Vh_,int PV,bf16*Oh,int PO,const bf16*Gh,int PG,u32x4(&okeep)[4],int omode,float lam,float oml,const float ...
;     ...
;     else if(Gh){
;       u32x4 gv[4]; const char*gst=shm+LDS_GST+wid*4096+lane*16;
;       #pragma unroll
;       for(int i=0;i<4;++i) gv[i]=*(const u32x4*)(gst+i*1024);
;       #pragma unroll
;       for(int i=0;i<4;++i){const int row=i*8+(lane>>3),ch=lane&7; u32x4 v=*(const u32x4*)(stg+row*64+ch*8);
;         #pragma unroll
;         for(int k=0;k<4;++k){ const float g0=__uint_as_float(gv[i][k]<<16),g1=__uint_as_float(gv[i][k]&0xffff0000u),o0=__uint_as_float(v[k]<<16),o1=__uint_as_float(v[k]&0xffff0000u);
;           v[k]=cvtpk_s(o0*g0*__builtin_amdgcn_rcpf(1.f+__builtin_amdgcn_exp2f(-1.4426950408889634f*g0)),o1*g1*__builtin_amdgcn_rcpf(1.f+__builtin_amdgcn_exp2f(-1.4426950408889634f*g1))); }
;         ATTN_STORE16(Ow+(long)row*PO+ch*8,v);} }
	v_lshlrev_b32_e32 v30, 16, v26
	v_and_b32_e32 v33, 0xffff0000, v26
	v_pk_mul_f32 v[32:33], v[30:31], v[32:33]
	v_add_f32_e32 v22, 1.0, v22
	v_rcp_f32_e32 v39, v22
	v_lshlrev_b32_e32 v26, 16, v23
	v_lshlrev_b32_e32 v0, 11, v0
	v_pk_mul_f32 v[30:31], v[38:39], v[32:33]
	s_nop 0
	v_cvt_pk_bf16_f32 v22, v30, v31
	v_and_b32_e32 v31, 0xffff0000, v23
	v_mul_f32_e32 v23, 0xbfb8aa3b, v26
	v_exp_f32_e32 v23, v23
	v_lshlrev_b32_e32 v30, 16, v27
	v_and_b32_e32 v27, 0xffff0000, v27
	v_pk_mul_f32 v[26:27], v[30:31], v[26:27]
	v_add_f32_e32 v23, 1.0, v23
	v_rcp_f32_e32 v32, v23
	v_mul_f32_e32 v23, 0xbfb8aa3b, v31
	v_exp_f32_e32 v23, v23
	v_lshlrev_b32_e32 v30, 16, v24
	v_and_b32_e32 v31, 0xffff0000, v28
	v_add_f32_e32 v23, 1.0, v23
	v_rcp_f32_e32 v33, v23
	s_nop 0
	v_pk_mul_f32 v[26:27], v[32:33], v[26:27]
	s_nop 0
	v_cvt_pk_bf16_f32 v23, v26, v27
	v_and_b32_e32 v27, 0xffff0000, v24
	v_mul_f32_e32 v24, 0xbfb8aa3b, v30
	v_exp_f32_e32 v24, v24
	v_lshlrev_b32_e32 v26, 16, v28
	v_pk_mul_f32 v[30:31], v[26:27], v[30:31]
	v_lshlrev_b32_e32 v28, 16, v25
	v_add_f32_e32 v24, 1.0, v24
	v_rcp_f32_e32 v32, v24
	v_mul_f32_e32 v24, 0xbfb8aa3b, v27
	v_exp_f32_e32 v24, v24
	s_nop 0
	v_add_f32_e32 v24, 1.0, v24
	v_rcp_f32_e32 v33, v24
	s_nop 0
	v_pk_mul_f32 v[26:27], v[32:33], v[30:31]
	s_nop 0
	v_cvt_pk_bf16_f32 v24, v26, v27
	v_and_b32_e32 v27, 0xffff0000, v25
	v_mul_f32_e32 v25, 0xbfb8aa3b, v28
	v_exp_f32_e32 v25, v25
	v_lshlrev_b32_e32 v26, 16, v29
	v_and_b32_e32 v29, 0xffff0000, v29
	v_pk_mul_f32 v[28:29], v[26:27], v[28:29]
	v_add_f32_e32 v25, 1.0, v25
	v_rcp_f32_e32 v30, v25
	v_mul_f32_e32 v25, 0xbfb8aa3b, v27
	v_exp_f32_e32 v25, v25
	s_nop 0
	v_add_f32_e32 v25, 1.0, v25
	v_rcp_f32_e32 v31, v25
	s_nop 0
	v_pk_mul_f32 v[26:27], v[30:31], v[28:29]
	s_nop 0
	v_cvt_pk_bf16_f32 v25, v26, v27
	v_lshl_add_u64 v[26:27], v[34:35], 0, v[0:1]
	v_lshlrev_b32_e32 v28, 16, v18
	global_store_dwordx4 v[26:27], v[22:25], off
	v_and_b32_e32 v27, 0xffff0000, v18
	v_mul_f32_e32 v18, 0xbfb8aa3b, v28
	v_exp_f32_e32 v18, v18
	v_or_b32_e32 v0, 24, v208
	v_lshl_add_u32 v22, v0, 7, v36
	ds_read_b128 v[22:25], v22 offset:51200
	v_add_f32_e32 v18, 1.0, v18
	v_rcp_f32_e32 v30, v18
	v_mul_f32_e32 v18, 0xbfb8aa3b, v27
	v_exp_f32_e32 v18, v18
	s_waitcnt lgkmcnt(0)
	v_lshlrev_b32_e32 v26, 16, v22
	v_and_b32_e32 v29, 0xffff0000, v22
	v_pk_mul_f32 v[28:29], v[26:27], v[28:29]
	v_add_f32_e32 v18, 1.0, v18
	v_rcp_f32_e32 v31, v18
	v_lshlrev_b32_e32 v22, 16, v19
	v_lshlrev_b32_e32 v0, 11, v0
	v_pk_mul_f32 v[26:27], v[30:31], v[28:29]
	s_nop 0
	v_cvt_pk_bf16_f32 v18, v26, v27
	v_and_b32_e32 v27, 0xffff0000, v19
	v_mul_f32_e32 v19, 0xbfb8aa3b, v22
	v_exp_f32_e32 v19, v19
	v_lshlrev_b32_e32 v26, 16, v23
	v_and_b32_e32 v23, 0xffff0000, v23
	v_pk_mul_f32 v[22:23], v[26:27], v[22:23]
	v_add_f32_e32 v19, 1.0, v19
	v_rcp_f32_e32 v28, v19
	v_mul_f32_e32 v19, 0xbfb8aa3b, v27
	v_exp_f32_e32 v19, v19
	v_lshlrev_b32_e32 v26, 16, v20
	v_and_b32_e32 v27, 0xffff0000, v24
	v_add_f32_e32 v19, 1.0, v19
	v_rcp_f32_e32 v29, v19
	s_nop 0
	v_pk_mul_f32 v[22:23], v[28:29], v[22:23]
	s_nop 0
	v_cvt_pk_bf16_f32 v19, v22, v23
	v_and_b32_e32 v23, 0xffff0000, v20
	v_mul_f32_e32 v20, 0xbfb8aa3b, v26
	v_exp_f32_e32 v20, v20
	v_lshlrev_b32_e32 v22, 16, v24
	v_pk_mul_f32 v[26:27], v[22:23], v[26:27]
	v_lshlrev_b32_e32 v24, 16, v21
	v_add_f32_e32 v20, 1.0, v20
	v_rcp_f32_e32 v28, v20
	v_mul_f32_e32 v20, 0xbfb8aa3b, v23
	v_exp_f32_e32 v20, v20
	s_nop 0
	v_add_f32_e32 v20, 1.0, v20
	v_rcp_f32_e32 v29, v20
	s_nop 0
	v_pk_mul_f32 v[22:23], v[28:29], v[26:27]
	s_nop 0
	v_cvt_pk_bf16_f32 v20, v22, v23
	v_and_b32_e32 v23, 0xffff0000, v21
	v_mul_f32_e32 v21, 0xbfb8aa3b, v24
	v_exp_f32_e32 v21, v21
	v_lshlrev_b32_e32 v22, 16, v25
	v_and_b32_e32 v25, 0xffff0000, v25
	v_pk_mul_f32 v[24:25], v[22:23], v[24:25]
	v_add_f32_e32 v21, 1.0, v21
	v_rcp_f32_e32 v26, v21
	v_mul_f32_e32 v21, 0xbfb8aa3b, v23
	v_exp_f32_e32 v21, v21
	s_nop 0
	v_add_f32_e32 v21, 1.0, v21
	v_rcp_f32_e32 v27, v21
	s_nop 0
	v_pk_mul_f32 v[22:23], v[26:27], v[24:25]
	s_nop 0
	v_cvt_pk_bf16_f32 v21, v22, v23
	v_lshl_add_u64 v[22:23], v[34:35], 0, v[0:1]
	global_store_dwordx4 v[22:23], v[18:21], off
